# GEMM main loops: per-segment s_setprio toggling replaced by one static priority raise for waves 4-7 per GEMM phase
# speedup vs baseline: 1.0022x; 1.0022x over previous
; __global__ void __launch_bounds__(NTHREADS, 2) mega(Params P) {
;     ...
;     for (int ph = P.ph_lo; ph < P.ph_hi; ++ph) {
;         if (ph > P.ph_lo && ph != 11 && ph != 23) grid.sync();
.LBB0_3:
	s_setprio 0
	v_readlane_b32 s2, v255, 51
	s_add_i32 s2, s2, 1
	s_cmp_ge_i32 s2, s21
	s_cbranch_scc1 .LBB0_777

; #define PG8_BAR __builtin_amdgcn_s_barrier()
; template <class Epi, bool ALIGN_EPI = true, bool SP2 = true>
; DI void gemm_phase(LAS unsigned char* lds, const Gemm g, const StaticOrder& S, const Epi& E) {
;     ...
;     for (int i = 0; i < 2; ++i) { int R, C; stage_rc(tid * 16 + i * 8192, R, C); const int Rb = Epi::PERM ? ((R & ~31) + perm32(R & 31)) : R;
;         voffA[i] = (unsigned)(R * g.lda + C) * 2u; voffB[i] = (unsigned)(Rb * K + C) * 2u; }
;     const size_t kstep = (size_t)(BK * 2);
;     const size_t hstep = (size_t)HALF * K * 2;
;     const size_t tstep = 2 * hstep;
;     const size_t hstepA = (size_t)HALF * g.lda * 2, tstepA = 2 * hstepA;
;     const unsigned ldsw = (unsigned)wid * 1024u;
;     const int aoff = lds_byte(wr * 64 + fr, fq * 8), boff = lds_byte(wc * 32 + fr, fq * 8);
;     ...
;     Unit cur, nxt; int ui = 0;
;     if (!S.next(0, cur)) return;
;     f32x4 acc[2][2][4][2];
; #pragma unroll
;     for (int a = 0; a < 2; ++a)
; #pragma unroll
;         for (int b = 0; b < 2; ++b)
; #pragma unroll
;             for (int m = 0; m < 4; ++m)
; #pragma unroll
;                 for (int n = 0; n < 2; ++n) acc[a][b][m][n] = (f32x4){0.f, 0.f, 0.f, 0.f};
;     bf16x8 At[4][2], B0[2][2], B1[2][2];
;     const char* cA = (const char*)g.A + (size_t)cur.pm * tstepA; const char* cB = (const char*)g.Bt + (size_t)cur.pn * tstep;
;     if constexpr (SP2) {
;         PG8_STAGE(PG8_SB(0, 0), cB, voffB); PG8_STAGE(PG8_SB(0, 1), cB + hstep, voffB); PG8_STAGE(PG8_SA(0, 0), cA, voffA); PG8_STAGE(PG8_SA(0, 1), cA + hstepA, voffA);
;         if (wr == 1) PG8_BAR;
; __global__ void __launch_bounds__(NTHREADS, 2) mega(Params P) {
;     ...
;         } else if (s == 4) {
;             if (l == 0) phase_mixer0(P, lds, BIGb, YC0);
;             else for (int u = bid; u < 256; u += G) gdn_unit(P, BIGb, GB, u >> 3, u & 7, lds);
;         } else if (s == 10) {
;             const bf16_t* Bt = (const bf16_t*)(ws + W_PLE + (size_t)l * SZ_PLE + 2097152);
;             pg8::Gemm g{PB, Bt, T_, D_, 256, 256}; pg8::StaticOrder S; S.init(T_, D_, G, bid);
;             EpiResid<false> E{nullptr, BIGb, nullptr, 0};
;             pg8::gemm_phase<EpiResid<false>>(lds, g, S, E);
.LBB0_30:
	s_mov_b64 s[4:5], 0
	v_readlane_b32 s6, v255, 56
	v_writelane_b32 v255, s4, 57
	s_mov_b64 s[2:3], -1
	s_mov_b64 s[0:1], 0
	v_writelane_b32 v255, s5, 58
	s_mov_b64 s[4:5], 0
	v_writelane_b32 v255, s4, 59
	s_cmp_lt_i32 s6, 5
	s_nop 0
	v_writelane_b32 v255, s5, 60
	s_mov_b64 s[4:5], 0
	v_writelane_b32 v255, s4, 61
	s_nop 1
	v_writelane_b32 v255, s5, 62
	s_cbranch_scc1 .LBB0_238
	s_cmp_gt_i32 s6, 7
	s_cbranch_scc0 .LBB0_231
	v_writelane_b32 v255, s2, 57
	s_mov_b64 s[4:5], 0
	s_cmp_gt_i32 s6, 8
	v_writelane_b32 v255, s3, 58
	s_mov_b64 s[2:3], 0
	v_writelane_b32 v255, s2, 59
	s_nop 1
	v_writelane_b32 v255, s3, 60
	s_mov_b64 s[2:3], 0
	v_writelane_b32 v255, s2, 61
	s_nop 1
	v_writelane_b32 v255, s3, 62
	s_cbranch_scc0 .LBB0_234
	s_mov_b64 s[2:3], -1
	v_writelane_b32 v255, s2, 61
	s_cmp_gt_i32 s6, 9
	s_nop 0
	v_writelane_b32 v255, s3, 62
	s_mov_b64 s[2:3], 0
	v_writelane_b32 v255, s2, 57
	s_nop 1
	v_writelane_b32 v255, s3, 58
	s_mov_b64 s[2:3], 0
	v_writelane_b32 v255, s2, 59
	s_nop 1
	v_writelane_b32 v255, s3, 60
	s_cbranch_scc0 .LBB0_234
	s_mov_b64 s[2:3], -1
	v_writelane_b32 v255, s2, 59
	s_cmp_eq_u32 s6, 10
	s_nop 0
	v_writelane_b32 v255, s3, 60
	s_cbranch_scc0 .LBB0_233
	v_readlane_b32 s2, v253, 14
	v_mov_b32_e32 v0, v163
	v_readlane_b32 s3, v253, 15
	s_andn2_b64 vcc, exec, s[2:3]
	v_readfirstlane_b32 s2, v0
	s_cbranch_vccnz .LBB0_232
	v_bfe_i32 v3, v0, 27, 1
	v_lshlrev_b32_e32 v1, 4, v0
	v_lshrrev_b32_e32 v3, 22, v3
	v_add_u32_e32 v3, v1, v3
	v_and_b32_e32 v3, 0xfffffc00, v3
	v_sub_u32_e32 v3, v1, v3
	v_readlane_b32 s6, v255, 54
	v_ashrrev_i32_e32 v2, 31, v0
	v_lshrrev_b32_e32 v4, 4, v3
	v_readlane_b32 s7, v255, 55
	v_lshrrev_b32_e32 v2, 26, v2
	v_bitop3_b32 v4, v4, v3, 32 bitop3:0x6c
	v_ashrrev_i32_e32 v3, 31, v3
	s_and_b64 s[6:7], s[6:7], exec
	v_add_u32_e32 v2, v0, v2
	v_lshrrev_b32_e32 v3, 26, v3
	s_cselect_b32 s3, 0x280000, 0
	v_ashrrev_i32_e32 v2, 6, v2
	v_add_u32_e32 v3, v4, v3
	s_add_u32 s3, s88, s3
	v_lshlrev_b32_e32 v5, 3, v2
	v_ashrrev_i32_e32 v3, 6, v3
	s_addc_u32 s6, s89, 0
	v_and_b32_e32 v5, -16, v5
	v_mul_i32_i24_e32 v6, 64, v3
	s_add_u32 s26, s3, 0x4400000
	v_add_u32_e32 v5, v3, v5
	v_sub_u32_e32 v4, v4, v6
	s_addc_u32 s34, s6, 0
	v_lshlrev_b32_e32 v2, 5, v2
	v_ashrrev_i16_sdwa v4, v166, sext(v4) dst_sel:DWORD dst_unused:UNUSED_PAD src0_sel:DWORD src1_sel:BYTE_0
	v_lshlrev_b32_e32 v6, 1, v5
	v_lshrrev_b32_e32 v7, 2, v5
	v_and_b32_e32 v3, 3, v3
	s_mov_b32 s6, 0x7fffe0
	v_and_b32_e32 v2, 32, v2
	v_bfe_i32 v4, v4, 0, 16
	v_and_b32_e32 v6, 24, v6
	v_and_b32_e32 v7, 4, v7
	v_and_or_b32 v3, v5, s6, v3
	v_or3_b32 v3, v3, v7, v6
	v_add_lshl_u32 v2, v2, v4, 1
	v_add_u32_e32 v1, 0x2000, v1
	v_lshl_add_u32 v128, v5, 9, v2
	v_lshl_add_u32 v129, v3, 9, v2
	v_ashrrev_i32_e32 v2, 31, v1
	v_lshrrev_b32_e32 v2, 22, v2
	v_add_u32_e32 v2, v1, v2
	v_ashrrev_i32_e32 v2, 10, v2
	v_mul_i32_i24_e32 v3, 0x400, v2
	v_sub_u32_e32 v1, v1, v3
	v_lshrrev_b32_e32 v3, 4, v1
	v_bitop3_b32 v1, v3, v1, 32 bitop3:0x6c
	v_ashrrev_i32_e32 v4, 31, v1
	v_lshrrev_b32_e32 v4, 26, v4
	v_lshlrev_b32_e32 v3, 3, v2
	v_add_u32_e32 v4, v1, v4
	v_and_b32_e32 v3, -16, v3
	v_ashrrev_i32_e32 v5, 6, v4
	v_add_u32_e32 v3, v5, v3
	v_and_b32_e32 v4, 0xc0, v4
	v_and_b32_e32 v5, 3, v5
	v_sub_u32_e32 v1, v1, v4
	v_and_or_b32 v5, v3, s6, v5
	s_ashr_i32 s6, s2, 6
	s_ashr_i32 s3, s2, 8
	v_lshlrev_b32_e32 v2, 5, v2
	v_ashrrev_i16_sdwa v1, v166, sext(v1) dst_sel:DWORD dst_unused:UNUSED_PAD src0_sel:DWORD src1_sel:BYTE_0
	v_lshlrev_b32_e32 v4, 1, v3
	v_lshrrev_b32_e32 v6, 2, v3
	s_lshl_b32 s36, s6, 10
	v_readlane_b32 s8, v254, 23
	v_and_b32_e32 v2, 32, v2
	v_bfe_i32 v1, v1, 0, 16
	v_and_b32_e32 v4, 24, v4
	v_and_b32_e32 v6, 4, v6
	v_readlane_b32 s9, v254, 24
	s_add_u32 s46, s26, s8
	v_or3_b32 v4, v5, v6, v4
	v_add_lshl_u32 v1, v2, v1, 1
	s_addc_u32 s47, s34, s9
	v_lshl_add_u32 v130, v3, 9, v1
	v_lshl_add_u32 v131, v4, 9, v1
	s_mov_b64 s[8:9], s[46:47]
	s_add_i32 s54, s36, 0
	v_mov_b32_e32 v1, v129
	s_add_i32 m0, s54, 0x10000
	s_nop 0
	global_load_lds_dwordx4 v1, s[8:9]
	v_mov_b32_e32 v1, v131
	s_add_i32 m0, s54, 0x12000
	s_nop 0
	global_load_lds_dwordx4 v1, s[8:9]
	s_add_u32 s8, s46, 0x10000
	s_addc_u32 s9, s47, 0
	v_mov_b32_e32 v1, v129
	s_add_i32 m0, s54, 0x14000
	s_add_i32 s55, s54, 0x2000
	global_load_lds_dwordx4 v1, s[8:9]
	v_mov_b32_e32 v1, v131
	s_add_i32 m0, s54, 0x16000
	s_add_i32 s69, s54, 0x4000
	global_load_lds_dwordx4 v1, s[8:9]
	v_readlane_b32 s8, v254, 29
	v_readlane_b32 s9, v254, 30
	v_mov_b32_e32 v1, v128
	s_mov_b32 m0, s54
	s_add_i32 s70, s54, 0x6000
	s_nop 1
	global_load_lds_dwordx4 v1, s[8:9]
	v_mov_b32_e32 v1, v130
	s_mov_b32 m0, s55
	s_cmp_eq_u32 s3, 1
	global_load_lds_dwordx4 v1, s[8:9]
	v_readlane_b32 s8, v254, 27
	v_readlane_b32 s9, v254, 28
	v_mov_b32_e32 v1, v128
	s_mov_b32 m0, s69
	s_cselect_b64 s[74:75], -1, 0
	s_nop 1
	global_load_lds_dwordx4 v1, s[8:9]
	v_mov_b32_e32 v1, v130
	s_mov_b32 m0, s70
	s_cmp_lg_u32 s3, 1
	global_load_lds_dwordx4 v1, s[8:9]
	s_cbranch_scc1 .LBB0_38
	s_barrier
	s_setprio 1

;     DI bool next(int i, Unit& u) const {
;         const long L = (long)i * G + c; if (L >= nwg) return false;
;         int wgid = (int)L; { const int q = nwg / NXCD, r = nwg % NXCD, xcd = wgid % NXCD, off = wgid / NXCD; wgid = (xcd < r ? xcd * (q + 1) : r * (q + 1) + (xcd - r) * q) + off; }
;         const int nig = WGM * nN, gid = wgid / nig, fm = gid * WGM, gsz = (nM - fm) < WGM ? (nM - fm) : WGM;
;         u.pm = fm + ((wgid % nig) % gsz); u.pn = (wgid % nig) / gsz; return true;
;     }
; template <class Epi, bool ALIGN_EPI = true, bool SP2 = true>
; DI void gemm_phase(LAS unsigned char* lds, const Gemm g, const StaticOrder& S, const Epi& E) {
;     const int tid = otid(), wid = __builtin_amdgcn_readfirstlane(tid >> 6), lane = tid & 63, wr = wid >> 2, wc = wid & 3, fr = lane & 15, fq = lane >> 4;
;     const int K = g.K, nt = K / BK;
;     unsigned voffA[2], voffB[2];
; #pragma unroll
;     for (int i = 0; i < 2; ++i) { int R, C; stage_rc(tid * 16 + i * 8192, R, C); const int Rb = Epi::PERM ? ((R & ~31) + perm32(R & 31)) : R;
;         voffA[i] = (unsigned)(R * g.lda + C) * 2u; voffB[i] = (unsigned)(Rb * K + C) * 2u; }
;     const size_t kstep = (size_t)(BK * 2);
;     const size_t hstep = (size_t)HALF * K * 2;
;     const size_t tstep = 2 * hstep;
;     const size_t hstepA = (size_t)HALF * g.lda * 2, tstepA = 2 * hstepA;
;     const unsigned ldsw = (unsigned)wid * 1024u;
;     const int aoff = lds_byte(wr * 64 + fr, fq * 8), boff = lds_byte(wc * 32 + fr, fq * 8);
;     ...
;     Unit cur, nxt; int ui = 0;
;     if (!S.next(0, cur)) return;
;     f32x4 acc[2][2][4][2];
; #pragma unroll
;     for (int a = 0; a < 2; ++a)
; #pragma unroll
;         for (int b = 0; b < 2; ++b)
; #pragma unroll
;             for (int m = 0; m < 4; ++m)
; #pragma unroll
;                 for (int n = 0; n < 2; ++n) acc[a][b][m][n] = (f32x4){0.f, 0.f, 0.f, 0.f};
;     bf16x8 At[4][2], B0[2][2], B1[2][2];
;     const char* cA = (const char*)g.A + (size_t)cur.pm * tstepA; const char* cB = (const char*)g.Bt + (size_t)cur.pn * tstep;
;     if constexpr (SP2) {
;         PG8_STAGE(PG8_SB(0, 0), cB, voffB); PG8_STAGE(PG8_SB(0, 1), cB + hstep, voffB); PG8_STAGE(PG8_SA(0, 0), cA, voffA); PG8_STAGE(PG8_SA(0, 1), cA + hstepA, voffA);
;         if (wr == 1) PG8_BAR;
; __global__ void __launch_bounds__(NTHREADS, 2) mega(Params P) {
;     ...
;         } else if (s == 3) {
.LBB0_257:
	s_andn2_b64 vcc, exec, s[0:1]
	s_cbranch_vccnz .LBB0_562
	v_readlane_b32 s0, v255, 54
	v_readlane_b32 s1, v255, 55
	s_and_b64 s[0:1], s[0:1], exec
	s_movk_i32 s0, 0x1100
	s_cselect_b32 s92, s0, 0x700
	v_mov_b32_e32 v0, v163
	s_cmp_ge_i32 s71, s92
	v_readfirstlane_b32 s3, v0
	s_cbranch_scc1 .LBB0_562
	v_bfe_i32 v3, v0, 27, 1
	v_lshlrev_b32_e32 v1, 4, v0
	v_lshrrev_b32_e32 v3, 22, v3
	v_add_u32_e32 v3, v1, v3
	v_and_b32_e32 v3, 0xfffffc00, v3
	v_sub_u32_e32 v3, v1, v3
	v_ashrrev_i32_e32 v2, 31, v0
	v_lshrrev_b32_e32 v4, 4, v3
	v_lshrrev_b32_e32 v2, 26, v2
	v_bitop3_b32 v4, v4, v3, 32 bitop3:0x6c
	v_ashrrev_i32_e32 v3, 31, v3
	v_readlane_b32 s0, v255, 54
	v_add_u32_e32 v2, v0, v2
	v_lshrrev_b32_e32 v3, 26, v3
	v_readlane_b32 s1, v255, 55
	v_ashrrev_i32_e32 v2, 6, v2
	v_add_u32_e32 v3, v4, v3
	s_and_b64 s[0:1], s[0:1], exec
	v_lshlrev_b32_e32 v5, 3, v2
	v_ashrrev_i32_e32 v3, 6, v3
	s_mov_b32 s0, 0x4c80000
	v_and_b32_e32 v5, -16, v5
	v_mul_i32_i24_e32 v6, 64, v3
	s_cselect_b32 s0, s0, 0x4700000
	v_add_u32_e32 v5, v3, v5
	v_sub_u32_e32 v4, v4, v6
	s_add_u32 s26, s88, s0
	v_lshlrev_b32_e32 v2, 5, v2
	v_ashrrev_i16_sdwa v4, v166, sext(v4) dst_sel:DWORD dst_unused:UNUSED_PAD src0_sel:DWORD src1_sel:BYTE_0
	v_lshlrev_b32_e32 v6, 1, v5
	v_lshrrev_b32_e32 v7, 2, v5
	v_and_b32_e32 v3, 3, v3
	s_mov_b32 s0, 0x1fffe0
	v_and_b32_e32 v2, 32, v2
	v_bfe_i32 v4, v4, 0, 16
	v_and_b32_e32 v6, 24, v6
	v_and_b32_e32 v7, 4, v7
	v_and_or_b32 v3, v5, s0, v3
	v_or3_b32 v3, v3, v7, v6
	v_add_lshl_u32 v2, v2, v4, 1
	v_add_u32_e32 v1, 0x2000, v1
	v_lshl_add_u32 v132, v5, 11, v2
	v_lshl_add_u32 v133, v3, 11, v2
	v_ashrrev_i32_e32 v2, 31, v1
	v_lshrrev_b32_e32 v2, 22, v2
	v_add_u32_e32 v2, v1, v2
	v_ashrrev_i32_e32 v2, 10, v2
	v_mul_i32_i24_e32 v3, 0x400, v2
	v_sub_u32_e32 v1, v1, v3
	v_lshrrev_b32_e32 v3, 4, v1
	v_bitop3_b32 v1, v3, v1, 32 bitop3:0x6c
	v_ashrrev_i32_e32 v4, 31, v1
	v_lshrrev_b32_e32 v4, 26, v4
	v_lshlrev_b32_e32 v3, 3, v2
	v_add_u32_e32 v4, v1, v4
	v_and_b32_e32 v3, -16, v3
	v_ashrrev_i32_e32 v5, 6, v4
	v_add_u32_e32 v3, v5, v3
	v_and_b32_e32 v5, 3, v5
	s_addc_u32 s34, s89, 0
	v_and_b32_e32 v4, 0xc0, v4
	v_and_or_b32 v5, v3, s0, v5
	s_ashr_i32 s7, s3, 6
	s_lshr_b32 s43, s92, 3
	v_readlane_b32 s0, v254, 11
	s_lshr_b32 s36, s92, 5
	s_ashr_i32 s6, s3, 8
	v_sub_u32_e32 v1, v1, v4
	s_lshl_b32 s42, s7, 10
	s_or_b32 s22, s43, 1
	v_readlane_b32 s1, v254, 12
	v_lshlrev_b32_e32 v2, 5, v2
	v_ashrrev_i16_sdwa v1, v166, sext(v1) dst_sel:DWORD dst_unused:UNUSED_PAD src0_sel:DWORD src1_sel:BYTE_0
	s_and_b64 s[0:1], s[0:1], exec
	v_and_b32_e32 v2, 32, v2
	v_bfe_i32 v1, v1, 0, 16
	s_cselect_b32 s0, s22, s43
	s_abs_i32 s47, s36
	v_add_lshl_u32 v1, v2, v1, 1
	v_cvt_f32_u32_e32 v2, s47
	v_lshlrev_b32_e32 v4, 1, v3
	v_lshrrev_b32_e32 v6, 2, v3
	v_and_b32_e32 v4, 24, v4
	v_and_b32_e32 v6, 4, v6
	v_or3_b32 v4, v5, v6, v4
	v_lshl_add_u32 v134, v3, 11, v1
	v_lshl_add_u32 v135, v4, 11, v1
	v_rcp_iflag_f32_e32 v1, v2
	v_readlane_b32 s1, v254, 13
	s_sub_i32 s4, 0, s47
	s_mul_i32 s0, s0, s1
	v_mul_f32_e32 v1, 0x4f7ffffe, v1
	v_cvt_u32_f32_e32 v1, v1
	v_readlane_b32 s1, v254, 14
	s_add_i32 s0, s0, s1
	s_abs_i32 s2, s0
	v_readfirstlane_b32 s49, v1
	s_mul_i32 s4, s4, s49
	s_mul_hi_u32 s4, s49, s4
	s_add_i32 s49, s49, s4
	s_mul_hi_u32 s4, s2, s49
	s_mul_i32 s5, s4, s47
	s_ashr_i32 s1, s0, 31
	s_ashr_i32 s74, s36, 31
	s_sub_i32 s2, s2, s5
	s_xor_b32 s1, s1, s74
	s_add_i32 s5, s4, 1
	s_sub_i32 s8, s2, s47
	s_cmp_ge_u32 s2, s47
	s_cselect_b32 s4, s5, s4
	s_cselect_b32 s2, s8, s2
	s_add_i32 s5, s4, 1
	s_cmp_ge_u32 s2, s47
	s_cselect_b32 s2, s5, s4
	s_xor_b32 s2, s2, s1
	s_sub_i32 s1, s2, s1
	s_lshl_b32 s4, s1, 3
	s_sub_i32 s2, 0x100, s4
	s_min_i32 s5, s2, 8
	s_sext_i32_i16 s2, s5
	v_cvt_f32_i32_e32 v1, s2
	s_mul_i32 s1, s1, s36
	s_sub_i32 s8, s0, s1
	v_cvt_f32_i32_e32 v2, s8
	v_rcp_iflag_f32_e32 v3, v1
	s_xor_b32 s0, s8, s2
	s_ashr_i32 s0, s0, 30
	s_or_b32 s2, s0, 1
	v_mul_f32_e32 v3, v2, v3
	v_trunc_f32_e32 v3, v3
	v_fma_f32 v2, -v3, v1, v2
	v_cvt_i32_f32_e32 v3, v3
	v_cmp_ge_f32_e64 s[0:1], |v2|, |v1|
	s_and_b64 s[0:1], s[0:1], exec
	s_cselect_b32 s0, s2, 0
	v_readfirstlane_b32 s1, v3
	s_add_i32 s2, s1, s0
	s_mul_i32 s0, s2, s5
	s_sub_i32 s0, s8, s0
	s_sext_i32_i16 s0, s0
	s_add_i32 s0, s4, s0
	s_ashr_i32 s1, s0, 31
	s_bfe_i64 s[8:9], s[2:3], 0x100000
	s_lshl_b64 s[4:5], s[0:1], 19
	s_lshl_b64 s[8:9], s[8:9], 19
	s_add_u32 s18, s26, s8
	s_addc_u32 s19, s34, s9
	s_mov_b64 s[8:9], s[18:19]
	s_add_i32 s54, s42, 0
	v_mov_b32_e32 v1, v133
	s_add_i32 m0, s54, 0x10000
	s_nop 0
	global_load_lds_dwordx4 v1, s[8:9]
	v_mov_b32_e32 v1, v135
	s_add_i32 m0, s54, 0x12000
	s_nop 0
	global_load_lds_dwordx4 v1, s[8:9]
	s_add_u32 s8, s18, 0x40000
	s_addc_u32 s9, s19, 0
	s_add_i32 m0, s54, 0x14000
	v_mov_b32_e32 v1, v133
	s_nop 0
	global_load_lds_dwordx4 v1, s[8:9]
	s_add_i32 m0, s54, 0x16000
	v_mov_b32_e32 v1, v135
	s_add_u32 s16, s94, s4
	s_addc_u32 s17, s95, s5
	global_load_lds_dwordx4 v1, s[8:9]
	s_mov_b64 s[4:5], s[16:17]
	v_mov_b32_e32 v1, v132
	s_mov_b32 m0, s54
	s_add_i32 s55, s54, 0x2000
	global_load_lds_dwordx4 v1, s[4:5]
	v_mov_b32_e32 v1, v134
	s_mov_b32 m0, s55
	s_nop 0
	global_load_lds_dwordx4 v1, s[4:5]
	s_add_u32 s4, s16, 0x40000
	s_addc_u32 s5, s17, 0
	s_add_i32 s69, s54, 0x4000
	v_mov_b32_e32 v1, v132
	s_mov_b32 m0, s69
	s_add_i32 s70, s54, 0x6000
	global_load_lds_dwordx4 v1, s[4:5]
	v_mov_b32_e32 v1, v134
	s_mov_b32 m0, s70
	s_cmp_eq_u32 s6, 1
	global_load_lds_dwordx4 v1, s[4:5]
	s_cselect_b64 s[76:77], -1, 0
	s_cmp_lg_u32 s6, 1
	s_cbranch_scc1 .LBB0_261
	s_barrier
	s_setprio 1

; #define PG8_LDA(dst, b, h) do { _Pragma("unroll") for (int m = 0; m < 4; ++m) _Pragma("unroll") for (int k = 0; k < 2; ++k) dst[m][k] = *(const LAS bf16x8*)(lds + PG8_SA(b, h) + aoff + m * 2048 + k * 1024); } while (0)
; #define PG8_LDB(dst, b, h) do { _Pragma("unroll") for (int n = 0; n < 2; ++n) _Pragma("unroll") for (int k = 0; k < 2; ++k) dst[n][k] = *(const LAS bf16x8*)(lds + PG8_SB(b, h) + boff + n * 2048 + k * 1024); } while (0)
; #define PG8_MMA(ai, bj, At, Bt) do { __builtin_amdgcn_s_setprio(1); _Pragma("unroll") for (int m = 0; m < 4; ++m) _Pragma("unroll") for (int n = 0; n < 2; ++n) _Pragma("unroll") for (int k = 0; k < 2; ++k) \
;         acc[ai][bj][m][n] = __builtin_amdgcn_mfma_f32_16x16x32_bf16(Bt[n][k], At[m][k], acc[ai][bj][m][n], 0, 0, 0); __builtin_amdgcn_s_setprio(0); } while (0)
; #define PG8_WAIT_V(n) asm volatile("s_waitcnt vmcnt(" #n ")" ::: "memory")
; #define PG8_WAIT_L(n) asm volatile("s_waitcnt lgkmcnt(" #n ")" ::: "memory")
; #define PG8_BAR __builtin_amdgcn_s_barrier()
; #define PG8_SCHED __builtin_amdgcn_sched_barrier(0)
; template <class Epi, bool ALIGN_EPI = true, bool SP2 = true>
; DI void gemm_phase(LAS unsigned char* lds, const Gemm g, const StaticOrder& S, const Epi& E) {
;     ...
;             PG8_LDB(B0, 0, 0); PG8_LDB(B1, 0, 1); PG8_SCHED; PG8_LDA(At, 0, 0); PG8_STAGE(PG8_SA(1, 1), a1 + hstepA, voffA);
;             PG8_WAIT_V(8); PG8_WAIT_L(0); PG8_BAR; PG8_MMA(0, 0, At, B0); PG8_MMA(0, 1, At, B1); PG8_BAR; PG8_SCHED;
;             PG8_LDA(At, 0, 1); PG8_STAGE(PG8_SB(0, 0), b2, voffB); PG8_STAGE(PG8_SB(0, 1), b2 + hstep, voffB); PG8_STAGE(PG8_SA(0, 0), a2, voffA);
;             PG8_WAIT_V(8); PG8_WAIT_L(0); PG8_BAR; PG8_MMA(1, 0, At, B0); PG8_MMA(1, 1, At, B1); PG8_BAR; PG8_SCHED;
.LBB0_536:
	s_add_u32 s18, s16, 0xfffc0080
	s_addc_u32 s19, s17, -1
	s_cmp_eq_u32 s46, 12
	s_cselect_b32 s44, s11, s18
	s_cselect_b32 s45, s1, s19
	s_cselect_b32 s40, s38, vcc_lo
	s_cselect_b32 s41, s9, vcc_hi
	s_add_u32 s18, s44, 0x80
	s_addc_u32 s19, s45, 0
	s_add_i32 s48, 0, 0x10000
	v_add_u32_e32 v136, s48, v143
	s_add_i32 s4, 0, 0x14000
	ds_read_b128 v[128:131], v136
	ds_read_b128 v[150:153], v136 offset:1024
	ds_read_b128 v[154:157], v136 offset:2048
	ds_read_b128 v[158:161], v136 offset:3072
	v_add_u32_e32 v136, s4, v143
	ds_read_b128 v[176:179], v136
	ds_read_b128 v[180:183], v136 offset:1024
	ds_read_b128 v[184:187], v136 offset:2048
	ds_read_b128 v[188:191], v136 offset:3072
	s_mov_b64 s[94:95], s[16:17]
	v_mov_b32_e32 v136, v132
	ds_read_b128 v[192:195], v148
	ds_read_b128 v[196:199], v148 offset:1024
	ds_read_b128 v[200:203], v148 offset:2048
	ds_read_b128 v[204:207], v148 offset:3072
	ds_read_b128 v[208:211], v148 offset:4096
	ds_read_b128 v[212:215], v148 offset:5120
	ds_read_b128 v[216:219], v148 offset:6144
	ds_read_b128 v[220:223], v148 offset:7168
	s_add_i32 m0, s54, 0xc000
	s_nop 0
	global_load_lds_dwordx4 v136, s[94:95]
	v_mov_b32_e32 v136, v134
	s_add_i32 m0, s54, 0xe000
	s_nop 0
	global_load_lds_dwordx4 v136, s[94:95]
	s_waitcnt vmcnt(8)
	s_waitcnt lgkmcnt(0)
	s_barrier
	s_waitcnt lgkmcnt(0)
	v_mfma_f32_16x16x32_bf16 v[124:127], v[128:131], v[192:195], v[124:127]
	v_mfma_f32_16x16x32_bf16 v[120:123], v[154:157], v[192:195], v[120:123]
	v_mfma_f32_16x16x32_bf16 v[116:119], v[128:131], v[200:203], v[116:119]
	v_mfma_f32_16x16x32_bf16 v[108:111], v[154:157], v[200:203], v[108:111]
	v_mfma_f32_16x16x32_bf16 v[100:103], v[128:131], v[208:211], v[100:103]
	v_mfma_f32_16x16x32_bf16 v[92:95], v[154:157], v[208:211], v[92:95]
	v_mfma_f32_16x16x32_bf16 v[84:87], v[128:131], v[216:219], v[84:87]
	v_mfma_f32_16x16x32_bf16 v[76:79], v[154:157], v[216:219], v[76:79]
	v_mfma_f32_16x16x32_bf16 v[124:127], v[150:153], v[196:199], v[124:127]
	v_mfma_f32_16x16x32_bf16 v[120:123], v[158:161], v[196:199], v[120:123]
	v_mfma_f32_16x16x32_bf16 v[116:119], v[150:153], v[204:207], v[116:119]
	v_mfma_f32_16x16x32_bf16 v[108:111], v[158:161], v[204:207], v[108:111]
	v_mfma_f32_16x16x32_bf16 v[100:103], v[150:153], v[212:215], v[100:103]
	v_mfma_f32_16x16x32_bf16 v[92:95], v[158:161], v[212:215], v[92:95]
	v_mfma_f32_16x16x32_bf16 v[84:87], v[150:153], v[220:223], v[84:87]
	v_mfma_f32_16x16x32_bf16 v[76:79], v[158:161], v[220:223], v[76:79]
	v_mfma_f32_16x16x32_bf16 v[112:115], v[176:179], v[192:195], v[112:115]
	v_mfma_f32_16x16x32_bf16 v[104:107], v[184:187], v[192:195], v[104:107]
	v_mfma_f32_16x16x32_bf16 v[96:99], v[176:179], v[200:203], v[96:99]
	v_mfma_f32_16x16x32_bf16 v[88:91], v[184:187], v[200:203], v[88:91]
	v_mfma_f32_16x16x32_bf16 v[80:83], v[176:179], v[208:211], v[80:83]
	v_mfma_f32_16x16x32_bf16 v[72:75], v[184:187], v[208:211], v[72:75]
	v_mfma_f32_16x16x32_bf16 v[68:71], v[176:179], v[216:219], v[68:71]
	v_mfma_f32_16x16x32_bf16 v[64:67], v[184:187], v[216:219], v[64:67]
	v_mfma_f32_16x16x32_bf16 v[112:115], v[180:183], v[196:199], v[112:115]
	v_mfma_f32_16x16x32_bf16 v[104:107], v[188:191], v[196:199], v[104:107]
	v_mfma_f32_16x16x32_bf16 v[96:99], v[180:183], v[204:207], v[96:99]
	v_mfma_f32_16x16x32_bf16 v[88:91], v[188:191], v[204:207], v[88:91]
	v_mfma_f32_16x16x32_bf16 v[80:83], v[180:183], v[212:215], v[80:83]
	v_mfma_f32_16x16x32_bf16 v[72:75], v[188:191], v[212:215], v[72:75]
	v_mfma_f32_16x16x32_bf16 v[68:71], v[180:183], v[220:223], v[68:71]
	v_mfma_f32_16x16x32_bf16 v[64:67], v[188:191], v[220:223], v[64:67]
	s_barrier
	s_mov_b64 s[94:95], s[40:41]
	v_mov_b32_e32 v136, v133
	s_add_i32 s5, s48, s42
	ds_read_b128 v[192:195], v148 offset:16384
	ds_read_b128 v[196:199], v148 offset:17408
	ds_read_b128 v[200:203], v148 offset:18432
	ds_read_b128 v[204:207], v148 offset:19456
	ds_read_b128 v[208:211], v148 offset:20480
	ds_read_b128 v[212:215], v148 offset:21504
	ds_read_b128 v[216:219], v148 offset:22528
	ds_read_b128 v[220:223], v148 offset:23552
	s_mov_b32 m0, s5
	s_nop 0
	global_load_lds_dwordx4 v136, s[94:95]
	v_mov_b32_e32 v136, v135
	s_add_i32 m0, s5, 0x2000
	s_nop 0
	global_load_lds_dwordx4 v136, s[94:95]
	s_add_u32 s94, s40, 0x40000
	s_addc_u32 s95, s41, 0
	v_mov_b32_e32 v136, v133
	s_add_i32 s4, s4, s42
	s_mov_b32 m0, s4
	s_nop 0
	global_load_lds_dwordx4 v136, s[94:95]
	v_mov_b32_e32 v136, v135
	s_add_i32 m0, s4, 0x2000
	s_nop 0
	global_load_lds_dwordx4 v136, s[94:95]
	s_mov_b64 s[94:95], s[44:45]
	v_mov_b32_e32 v136, v132
	s_mov_b32 m0, s54
	s_nop 0
	global_load_lds_dwordx4 v136, s[94:95]
	v_mov_b32_e32 v136, v134
	s_mov_b32 m0, s55
	s_nop 0
	global_load_lds_dwordx4 v136, s[94:95]
	s_waitcnt vmcnt(8)
	s_waitcnt lgkmcnt(0)
	s_barrier
; #define PG8_LDA(dst, b, h) do { _Pragma("unroll") for (int m = 0; m < 4; ++m) _Pragma("unroll") for (int k = 0; k < 2; ++k) dst[m][k] = *(const LAS bf16x8*)(lds + PG8_SA(b, h) + aoff + m * 2048 + k * 1024); } while (0)
; #define PG8_LDB(dst, b, h) do { _Pragma("unroll") for (int n = 0; n < 2; ++n) _Pragma("unroll") for (int k = 0; k < 2; ++k) dst[n][k] = *(const LAS bf16x8*)(lds + PG8_SB(b, h) + boff + n * 2048 + k * 1024); } while (0)
; #define PG8_MMA(ai, bj, At, Bt) do { __builtin_amdgcn_s_setprio(1); _Pragma("unroll") for (int m = 0; m < 4; ++m) _Pragma("unroll") for (int n = 0; n < 2; ++n) _Pragma("unroll") for (int k = 0; k < 2; ++k) \
;         acc[ai][bj][m][n] = __builtin_amdgcn_mfma_f32_16x16x32_bf16(Bt[n][k], At[m][k], acc[ai][bj][m][n], 0, 0, 0); __builtin_amdgcn_s_setprio(0); } while (0)
; #define PG8_WAIT_V(n) asm volatile("s_waitcnt vmcnt(" #n ")" ::: "memory")
; #define PG8_WAIT_L(n) asm volatile("s_waitcnt lgkmcnt(" #n ")" ::: "memory")
; #define PG8_BAR __builtin_amdgcn_s_barrier()
; #define PG8_SCHED __builtin_amdgcn_sched_barrier(0)
; template <class Epi, bool ALIGN_EPI = true, bool SP2 = true>
; DI void gemm_phase(LAS unsigned char* lds, const Gemm g, const StaticOrder& S, const Epi& E) {
;     ...
;             PG8_WAIT_V(8); PG8_WAIT_L(0); PG8_BAR; PG8_MMA(0, 0, At, B0); PG8_MMA(0, 1, At, B1); PG8_BAR; PG8_SCHED;
;             PG8_LDA(At, 0, 1); PG8_STAGE(PG8_SB(0, 0), b2, voffB); PG8_STAGE(PG8_SB(0, 1), b2 + hstep, voffB); PG8_STAGE(PG8_SA(0, 0), a2, voffA);
;             PG8_WAIT_V(8); PG8_WAIT_L(0); PG8_BAR; PG8_MMA(1, 0, At, B0); PG8_MMA(1, 1, At, B1); PG8_BAR; PG8_SCHED;
;             PG8_LDB(B0, 1, 0); PG8_LDB(B1, 1, 1); PG8_SCHED; PG8_LDA(At, 1, 0); PG8_STAGE(PG8_SA(0, 1), a2 + hstepA, voffA);
;             PG8_WAIT_V(8); PG8_WAIT_L(0); PG8_BAR; PG8_MMA(0, 0, At, B0); PG8_MMA(0, 1, At, B1); PG8_BAR; PG8_SCHED;
	s_waitcnt lgkmcnt(0)
	v_mfma_f32_16x16x32_bf16 v[60:63], v[128:131], v[192:195], v[60:63]
	v_mfma_f32_16x16x32_bf16 v[56:59], v[154:157], v[192:195], v[56:59]
	v_mfma_f32_16x16x32_bf16 v[52:55], v[128:131], v[200:203], v[52:55]
	v_mfma_f32_16x16x32_bf16 v[44:47], v[154:157], v[200:203], v[44:47]
	v_mfma_f32_16x16x32_bf16 v[36:39], v[128:131], v[208:211], v[36:39]
	v_mfma_f32_16x16x32_bf16 v[28:31], v[154:157], v[208:211], v[28:31]
	v_mfma_f32_16x16x32_bf16 v[20:23], v[128:131], v[216:219], v[20:23]
	v_mfma_f32_16x16x32_bf16 v[12:15], v[154:157], v[216:219], v[12:15]
	v_mfma_f32_16x16x32_bf16 v[60:63], v[150:153], v[196:199], v[60:63]
	v_mfma_f32_16x16x32_bf16 v[56:59], v[158:161], v[196:199], v[56:59]
	v_mfma_f32_16x16x32_bf16 v[52:55], v[150:153], v[204:207], v[52:55]
	v_mfma_f32_16x16x32_bf16 v[44:47], v[158:161], v[204:207], v[44:47]
	v_mfma_f32_16x16x32_bf16 v[36:39], v[150:153], v[212:215], v[36:39]
	v_mfma_f32_16x16x32_bf16 v[28:31], v[158:161], v[212:215], v[28:31]
	v_mfma_f32_16x16x32_bf16 v[20:23], v[150:153], v[220:223], v[20:23]
	v_mfma_f32_16x16x32_bf16 v[12:15], v[158:161], v[220:223], v[12:15]
	v_mfma_f32_16x16x32_bf16 v[48:51], v[176:179], v[192:195], v[48:51]
	v_mfma_f32_16x16x32_bf16 v[40:43], v[184:187], v[192:195], v[40:43]
	v_mfma_f32_16x16x32_bf16 v[32:35], v[176:179], v[200:203], v[32:35]
	v_mfma_f32_16x16x32_bf16 v[24:27], v[184:187], v[200:203], v[24:27]
	v_mfma_f32_16x16x32_bf16 v[16:19], v[176:179], v[208:211], v[16:19]
	v_mfma_f32_16x16x32_bf16 v[8:11], v[184:187], v[208:211], v[8:11]
	v_mfma_f32_16x16x32_bf16 v[4:7], v[176:179], v[216:219], v[4:7]
	v_mfma_f32_16x16x32_bf16 v[0:3], v[184:187], v[216:219], v[0:3]
	v_mfma_f32_16x16x32_bf16 v[48:51], v[180:183], v[196:199], v[48:51]
	v_mfma_f32_16x16x32_bf16 v[40:43], v[188:191], v[196:199], v[40:43]
	v_mfma_f32_16x16x32_bf16 v[32:35], v[180:183], v[204:207], v[32:35]
	v_mfma_f32_16x16x32_bf16 v[24:27], v[188:191], v[204:207], v[24:27]
	v_mfma_f32_16x16x32_bf16 v[16:19], v[180:183], v[212:215], v[16:19]
	v_mfma_f32_16x16x32_bf16 v[8:11], v[188:191], v[212:215], v[8:11]
	v_mfma_f32_16x16x32_bf16 v[4:7], v[180:183], v[220:223], v[4:7]
	v_mfma_f32_16x16x32_bf16 v[0:3], v[188:191], v[220:223], v[0:3]
	s_barrier
	s_add_i32 s4, 0, 0x18000
	v_add_u32_e32 v136, s4, v143
	s_add_i32 s5, 0, 0x1c000
	ds_read_b128 v[128:131], v136
	ds_read_b128 v[150:153], v136 offset:1024
	ds_read_b128 v[154:157], v136 offset:2048
	ds_read_b128 v[158:161], v136 offset:3072
	v_add_u32_e32 v136, s5, v143
	ds_read_b128 v[176:179], v136
	ds_read_b128 v[180:183], v136 offset:1024
	ds_read_b128 v[184:187], v136 offset:2048
	ds_read_b128 v[188:191], v136 offset:3072
	s_add_u32 s44, s44, 0x40000
	s_addc_u32 s45, s45, 0
	v_mov_b32_e32 v136, v132
	s_mov_b32 m0, s69
	ds_read_b128 v[192:195], v148 offset:32768
	ds_read_b128 v[196:199], v148 offset:33792
	ds_read_b128 v[200:203], v148 offset:34816
	ds_read_b128 v[204:207], v148 offset:35840
	ds_read_b128 v[208:211], v148 offset:36864
	ds_read_b128 v[212:215], v148 offset:37888
	ds_read_b128 v[216:219], v148 offset:38912
	ds_read_b128 v[220:223], v148 offset:39936
	s_nop 0
	global_load_lds_dwordx4 v136, s[44:45]
	v_mov_b32_e32 v136, v134
	s_mov_b32 m0, s70
	s_nop 0
	global_load_lds_dwordx4 v136, s[44:45]
	s_waitcnt vmcnt(8)
	s_waitcnt lgkmcnt(0)
	s_barrier
	s_waitcnt lgkmcnt(0)
	v_mfma_f32_16x16x32_bf16 v[124:127], v[128:131], v[192:195], v[124:127]
	v_mfma_f32_16x16x32_bf16 v[120:123], v[154:157], v[192:195], v[120:123]
	v_mfma_f32_16x16x32_bf16 v[116:119], v[128:131], v[200:203], v[116:119]
	v_mfma_f32_16x16x32_bf16 v[108:111], v[154:157], v[200:203], v[108:111]
	v_mfma_f32_16x16x32_bf16 v[100:103], v[128:131], v[208:211], v[100:103]
	v_mfma_f32_16x16x32_bf16 v[92:95], v[154:157], v[208:211], v[92:95]
	v_mfma_f32_16x16x32_bf16 v[84:87], v[128:131], v[216:219], v[84:87]
	v_mfma_f32_16x16x32_bf16 v[76:79], v[154:157], v[216:219], v[76:79]
	v_mfma_f32_16x16x32_bf16 v[124:127], v[150:153], v[196:199], v[124:127]
	v_mfma_f32_16x16x32_bf16 v[120:123], v[158:161], v[196:199], v[120:123]
	v_mfma_f32_16x16x32_bf16 v[116:119], v[150:153], v[204:207], v[116:119]
	v_mfma_f32_16x16x32_bf16 v[108:111], v[158:161], v[204:207], v[108:111]
	v_mfma_f32_16x16x32_bf16 v[100:103], v[150:153], v[212:215], v[100:103]
	v_mfma_f32_16x16x32_bf16 v[92:95], v[158:161], v[212:215], v[92:95]
	v_mfma_f32_16x16x32_bf16 v[84:87], v[150:153], v[220:223], v[84:87]
	v_mfma_f32_16x16x32_bf16 v[76:79], v[158:161], v[220:223], v[76:79]
	v_mfma_f32_16x16x32_bf16 v[112:115], v[176:179], v[192:195], v[112:115]
	v_mfma_f32_16x16x32_bf16 v[104:107], v[184:187], v[192:195], v[104:107]
	v_mfma_f32_16x16x32_bf16 v[96:99], v[176:179], v[200:203], v[96:99]
	v_mfma_f32_16x16x32_bf16 v[88:91], v[184:187], v[200:203], v[88:91]
	v_mfma_f32_16x16x32_bf16 v[80:83], v[176:179], v[208:211], v[80:83]
	v_mfma_f32_16x16x32_bf16 v[72:75], v[184:187], v[208:211], v[72:75]
	v_mfma_f32_16x16x32_bf16 v[68:71], v[176:179], v[216:219], v[68:71]
	v_mfma_f32_16x16x32_bf16 v[64:67], v[184:187], v[216:219], v[64:67]
	v_mfma_f32_16x16x32_bf16 v[112:115], v[180:183], v[196:199], v[112:115]
	v_mfma_f32_16x16x32_bf16 v[104:107], v[188:191], v[196:199], v[104:107]
	v_mfma_f32_16x16x32_bf16 v[96:99], v[180:183], v[204:207], v[96:99]
	v_mfma_f32_16x16x32_bf16 v[88:91], v[188:191], v[204:207], v[88:91]
	v_mfma_f32_16x16x32_bf16 v[80:83], v[180:183], v[212:215], v[80:83]
	v_mfma_f32_16x16x32_bf16 v[72:75], v[188:191], v[212:215], v[72:75]
	v_mfma_f32_16x16x32_bf16 v[68:71], v[180:183], v[220:223], v[68:71]
	v_mfma_f32_16x16x32_bf16 v[64:67], v[188:191], v[220:223], v[64:67]
	s_barrier
; #define PG8_LDA(dst, b, h) do { _Pragma("unroll") for (int m = 0; m < 4; ++m) _Pragma("unroll") for (int k = 0; k < 2; ++k) dst[m][k] = *(const LAS bf16x8*)(lds + PG8_SA(b, h) + aoff + m * 2048 + k * 1024); } while (0)
; #define PG8_LDB(dst, b, h) do { _Pragma("unroll") for (int n = 0; n < 2; ++n) _Pragma("unroll") for (int k = 0; k < 2; ++k) dst[n][k] = *(const LAS bf16x8*)(lds + PG8_SB(b, h) + boff + n * 2048 + k * 1024); } while (0)
; #define PG8_MMA(ai, bj, At, Bt) do { __builtin_amdgcn_s_setprio(1); _Pragma("unroll") for (int m = 0; m < 4; ++m) _Pragma("unroll") for (int n = 0; n < 2; ++n) _Pragma("unroll") for (int k = 0; k < 2; ++k) \
;         acc[ai][bj][m][n] = __builtin_amdgcn_mfma_f32_16x16x32_bf16(Bt[n][k], At[m][k], acc[ai][bj][m][n], 0, 0, 0); __builtin_amdgcn_s_setprio(0); } while (0)
; #define PG8_WAIT_V(n) asm volatile("s_waitcnt vmcnt(" #n ")" ::: "memory")
; #define PG8_WAIT_L(n) asm volatile("s_waitcnt lgkmcnt(" #n ")" ::: "memory")
; #define PG8_BAR __builtin_amdgcn_s_barrier()
; #define PG8_SCHED __builtin_amdgcn_sched_barrier(0)
; template <class Epi, bool ALIGN_EPI = true, bool SP2 = true>
; DI void gemm_phase(LAS unsigned char* lds, const Gemm g, const StaticOrder& S, const Epi& E) {
;     ...
;             PG8_LDB(B0, 1, 0); PG8_LDB(B1, 1, 1); PG8_SCHED; PG8_LDA(At, 1, 0); PG8_STAGE(PG8_SA(0, 1), a2 + hstepA, voffA);
;             PG8_WAIT_V(8); PG8_WAIT_L(0); PG8_BAR; PG8_MMA(0, 0, At, B0); PG8_MMA(0, 1, At, B1); PG8_BAR; PG8_SCHED;
;             PG8_LDA(At, 1, 1); PG8_STAGE(PG8_SB(1, 0), b3, voffB); PG8_STAGE(PG8_SB(1, 1), b3 + hstep, voffB); PG8_STAGE(PG8_SA(1, 0), a3, voffA);
;             PG8_WAIT_V(8); PG8_WAIT_L(0); PG8_BAR; PG8_MMA(1, 0, At, B0); PG8_MMA(1, 1, At, B1); PG8_BAR; PG8_SCHED;
;     ...
;         if constexpr (ALIGN_EPI) { if (wr == 0) PG8_BAR; }
	s_add_u32 s44, s40, 0x80
	s_addc_u32 s45, s41, 0
	v_mov_b32_e32 v136, v133
	s_add_i32 s4, s4, s42
	ds_read_b128 v[192:195], v148 offset:49152
	ds_read_b128 v[196:199], v148 offset:50176
	ds_read_b128 v[200:203], v148 offset:51200
	ds_read_b128 v[204:207], v148 offset:52224
	ds_read_b128 v[208:211], v148 offset:53248
	ds_read_b128 v[212:215], v148 offset:54272
	ds_read_b128 v[216:219], v148 offset:55296
	ds_read_b128 v[220:223], v148 offset:56320
	s_mov_b32 m0, s4
	s_nop 0
	global_load_lds_dwordx4 v136, s[44:45]
	v_mov_b32_e32 v136, v135
	s_add_i32 m0, s4, 0x2000
	s_add_u32 s40, s40, 0x40080
	global_load_lds_dwordx4 v136, s[44:45]
	s_addc_u32 s41, s41, 0
	v_mov_b32_e32 v136, v133
	s_add_i32 s4, s5, s42
	s_mov_b32 m0, s4
	s_nop 0
	global_load_lds_dwordx4 v136, s[40:41]
	v_mov_b32_e32 v136, v135
	s_add_i32 m0, s4, 0x2000
	s_nop 0
	global_load_lds_dwordx4 v136, s[40:41]
	v_mov_b32_e32 v136, v132
	s_mov_b32 m0, s83
	s_nop 0
	global_load_lds_dwordx4 v136, s[18:19]
	v_mov_b32_e32 v136, v134
	s_mov_b32 m0, s86
	s_nop 0
	global_load_lds_dwordx4 v136, s[18:19]
	s_waitcnt vmcnt(8)
	s_waitcnt lgkmcnt(0)
	s_barrier
	s_waitcnt lgkmcnt(0)
	v_mfma_f32_16x16x32_bf16 v[60:63], v[128:131], v[192:195], v[60:63]
	v_mfma_f32_16x16x32_bf16 v[56:59], v[154:157], v[192:195], v[56:59]
	v_mfma_f32_16x16x32_bf16 v[52:55], v[128:131], v[200:203], v[52:55]
	v_mfma_f32_16x16x32_bf16 v[44:47], v[154:157], v[200:203], v[44:47]
	v_mfma_f32_16x16x32_bf16 v[36:39], v[128:131], v[208:211], v[36:39]
	v_mfma_f32_16x16x32_bf16 v[28:31], v[154:157], v[208:211], v[28:31]
	v_mfma_f32_16x16x32_bf16 v[20:23], v[128:131], v[216:219], v[20:23]
	v_mfma_f32_16x16x32_bf16 v[12:15], v[154:157], v[216:219], v[12:15]
	v_mfma_f32_16x16x32_bf16 v[60:63], v[150:153], v[196:199], v[60:63]
	v_mfma_f32_16x16x32_bf16 v[56:59], v[158:161], v[196:199], v[56:59]
	v_mfma_f32_16x16x32_bf16 v[52:55], v[150:153], v[204:207], v[52:55]
	v_mfma_f32_16x16x32_bf16 v[44:47], v[158:161], v[204:207], v[44:47]
	v_mfma_f32_16x16x32_bf16 v[36:39], v[150:153], v[212:215], v[36:39]
	v_mfma_f32_16x16x32_bf16 v[28:31], v[158:161], v[212:215], v[28:31]
	v_mfma_f32_16x16x32_bf16 v[20:23], v[150:153], v[220:223], v[20:23]
	v_mfma_f32_16x16x32_bf16 v[12:15], v[158:161], v[220:223], v[12:15]
	v_mfma_f32_16x16x32_bf16 v[48:51], v[176:179], v[192:195], v[48:51]
	v_mfma_f32_16x16x32_bf16 v[40:43], v[184:187], v[192:195], v[40:43]
	v_mfma_f32_16x16x32_bf16 v[32:35], v[176:179], v[200:203], v[32:35]
	v_mfma_f32_16x16x32_bf16 v[24:27], v[184:187], v[200:203], v[24:27]
	v_mfma_f32_16x16x32_bf16 v[16:19], v[176:179], v[208:211], v[16:19]
	v_mfma_f32_16x16x32_bf16 v[8:11], v[184:187], v[208:211], v[8:11]
	v_mfma_f32_16x16x32_bf16 v[4:7], v[176:179], v[216:219], v[4:7]
	v_mfma_f32_16x16x32_bf16 v[0:3], v[184:187], v[216:219], v[0:3]
	v_mfma_f32_16x16x32_bf16 v[48:51], v[180:183], v[196:199], v[48:51]
	v_mfma_f32_16x16x32_bf16 v[40:43], v[188:191], v[196:199], v[40:43]
	v_mfma_f32_16x16x32_bf16 v[32:35], v[180:183], v[204:207], v[32:35]
	v_mfma_f32_16x16x32_bf16 v[24:27], v[188:191], v[204:207], v[24:27]
	v_mfma_f32_16x16x32_bf16 v[16:19], v[180:183], v[212:215], v[16:19]
	v_mfma_f32_16x16x32_bf16 v[8:11], v[188:191], v[212:215], v[8:11]
	v_mfma_f32_16x16x32_bf16 v[4:7], v[180:183], v[220:223], v[4:7]
	v_mfma_f32_16x16x32_bf16 v[0:3], v[188:191], v[220:223], v[0:3]
	s_barrier
	s_add_i32 s46, s46, 2
	s_add_u32 s16, s16, 0x100
	s_addc_u32 s17, s17, 0
	s_add_u32 vcc_lo, vcc_lo, 0x100
	s_addc_u32 vcc_hi, vcc_hi, 0
	s_cmp_gt_u32 s46, 13
	s_cbranch_scc0 .LBB0_536
	s_and_b64 vcc, exec, s[6:7]
	s_cbranch_vccz .LBB0_539
	s_barrier

; #define PG8_LDA(dst, b, h) do { _Pragma("unroll") for (int m = 0; m < 4; ++m) _Pragma("unroll") for (int k = 0; k < 2; ++k) dst[m][k] = *(const LAS bf16x8*)(lds + PG8_SA(b, h) + aoff + m * 2048 + k * 1024); } while (0)
; #define PG8_LDB(dst, b, h) do { _Pragma("unroll") for (int n = 0; n < 2; ++n) _Pragma("unroll") for (int k = 0; k < 2; ++k) dst[n][k] = *(const LAS bf16x8*)(lds + PG8_SB(b, h) + boff + n * 2048 + k * 1024); } while (0)
; #define PG8_MMA(ai, bj, At, Bt) do { __builtin_amdgcn_s_setprio(1); _Pragma("unroll") for (int m = 0; m < 4; ++m) _Pragma("unroll") for (int n = 0; n < 2; ++n) _Pragma("unroll") for (int k = 0; k < 2; ++k) \
;         acc[ai][bj][m][n] = __builtin_amdgcn_mfma_f32_16x16x32_bf16(Bt[n][k], At[m][k], acc[ai][bj][m][n], 0, 0, 0); __builtin_amdgcn_s_setprio(0); } while (0)
; #define PG8_WAIT_V(n) asm volatile("s_waitcnt vmcnt(" #n ")" ::: "memory")
; #define PG8_WAIT_L(n) asm volatile("s_waitcnt lgkmcnt(" #n ")" ::: "memory")
; #define PG8_BAR __builtin_amdgcn_s_barrier()
; #define PG8_SCHED __builtin_amdgcn_sched_barrier(0)
; template <class Epi, bool ALIGN_EPI = true, bool SP2 = true>
; DI void gemm_phase(LAS unsigned char* lds, const Gemm g, const StaticOrder& S, const Epi& E) {
;     ...
;     for (;;) {
;         const bool has_next = S.next(ui + 1, nxt);
;         const char* nA = has_next ? (const char*)g.A + (size_t)nxt.pm * tstepA : cA; const char* nB = has_next ? (const char*)g.Bt + (size_t)nxt.pn * tstep : cB;
;         for (int t = 0; t < nt; t += 2) {
;             const bool last = (t == nt - 2);
;             const char* a1 = cA + (size_t)(t + 1) * kstep;
;             const char* a2 = last ? nA : cA + (size_t)(t + 2) * kstep; const char* b2 = last ? nB : cB + (size_t)(t + 2) * kstep;
;             const char* a3 = a2 + kstep; const char* b3 = b2 + kstep;
;             if constexpr (SP2) {
;             PG8_LDB(B0, 0, 0); PG8_LDB(B1, 0, 1); PG8_SCHED; PG8_LDA(At, 0, 0); PG8_STAGE(PG8_SA(1, 1), a1 + hstepA, voffA);
;             PG8_WAIT_V(8); PG8_WAIT_L(0); PG8_BAR; PG8_MMA(0, 0, At, B0); PG8_MMA(0, 1, At, B1); PG8_BAR; PG8_SCHED;
;             PG8_LDA(At, 0, 1); PG8_STAGE(PG8_SB(0, 0), b2, voffB); PG8_STAGE(PG8_SB(0, 1), b2 + hstep, voffB); PG8_STAGE(PG8_SA(0, 0), a2, voffA);
;             PG8_WAIT_V(8); PG8_WAIT_L(0); PG8_BAR; PG8_MMA(1, 0, At, B0); PG8_MMA(1, 1, At, B1); PG8_BAR; PG8_SCHED;
.LBB0_556:
	s_ashr_i32 s15, s14, 31
	s_lshl_b64 s[6:7], s[14:15], 17
	v_readlane_b32 s8, v254, 25
	s_add_u32 s40, s8, s6
	v_readlane_b32 s6, v254, 26
	s_addc_u32 s41, s6, s7
	s_and_b64 s[6:7], s[2:3], exec
	s_cselect_b32 s49, s41, s17
	s_cselect_b32 s48, s40, s16
	s_ashr_i32 s13, s12, 31
	s_lshl_b64 s[6:7], s[12:13], 17
	s_add_u32 s18, s26, s6
	s_addc_u32 s19, s34, s7
	s_and_b64 s[6:7], s[2:3], exec
	s_cselect_b32 s45, s19, s47
	s_cselect_b32 s44, s18, s46
	s_add_u32 s8, s16, 0x100
	s_addc_u32 s9, s17, 0
	s_add_u32 s42, s46, 0x100
	s_addc_u32 s43, s47, 0
	s_add_u32 s6, s16, 0x180
	s_addc_u32 s7, s17, 0
	s_add_i32 s86, 0, 0x10000
	s_add_i32 s96, 0, 0x14000
	v_add_u32_e32 v134, s86, v132
	v_add_u32_e32 v135, s96, v132
	ds_read_b128 v[0:3], v134
	ds_read_b128 v[4:7], v134 offset:1024
	ds_read_b128 v[8:11], v134 offset:2048
	ds_read_b128 v[12:15], v134 offset:3072
	ds_read_b128 v[16:19], v135
	ds_read_b128 v[20:23], v135 offset:1024
	ds_read_b128 v[24:27], v135 offset:2048
	ds_read_b128 v[28:31], v135 offset:3072
	v_mov_b32_e32 v169, 0x41b17218
	v_mov_b64_e32 v[160:161], 0x400
	v_mov_b32_e32 v143, 0x3eaaaaab
	s_add_u32 s94, s16, 0x10080
	s_addc_u32 s95, s17, 0
	v_mov_b32_e32 v64, v128
	s_add_i32 s92, s54, 0xc000
	ds_read_b128 v[32:35], v133
	ds_read_b128 v[36:39], v133 offset:1024
	ds_read_b128 v[40:43], v133 offset:2048
	ds_read_b128 v[44:47], v133 offset:3072
	ds_read_b128 v[48:51], v133 offset:4096
	ds_read_b128 v[52:55], v133 offset:5120
	ds_read_b128 v[56:59], v133 offset:6144
	ds_read_b128 v[60:63], v133 offset:7168
	s_mov_b32 m0, s92
	s_add_i32 s13, s54, 0xe000
	global_load_lds_dwordx4 v64, s[94:95]
	v_mov_b32_e32 v64, v130
	s_mov_b32 m0, s13
	s_nop 0
	global_load_lds_dwordx4 v64, s[94:95]
	s_waitcnt vmcnt(8)
	s_waitcnt lgkmcnt(0)
	s_barrier
	s_waitcnt lgkmcnt(0)
	v_mfma_f32_16x16x32_bf16 v[64:67], v[0:3], v[32:35], 0
	v_mfma_f32_16x16x32_bf16 v[68:71], v[8:11], v[32:35], 0
	v_mfma_f32_16x16x32_bf16 v[72:75], v[0:3], v[40:43], 0
	v_mfma_f32_16x16x32_bf16 v[76:79], v[8:11], v[40:43], 0
	v_mfma_f32_16x16x32_bf16 v[80:83], v[0:3], v[48:51], 0
	v_mfma_f32_16x16x32_bf16 v[84:87], v[8:11], v[48:51], 0
	v_mfma_f32_16x16x32_bf16 v[88:91], v[0:3], v[56:59], 0
	v_mfma_f32_16x16x32_bf16 v[92:95], v[8:11], v[56:59], 0
	v_mfma_f32_16x16x32_bf16 v[64:67], v[4:7], v[36:39], v[64:67]
	v_mfma_f32_16x16x32_bf16 v[68:71], v[12:15], v[36:39], v[68:71]
	v_mfma_f32_16x16x32_bf16 v[72:75], v[4:7], v[44:47], v[72:75]
	v_mfma_f32_16x16x32_bf16 v[76:79], v[12:15], v[44:47], v[76:79]
	v_mfma_f32_16x16x32_bf16 v[80:83], v[4:7], v[52:55], v[80:83]
	v_mfma_f32_16x16x32_bf16 v[84:87], v[12:15], v[52:55], v[84:87]
	v_mfma_f32_16x16x32_bf16 v[88:91], v[4:7], v[60:63], v[88:91]
	v_mfma_f32_16x16x32_bf16 v[92:95], v[12:15], v[60:63], v[92:95]
	v_mfma_f32_16x16x32_bf16 v[96:99], v[16:19], v[32:35], 0
	v_mfma_f32_16x16x32_bf16 v[32:35], v[24:27], v[32:35], 0
	v_mfma_f32_16x16x32_bf16 v[96:99], v[20:23], v[36:39], v[96:99]
	v_mfma_f32_16x16x32_bf16 v[32:35], v[28:31], v[36:39], v[32:35]
	v_mfma_f32_16x16x32_bf16 v[36:39], v[16:19], v[40:43], 0
	v_mfma_f32_16x16x32_bf16 v[40:43], v[24:27], v[40:43], 0
	v_mfma_f32_16x16x32_bf16 v[36:39], v[20:23], v[44:47], v[36:39]
	v_mfma_f32_16x16x32_bf16 v[40:43], v[28:31], v[44:47], v[40:43]
	v_mfma_f32_16x16x32_bf16 v[44:47], v[16:19], v[48:51], 0
	v_mfma_f32_16x16x32_bf16 v[48:51], v[24:27], v[48:51], 0
	v_mfma_f32_16x16x32_bf16 v[44:47], v[20:23], v[52:55], v[44:47]
	v_mfma_f32_16x16x32_bf16 v[48:51], v[28:31], v[52:55], v[48:51]
	v_mfma_f32_16x16x32_bf16 v[52:55], v[16:19], v[56:59], 0
	v_mfma_f32_16x16x32_bf16 v[56:59], v[24:27], v[56:59], 0
	v_mfma_f32_16x16x32_bf16 v[52:55], v[20:23], v[60:63], v[52:55]
	v_mfma_f32_16x16x32_bf16 v[56:59], v[28:31], v[60:63], v[56:59]
	s_barrier
	v_mov_b32_e32 v136, v129
	s_add_i32 s86, s86, s36
	ds_read_b128 v[60:63], v133 offset:16384
	ds_read_b128 v[100:103], v133 offset:17408
	ds_read_b128 v[104:107], v133 offset:18432
	ds_read_b128 v[108:111], v133 offset:19456
	ds_read_b128 v[112:115], v133 offset:20480
	ds_read_b128 v[116:119], v133 offset:21504
	ds_read_b128 v[120:123], v133 offset:22528
	ds_read_b128 v[124:127], v133 offset:23552
	s_mov_b32 m0, s86
	s_add_i32 s15, s86, 0x2000
	global_load_lds_dwordx4 v136, s[42:43]
	v_mov_b32_e32 v136, v131
	s_mov_b32 m0, s15
	s_add_u32 s94, s46, 0x10100
	global_load_lds_dwordx4 v136, s[42:43]
	s_addc_u32 s95, s47, 0
	v_mov_b32_e32 v136, v129
	s_add_i32 s42, s96, s36
	s_mov_b32 m0, s42
	s_add_i32 s43, s42, 0x2000
	global_load_lds_dwordx4 v136, s[94:95]
	v_mov_b32_e32 v136, v131
	s_mov_b32 m0, s43
	s_nop 0
	global_load_lds_dwordx4 v136, s[94:95]
	v_mov_b32_e32 v136, v128
	s_mov_b32 m0, s54
	s_nop 0
	global_load_lds_dwordx4 v136, s[8:9]
	v_mov_b32_e32 v136, v130
	s_mov_b32 m0, s55
	s_nop 0
	global_load_lds_dwordx4 v136, s[8:9]
	s_waitcnt vmcnt(8)
	s_waitcnt lgkmcnt(0)
	s_barrier
; #define PG8_LDA(dst, b, h) do { _Pragma("unroll") for (int m = 0; m < 4; ++m) _Pragma("unroll") for (int k = 0; k < 2; ++k) dst[m][k] = *(const LAS bf16x8*)(lds + PG8_SA(b, h) + aoff + m * 2048 + k * 1024); } while (0)
; #define PG8_LDB(dst, b, h) do { _Pragma("unroll") for (int n = 0; n < 2; ++n) _Pragma("unroll") for (int k = 0; k < 2; ++k) dst[n][k] = *(const LAS bf16x8*)(lds + PG8_SB(b, h) + boff + n * 2048 + k * 1024); } while (0)
; #define PG8_MMA(ai, bj, At, Bt) do { __builtin_amdgcn_s_setprio(1); _Pragma("unroll") for (int m = 0; m < 4; ++m) _Pragma("unroll") for (int n = 0; n < 2; ++n) _Pragma("unroll") for (int k = 0; k < 2; ++k) \
;         acc[ai][bj][m][n] = __builtin_amdgcn_mfma_f32_16x16x32_bf16(Bt[n][k], At[m][k], acc[ai][bj][m][n], 0, 0, 0); __builtin_amdgcn_s_setprio(0); } while (0)
; #define PG8_WAIT_V(n) asm volatile("s_waitcnt vmcnt(" #n ")" ::: "memory")
; #define PG8_WAIT_L(n) asm volatile("s_waitcnt lgkmcnt(" #n ")" ::: "memory")
; #define PG8_BAR __builtin_amdgcn_s_barrier()
; #define PG8_SCHED __builtin_amdgcn_sched_barrier(0)
; template <class Epi, bool ALIGN_EPI = true, bool SP2 = true>
; DI void gemm_phase(LAS unsigned char* lds, const Gemm g, const StaticOrder& S, const Epi& E) {
;     ...
;             PG8_WAIT_V(8); PG8_WAIT_L(0); PG8_BAR; PG8_MMA(1, 0, At, B0); PG8_MMA(1, 1, At, B1); PG8_BAR; PG8_SCHED;
;             PG8_LDB(B0, 1, 0); PG8_LDB(B1, 1, 1); PG8_SCHED; PG8_LDA(At, 1, 0); PG8_STAGE(PG8_SA(0, 1), a2 + hstepA, voffA);
;             PG8_WAIT_V(8); PG8_WAIT_L(0); PG8_BAR; PG8_MMA(0, 0, At, B0); PG8_MMA(0, 1, At, B1); PG8_BAR; PG8_SCHED;
;             PG8_LDA(At, 1, 1); PG8_STAGE(PG8_SB(1, 0), b3, voffB); PG8_STAGE(PG8_SB(1, 1), b3 + hstep, voffB); PG8_STAGE(PG8_SA(1, 0), a3, voffA);
	s_waitcnt lgkmcnt(0)
	v_mfma_f32_16x16x32_bf16 v[148:151], v[0:3], v[60:63], 0
	v_mfma_f32_16x16x32_bf16 v[156:159], v[0:3], v[104:107], 0
	v_mfma_f32_16x16x32_bf16 v[180:183], v[0:3], v[112:115], 0
	v_mfma_f32_16x16x32_bf16 v[0:3], v[0:3], v[120:123], 0
	v_mfma_f32_16x16x32_bf16 v[148:151], v[4:7], v[100:103], v[148:151]
	v_mfma_f32_16x16x32_bf16 v[156:159], v[4:7], v[108:111], v[156:159]
	v_mfma_f32_16x16x32_bf16 v[180:183], v[4:7], v[116:119], v[180:183]
	v_mfma_f32_16x16x32_bf16 v[0:3], v[4:7], v[124:127], v[0:3]
	v_mfma_f32_16x16x32_bf16 v[4:7], v[8:11], v[120:123], 0
	v_mfma_f32_16x16x32_bf16 v[152:155], v[8:11], v[60:63], 0
	v_mfma_f32_16x16x32_bf16 v[176:179], v[8:11], v[104:107], 0
	v_mfma_f32_16x16x32_bf16 v[184:187], v[8:11], v[112:115], 0
	v_mfma_f32_16x16x32_bf16 v[4:7], v[12:15], v[124:127], v[4:7]
	v_mfma_f32_16x16x32_bf16 v[152:155], v[12:15], v[100:103], v[152:155]
	v_mfma_f32_16x16x32_bf16 v[176:179], v[12:15], v[108:111], v[176:179]
	v_mfma_f32_16x16x32_bf16 v[184:187], v[12:15], v[116:119], v[184:187]
	v_mfma_f32_16x16x32_bf16 v[8:11], v[16:19], v[60:63], 0
	v_mfma_f32_16x16x32_bf16 v[12:15], v[24:27], v[60:63], 0
	v_mfma_f32_16x16x32_bf16 v[8:11], v[20:23], v[100:103], v[8:11]
	v_mfma_f32_16x16x32_bf16 v[12:15], v[28:31], v[100:103], v[12:15]
	v_mfma_f32_16x16x32_bf16 v[60:63], v[16:19], v[104:107], 0
	v_mfma_f32_16x16x32_bf16 v[100:103], v[24:27], v[104:107], 0
	v_mfma_f32_16x16x32_bf16 v[104:107], v[16:19], v[112:115], 0
	v_mfma_f32_16x16x32_bf16 v[16:19], v[16:19], v[120:123], 0
	v_mfma_f32_16x16x32_bf16 v[60:63], v[20:23], v[108:111], v[60:63]
	v_mfma_f32_16x16x32_bf16 v[100:103], v[28:31], v[108:111], v[100:103]
	v_mfma_f32_16x16x32_bf16 v[104:107], v[20:23], v[116:119], v[104:107]
	v_mfma_f32_16x16x32_bf16 v[108:111], v[24:27], v[112:115], 0
	v_mfma_f32_16x16x32_bf16 v[16:19], v[20:23], v[124:127], v[16:19]
	v_mfma_f32_16x16x32_bf16 v[20:23], v[24:27], v[120:123], 0
	v_mfma_f32_16x16x32_bf16 v[108:111], v[28:31], v[116:119], v[108:111]
	v_mfma_f32_16x16x32_bf16 v[20:23], v[28:31], v[124:127], v[20:23]
	s_barrier
	s_add_i32 s96, 0, 0x18000
	s_add_i32 s97, 0, 0x1c000
	v_add_u32_e32 v136, s96, v132
	v_add_u32_e32 v138, s97, v132
	ds_read_b128 v[24:27], v136
	ds_read_b128 v[28:31], v136 offset:1024
	ds_read_b128 v[112:115], v136 offset:2048
	ds_read_b128 v[116:119], v136 offset:3072
	ds_read_b128 v[120:123], v138
	ds_read_b128 v[124:127], v138 offset:1024
	ds_read_b128 v[188:191], v138 offset:2048
	ds_read_b128 v[192:195], v138 offset:3072
	s_add_u32 s8, s16, 0x10100
	s_addc_u32 s9, s17, 0
	v_mov_b32_e32 v139, v128
	s_mov_b32 m0, s69
	ds_read_b128 v[196:199], v133 offset:32768
	ds_read_b128 v[200:203], v133 offset:33792
	ds_read_b128 v[204:207], v133 offset:34816
	ds_read_b128 v[208:211], v133 offset:35840
	ds_read_b128 v[212:215], v133 offset:36864
	ds_read_b128 v[216:219], v133 offset:37888
	ds_read_b128 v[220:223], v133 offset:38912
	ds_read_b128 v[224:227], v133 offset:39936
	s_nop 0
	global_load_lds_dwordx4 v139, s[8:9]
	v_mov_b32_e32 v139, v130
	s_mov_b32 m0, s70
	s_nop 0
	global_load_lds_dwordx4 v139, s[8:9]
	s_waitcnt vmcnt(8)
	s_waitcnt lgkmcnt(0)
	s_barrier
	s_waitcnt lgkmcnt(0)
	v_mfma_f32_16x16x32_bf16 v[64:67], v[24:27], v[196:199], v[64:67]
	v_mfma_f32_16x16x32_bf16 v[68:71], v[112:115], v[196:199], v[68:71]
	v_mfma_f32_16x16x32_bf16 v[72:75], v[24:27], v[204:207], v[72:75]
	v_mfma_f32_16x16x32_bf16 v[76:79], v[112:115], v[204:207], v[76:79]
	v_mfma_f32_16x16x32_bf16 v[80:83], v[24:27], v[212:215], v[80:83]
	v_mfma_f32_16x16x32_bf16 v[84:87], v[112:115], v[212:215], v[84:87]
	v_mfma_f32_16x16x32_bf16 v[88:91], v[24:27], v[220:223], v[88:91]
	v_mfma_f32_16x16x32_bf16 v[92:95], v[112:115], v[220:223], v[92:95]
	v_mfma_f32_16x16x32_bf16 v[64:67], v[28:31], v[200:203], v[64:67]
	v_mfma_f32_16x16x32_bf16 v[68:71], v[116:119], v[200:203], v[68:71]
	v_mfma_f32_16x16x32_bf16 v[72:75], v[28:31], v[208:211], v[72:75]
	v_mfma_f32_16x16x32_bf16 v[76:79], v[116:119], v[208:211], v[76:79]
	v_mfma_f32_16x16x32_bf16 v[80:83], v[28:31], v[216:219], v[80:83]
	v_mfma_f32_16x16x32_bf16 v[84:87], v[116:119], v[216:219], v[84:87]
	v_mfma_f32_16x16x32_bf16 v[88:91], v[28:31], v[224:227], v[88:91]
	v_mfma_f32_16x16x32_bf16 v[92:95], v[116:119], v[224:227], v[92:95]
	v_mfma_f32_16x16x32_bf16 v[96:99], v[120:123], v[196:199], v[96:99]
	v_mfma_f32_16x16x32_bf16 v[32:35], v[188:191], v[196:199], v[32:35]
	v_mfma_f32_16x16x32_bf16 v[36:39], v[120:123], v[204:207], v[36:39]
	v_mfma_f32_16x16x32_bf16 v[40:43], v[188:191], v[204:207], v[40:43]
	v_mfma_f32_16x16x32_bf16 v[44:47], v[120:123], v[212:215], v[44:47]
	v_mfma_f32_16x16x32_bf16 v[48:51], v[188:191], v[212:215], v[48:51]
	v_mfma_f32_16x16x32_bf16 v[52:55], v[120:123], v[220:223], v[52:55]
	v_mfma_f32_16x16x32_bf16 v[56:59], v[188:191], v[220:223], v[56:59]
	v_mfma_f32_16x16x32_bf16 v[96:99], v[124:127], v[200:203], v[96:99]
	v_mfma_f32_16x16x32_bf16 v[32:35], v[192:195], v[200:203], v[32:35]
	v_mfma_f32_16x16x32_bf16 v[36:39], v[124:127], v[208:211], v[36:39]
	v_mfma_f32_16x16x32_bf16 v[40:43], v[192:195], v[208:211], v[40:43]
	v_mfma_f32_16x16x32_bf16 v[44:47], v[124:127], v[216:219], v[44:47]
	v_mfma_f32_16x16x32_bf16 v[48:51], v[192:195], v[216:219], v[48:51]
	v_mfma_f32_16x16x32_bf16 v[52:55], v[124:127], v[224:227], v[52:55]
	v_mfma_f32_16x16x32_bf16 v[56:59], v[192:195], v[224:227], v[56:59]
	s_barrier
; #define PG8_LDA(dst, b, h) do { _Pragma("unroll") for (int m = 0; m < 4; ++m) _Pragma("unroll") for (int k = 0; k < 2; ++k) dst[m][k] = *(const LAS bf16x8*)(lds + PG8_SA(b, h) + aoff + m * 2048 + k * 1024); } while (0)
; #define PG8_LDB(dst, b, h) do { _Pragma("unroll") for (int n = 0; n < 2; ++n) _Pragma("unroll") for (int k = 0; k < 2; ++k) dst[n][k] = *(const LAS bf16x8*)(lds + PG8_SB(b, h) + boff + n * 2048 + k * 1024); } while (0)
; #define PG8_MMA(ai, bj, At, Bt) do { __builtin_amdgcn_s_setprio(1); _Pragma("unroll") for (int m = 0; m < 4; ++m) _Pragma("unroll") for (int n = 0; n < 2; ++n) _Pragma("unroll") for (int k = 0; k < 2; ++k) \
;         acc[ai][bj][m][n] = __builtin_amdgcn_mfma_f32_16x16x32_bf16(Bt[n][k], At[m][k], acc[ai][bj][m][n], 0, 0, 0); __builtin_amdgcn_s_setprio(0); } while (0)
; #define PG8_WAIT_V(n) asm volatile("s_waitcnt vmcnt(" #n ")" ::: "memory")
; #define PG8_WAIT_L(n) asm volatile("s_waitcnt lgkmcnt(" #n ")" ::: "memory")
; #define PG8_BAR __builtin_amdgcn_s_barrier()
; #define PG8_SCHED __builtin_amdgcn_sched_barrier(0)
; template <class Epi, bool ALIGN_EPI = true, bool SP2 = true>
; DI void gemm_phase(LAS unsigned char* lds, const Gemm g, const StaticOrder& S, const Epi& E) {
;     ...
;             PG8_LDB(B0, 0, 0); PG8_LDB(B1, 0, 1); PG8_SCHED; PG8_LDA(At, 0, 0); PG8_STAGE(PG8_SA(1, 1), a1 + hstepA, voffA);
;             PG8_WAIT_V(8); PG8_WAIT_L(0); PG8_BAR; PG8_MMA(0, 0, At, B0); PG8_MMA(0, 1, At, B1); PG8_BAR; PG8_SCHED;
;             PG8_LDA(At, 0, 1); PG8_STAGE(PG8_SB(0, 0), b2, voffB); PG8_STAGE(PG8_SB(0, 1), b2 + hstep, voffB); PG8_STAGE(PG8_SA(0, 0), a2, voffA);
;             PG8_WAIT_V(8); PG8_WAIT_L(0); PG8_BAR; PG8_MMA(1, 0, At, B0); PG8_MMA(1, 1, At, B1); PG8_BAR; PG8_SCHED;
;             PG8_LDB(B0, 1, 0); PG8_LDB(B1, 1, 1); PG8_SCHED; PG8_LDA(At, 1, 0); PG8_STAGE(PG8_SA(0, 1), a2 + hstepA, voffA);
;             PG8_WAIT_V(8); PG8_WAIT_L(0); PG8_BAR; PG8_MMA(0, 0, At, B0); PG8_MMA(0, 1, At, B1); PG8_BAR; PG8_SCHED;
;             PG8_LDA(At, 1, 1); PG8_STAGE(PG8_SB(1, 0), b3, voffB); PG8_STAGE(PG8_SB(1, 1), b3 + hstep, voffB); PG8_STAGE(PG8_SA(1, 0), a3, voffA);
;             PG8_WAIT_V(8); PG8_WAIT_L(0); PG8_BAR; PG8_MMA(1, 0, At, B0); PG8_MMA(1, 1, At, B1); PG8_BAR; PG8_SCHED;
	s_add_u32 s94, s46, 0x180
	s_addc_u32 s95, s47, 0
	v_mov_b32_e32 v139, v129
	s_add_i32 s96, s96, s36
	ds_read_b128 v[196:199], v133 offset:49152
	ds_read_b128 v[200:203], v133 offset:50176
	ds_read_b128 v[204:207], v133 offset:51200
	ds_read_b128 v[208:211], v133 offset:52224
	ds_read_b128 v[212:215], v133 offset:53248
	ds_read_b128 v[216:219], v133 offset:54272
	ds_read_b128 v[220:223], v133 offset:55296
	ds_read_b128 v[224:227], v133 offset:56320
	s_mov_b32 m0, s96
	s_add_i32 s8, s96, 0x2000
	global_load_lds_dwordx4 v139, s[94:95]
	v_mov_b32_e32 v139, v131
	s_mov_b32 m0, s8
	s_nop 0
	global_load_lds_dwordx4 v139, s[94:95]
	s_add_u32 s94, s46, 0x10180
	s_addc_u32 s95, s47, 0
	v_mov_b32_e32 v139, v129
	s_add_i32 s9, s97, s36
	s_mov_b32 m0, s9
	s_add_i32 s46, s9, 0x2000
	global_load_lds_dwordx4 v139, s[94:95]
	v_mov_b32_e32 v139, v131
	s_mov_b32 m0, s46
	s_nop 0
	global_load_lds_dwordx4 v139, s[94:95]
	v_mov_b32_e32 v139, v128
	s_mov_b32 m0, s73
	s_nop 0
	global_load_lds_dwordx4 v139, s[6:7]
	v_mov_b32_e32 v139, v130
	s_mov_b32 m0, s81
	s_nop 0
	global_load_lds_dwordx4 v139, s[6:7]
	s_waitcnt vmcnt(8)
	s_waitcnt lgkmcnt(0)
	s_barrier
	s_waitcnt lgkmcnt(0)
	v_mfma_f32_16x16x32_bf16 v[0:3], v[24:27], v[220:223], v[0:3]
	v_mfma_f32_16x16x32_bf16 v[4:7], v[112:115], v[220:223], v[4:7]
	v_mfma_f32_16x16x32_bf16 v[148:151], v[24:27], v[196:199], v[148:151]
	v_mfma_f32_16x16x32_bf16 v[152:155], v[112:115], v[196:199], v[152:155]
	v_mfma_f32_16x16x32_bf16 v[156:159], v[24:27], v[204:207], v[156:159]
	v_mfma_f32_16x16x32_bf16 v[176:179], v[112:115], v[204:207], v[176:179]
	v_mfma_f32_16x16x32_bf16 v[180:183], v[24:27], v[212:215], v[180:183]
	v_mfma_f32_16x16x32_bf16 v[184:187], v[112:115], v[212:215], v[184:187]
	v_mfma_f32_16x16x32_bf16 v[0:3], v[28:31], v[224:227], v[0:3]
	v_mfma_f32_16x16x32_bf16 v[4:7], v[116:119], v[224:227], v[4:7]
	v_mfma_f32_16x16x32_bf16 v[148:151], v[28:31], v[200:203], v[148:151]
	v_mfma_f32_16x16x32_bf16 v[152:155], v[116:119], v[200:203], v[152:155]
	v_mfma_f32_16x16x32_bf16 v[156:159], v[28:31], v[208:211], v[156:159]
	v_mfma_f32_16x16x32_bf16 v[176:179], v[116:119], v[208:211], v[176:179]
	v_mfma_f32_16x16x32_bf16 v[180:183], v[28:31], v[216:219], v[180:183]
	v_mfma_f32_16x16x32_bf16 v[184:187], v[116:119], v[216:219], v[184:187]
	v_mfma_f32_16x16x32_bf16 v[8:11], v[120:123], v[196:199], v[8:11]
	v_mfma_f32_16x16x32_bf16 v[12:15], v[188:191], v[196:199], v[12:15]
	v_mfma_f32_16x16x32_bf16 v[24:27], v[120:123], v[204:207], v[60:63]
	v_mfma_f32_16x16x32_bf16 v[28:31], v[188:191], v[204:207], v[100:103]
	v_mfma_f32_16x16x32_bf16 v[60:63], v[120:123], v[212:215], v[104:107]
	v_mfma_f32_16x16x32_bf16 v[100:103], v[188:191], v[212:215], v[108:111]
	v_mfma_f32_16x16x32_bf16 v[16:19], v[120:123], v[220:223], v[16:19]
	v_mfma_f32_16x16x32_bf16 v[20:23], v[188:191], v[220:223], v[20:23]
	v_mfma_f32_16x16x32_bf16 v[8:11], v[124:127], v[200:203], v[8:11]
	v_mfma_f32_16x16x32_bf16 v[12:15], v[192:195], v[200:203], v[12:15]
	v_mfma_f32_16x16x32_bf16 v[24:27], v[124:127], v[208:211], v[24:27]
	v_mfma_f32_16x16x32_bf16 v[28:31], v[192:195], v[208:211], v[28:31]
	v_mfma_f32_16x16x32_bf16 v[60:63], v[124:127], v[216:219], v[60:63]
	v_mfma_f32_16x16x32_bf16 v[100:103], v[192:195], v[216:219], v[100:103]
	v_mfma_f32_16x16x32_bf16 v[16:19], v[124:127], v[224:227], v[16:19]
	v_mfma_f32_16x16x32_bf16 v[20:23], v[192:195], v[224:227], v[20:23]
	s_barrier
	ds_read_b128 v[104:107], v134
	ds_read_b128 v[108:111], v134 offset:1024
	ds_read_b128 v[112:115], v134 offset:2048
	ds_read_b128 v[116:119], v134 offset:3072
	ds_read_b128 v[120:123], v135
	ds_read_b128 v[124:127], v135 offset:1024
	ds_read_b128 v[188:191], v135 offset:2048
	ds_read_b128 v[192:195], v135 offset:3072
	s_add_u32 s6, s48, 0x80
	s_addc_u32 s7, s49, 0
	s_add_u32 s16, s16, 0x10180
	s_addc_u32 s17, s17, 0
	v_mov_b32_e32 v134, v128
	s_mov_b32 m0, s92
	ds_read_b128 v[196:199], v133
	ds_read_b128 v[200:203], v133 offset:1024
	ds_read_b128 v[204:207], v133 offset:2048
	ds_read_b128 v[208:211], v133 offset:3072
	ds_read_b128 v[212:215], v133 offset:4096
	ds_read_b128 v[216:219], v133 offset:5120
	ds_read_b128 v[220:223], v133 offset:6144
	ds_read_b128 v[224:227], v133 offset:7168
	s_nop 0
	global_load_lds_dwordx4 v134, s[16:17]
	v_mov_b32_e32 v134, v130
	s_mov_b32 m0, s13
	s_nop 0
	global_load_lds_dwordx4 v134, s[16:17]
	s_waitcnt vmcnt(8)
	s_waitcnt lgkmcnt(0)
	s_barrier
	s_waitcnt lgkmcnt(0)
	v_mfma_f32_16x16x32_bf16 v[64:67], v[104:107], v[196:199], v[64:67]
	v_mfma_f32_16x16x32_bf16 v[68:71], v[112:115], v[196:199], v[68:71]
	v_mfma_f32_16x16x32_bf16 v[72:75], v[104:107], v[204:207], v[72:75]
	v_mfma_f32_16x16x32_bf16 v[76:79], v[112:115], v[204:207], v[76:79]
	v_mfma_f32_16x16x32_bf16 v[80:83], v[104:107], v[212:215], v[80:83]
	v_mfma_f32_16x16x32_bf16 v[84:87], v[112:115], v[212:215], v[84:87]
	v_mfma_f32_16x16x32_bf16 v[88:91], v[104:107], v[220:223], v[88:91]
	v_mfma_f32_16x16x32_bf16 v[92:95], v[112:115], v[220:223], v[92:95]
	v_mfma_f32_16x16x32_bf16 v[64:67], v[108:111], v[200:203], v[64:67]
	v_mfma_f32_16x16x32_bf16 v[68:71], v[116:119], v[200:203], v[68:71]
	v_mfma_f32_16x16x32_bf16 v[72:75], v[108:111], v[208:211], v[72:75]
	v_mfma_f32_16x16x32_bf16 v[76:79], v[116:119], v[208:211], v[76:79]
	v_mfma_f32_16x16x32_bf16 v[80:83], v[108:111], v[216:219], v[80:83]
	v_mfma_f32_16x16x32_bf16 v[84:87], v[116:119], v[216:219], v[84:87]
	v_mfma_f32_16x16x32_bf16 v[88:91], v[108:111], v[224:227], v[88:91]
	v_mfma_f32_16x16x32_bf16 v[92:95], v[116:119], v[224:227], v[92:95]
	v_mfma_f32_16x16x32_bf16 v[36:39], v[120:123], v[204:207], v[36:39]
	v_mfma_f32_16x16x32_bf16 v[96:99], v[120:123], v[196:199], v[96:99]
	v_mfma_f32_16x16x32_bf16 v[32:35], v[188:191], v[196:199], v[32:35]
	v_mfma_f32_16x16x32_bf16 v[196:199], v[124:127], v[208:211], v[36:39]
	v_mfma_f32_16x16x32_bf16 v[36:39], v[188:191], v[204:207], v[40:43]
	v_mfma_f32_16x16x32_bf16 v[40:43], v[192:195], v[208:211], v[36:39]
	v_mfma_f32_16x16x32_bf16 v[36:39], v[120:123], v[212:215], v[44:47]
	v_mfma_f32_16x16x32_bf16 v[96:99], v[124:127], v[200:203], v[96:99]
	v_mfma_f32_16x16x32_bf16 v[32:35], v[192:195], v[200:203], v[32:35]
	v_mfma_f32_16x16x32_bf16 v[200:203], v[124:127], v[216:219], v[36:39]
	v_mfma_f32_16x16x32_bf16 v[36:39], v[188:191], v[212:215], v[48:51]
	v_mfma_f32_16x16x32_bf16 v[48:51], v[192:195], v[216:219], v[36:39]
	v_mfma_f32_16x16x32_bf16 v[36:39], v[120:123], v[220:223], v[52:55]
	v_mfma_f32_16x16x32_bf16 v[52:55], v[124:127], v[224:227], v[36:39]
	v_mfma_f32_16x16x32_bf16 v[36:39], v[188:191], v[220:223], v[56:59]
	v_mfma_f32_16x16x32_bf16 v[56:59], v[192:195], v[224:227], v[36:39]
	s_barrier
; #define PG8_LDA(dst, b, h) do { _Pragma("unroll") for (int m = 0; m < 4; ++m) _Pragma("unroll") for (int k = 0; k < 2; ++k) dst[m][k] = *(const LAS bf16x8*)(lds + PG8_SA(b, h) + aoff + m * 2048 + k * 1024); } while (0)
; #define PG8_LDB(dst, b, h) do { _Pragma("unroll") for (int n = 0; n < 2; ++n) _Pragma("unroll") for (int k = 0; k < 2; ++k) dst[n][k] = *(const LAS bf16x8*)(lds + PG8_SB(b, h) + boff + n * 2048 + k * 1024); } while (0)
; #define PG8_MMA(ai, bj, At, Bt) do { __builtin_amdgcn_s_setprio(1); _Pragma("unroll") for (int m = 0; m < 4; ++m) _Pragma("unroll") for (int n = 0; n < 2; ++n) _Pragma("unroll") for (int k = 0; k < 2; ++k) \
;         acc[ai][bj][m][n] = __builtin_amdgcn_mfma_f32_16x16x32_bf16(Bt[n][k], At[m][k], acc[ai][bj][m][n], 0, 0, 0); __builtin_amdgcn_s_setprio(0); } while (0)
; #define PG8_WAIT_V(n) asm volatile("s_waitcnt vmcnt(" #n ")" ::: "memory")
; #define PG8_WAIT_L(n) asm volatile("s_waitcnt lgkmcnt(" #n ")" ::: "memory")
; #define PG8_BAR __builtin_amdgcn_s_barrier()
; #define PG8_SCHED __builtin_amdgcn_sched_barrier(0)
; template <class Epi, bool ALIGN_EPI = true, bool SP2 = true>
; DI void gemm_phase(LAS unsigned char* lds, const Gemm g, const StaticOrder& S, const Epi& E) {
;     ...
;             PG8_LDB(B0, 0, 0); PG8_LDB(B1, 0, 1); PG8_SCHED; PG8_LDA(At, 0, 0); PG8_STAGE(PG8_SA(1, 1), a1 + hstepA, voffA);
;             PG8_WAIT_V(8); PG8_WAIT_L(0); PG8_BAR; PG8_MMA(0, 0, At, B0); PG8_MMA(0, 1, At, B1); PG8_BAR; PG8_SCHED;
;             PG8_LDA(At, 0, 1); PG8_STAGE(PG8_SB(0, 0), b2, voffB); PG8_STAGE(PG8_SB(0, 1), b2 + hstep, voffB); PG8_STAGE(PG8_SA(0, 0), a2, voffA);
;             PG8_WAIT_V(8); PG8_WAIT_L(0); PG8_BAR; PG8_MMA(1, 0, At, B0); PG8_MMA(1, 1, At, B1); PG8_BAR; PG8_SCHED;
;             PG8_LDB(B0, 1, 0); PG8_LDB(B1, 1, 1); PG8_SCHED; PG8_LDA(At, 1, 0); PG8_STAGE(PG8_SA(0, 1), a2 + hstepA, voffA);
;             PG8_WAIT_V(8); PG8_WAIT_L(0); PG8_BAR; PG8_MMA(0, 0, At, B0); PG8_MMA(0, 1, At, B1); PG8_BAR; PG8_SCHED;
;             PG8_LDA(At, 1, 1); PG8_STAGE(PG8_SB(1, 0), b3, voffB); PG8_STAGE(PG8_SB(1, 1), b3 + hstep, voffB); PG8_STAGE(PG8_SA(1, 0), a3, voffA);
;             PG8_WAIT_V(8); PG8_WAIT_L(0); PG8_BAR; PG8_MMA(1, 0, At, B0); PG8_MMA(1, 1, At, B1); PG8_BAR; PG8_SCHED;
	s_mov_b64 s[16:17], s[44:45]
	v_mov_b32_e32 v134, v129
	s_mov_b32 m0, s86
	s_nop 1
	ds_read_b128 v[36:39], v133 offset:16384
	ds_read_b128 v[44:47], v133 offset:17408
	ds_read_b128 v[204:207], v133 offset:18432
	ds_read_b128 v[208:211], v133 offset:19456
	ds_read_b128 v[212:215], v133 offset:20480
	ds_read_b128 v[216:219], v133 offset:21504
	ds_read_b128 v[220:223], v133 offset:22528
	ds_read_b128 v[224:227], v133 offset:23552
	s_nop 0
	global_load_lds_dwordx4 v134, s[16:17]
	v_mov_b32_e32 v134, v131
	s_mov_b32 m0, s15
	s_nop 0
	global_load_lds_dwordx4 v134, s[16:17]
	s_add_u32 s16, s44, 0x10000
	s_addc_u32 s17, s45, 0
	v_mov_b32_e32 v134, v129
	s_mov_b32 m0, s42
	s_nop 0
	global_load_lds_dwordx4 v134, s[16:17]
	v_mov_b32_e32 v134, v131
	s_mov_b32 m0, s43
	s_nop 0
	global_load_lds_dwordx4 v134, s[16:17]
	s_mov_b64 s[16:17], s[48:49]
	v_mov_b32_e32 v134, v128
	s_mov_b32 m0, s54
	s_nop 0
	global_load_lds_dwordx4 v134, s[16:17]
	v_mov_b32_e32 v134, v130
	s_mov_b32 m0, s55
	s_nop 0
	global_load_lds_dwordx4 v134, s[16:17]
	s_waitcnt vmcnt(8)
	s_waitcnt lgkmcnt(0)
	s_barrier
	s_waitcnt lgkmcnt(0)
	v_mfma_f32_16x16x32_bf16 v[0:3], v[104:107], v[220:223], v[0:3]
	v_mfma_f32_16x16x32_bf16 v[4:7], v[112:115], v[220:223], v[4:7]
	v_mfma_f32_16x16x32_bf16 v[148:151], v[104:107], v[36:39], v[148:151]
	v_mfma_f32_16x16x32_bf16 v[152:155], v[112:115], v[36:39], v[152:155]
	v_mfma_f32_16x16x32_bf16 v[156:159], v[104:107], v[204:207], v[156:159]
	v_mfma_f32_16x16x32_bf16 v[176:179], v[112:115], v[204:207], v[176:179]
	v_mfma_f32_16x16x32_bf16 v[180:183], v[104:107], v[212:215], v[180:183]
	v_mfma_f32_16x16x32_bf16 v[184:187], v[112:115], v[212:215], v[184:187]
	v_mfma_f32_16x16x32_bf16 v[0:3], v[108:111], v[224:227], v[0:3]
	v_mfma_f32_16x16x32_bf16 v[4:7], v[116:119], v[224:227], v[4:7]
	v_mfma_f32_16x16x32_bf16 v[148:151], v[108:111], v[44:47], v[148:151]
	v_mfma_f32_16x16x32_bf16 v[152:155], v[116:119], v[44:47], v[152:155]
	v_mfma_f32_16x16x32_bf16 v[156:159], v[108:111], v[208:211], v[156:159]
	v_mfma_f32_16x16x32_bf16 v[176:179], v[116:119], v[208:211], v[176:179]
	v_mfma_f32_16x16x32_bf16 v[180:183], v[108:111], v[216:219], v[180:183]
	v_mfma_f32_16x16x32_bf16 v[184:187], v[116:119], v[216:219], v[184:187]
	v_mfma_f32_16x16x32_bf16 v[8:11], v[120:123], v[36:39], v[8:11]
	v_mfma_f32_16x16x32_bf16 v[228:231], v[124:127], v[44:47], v[8:11]
	v_mfma_f32_16x16x32_bf16 v[8:11], v[188:191], v[36:39], v[12:15]
	v_mfma_f32_16x16x32_bf16 v[232:235], v[192:195], v[44:47], v[8:11]
	v_mfma_f32_16x16x32_bf16 v[8:11], v[120:123], v[204:207], v[24:27]
	v_mfma_f32_16x16x32_bf16 v[236:239], v[124:127], v[208:211], v[8:11]
	v_mfma_f32_16x16x32_bf16 v[8:11], v[188:191], v[204:207], v[28:31]
	v_mfma_f32_16x16x32_bf16 v[204:207], v[192:195], v[208:211], v[8:11]
	v_mfma_f32_16x16x32_bf16 v[8:11], v[120:123], v[212:215], v[60:63]
	v_mfma_f32_16x16x32_bf16 v[208:211], v[124:127], v[216:219], v[8:11]
	v_mfma_f32_16x16x32_bf16 v[8:11], v[188:191], v[212:215], v[100:103]
	v_mfma_f32_16x16x32_bf16 v[212:215], v[192:195], v[216:219], v[8:11]
	v_mfma_f32_16x16x32_bf16 v[8:11], v[120:123], v[220:223], v[16:19]
	v_mfma_f32_16x16x32_bf16 v[216:219], v[124:127], v[224:227], v[8:11]
	v_mfma_f32_16x16x32_bf16 v[8:11], v[188:191], v[220:223], v[20:23]
	v_mfma_f32_16x16x32_bf16 v[188:191], v[192:195], v[224:227], v[8:11]
	s_barrier
	s_nop 4
	ds_read_b128 v[8:11], v136
	ds_read_b128 v[12:15], v136 offset:1024
	ds_read_b128 v[16:19], v136 offset:2048
	ds_read_b128 v[20:23], v136 offset:3072
	ds_read_b128 v[192:195], v138
	ds_read_b128 v[220:223], v138 offset:1024
	ds_read_b128 v[224:227], v138 offset:2048
	ds_read_b128 v[240:243], v138 offset:3072
	s_add_u32 s16, s48, 0x10000
	s_addc_u32 s17, s49, 0
	v_mov_b32_e32 v36, v128
	s_mov_b32 m0, s69
	ds_read_b128 v[24:27], v133 offset:32768
	ds_read_b128 v[28:31], v133 offset:33792
	ds_read_b128 v[60:63], v133 offset:34816
	ds_read_b128 v[244:247], v133 offset:35840
	ds_read_b128 v[248:251], v133 offset:36864
	ds_read_b128 v[144:147], v133 offset:37888
	ds_read_b128 v[138:141], v133 offset:38912
	ds_read_b128 v[172:175], v133 offset:39936
	s_nop 0
	global_load_lds_dwordx4 v36, s[16:17]
	v_mov_b32_e32 v36, v130
	s_mov_b32 m0, s70
	s_nop 0
	global_load_lds_dwordx4 v36, s[16:17]
	s_waitcnt vmcnt(8)
	s_waitcnt lgkmcnt(0)
	s_barrier
; #define PG8_LDA(dst, b, h) do { _Pragma("unroll") for (int m = 0; m < 4; ++m) _Pragma("unroll") for (int k = 0; k < 2; ++k) dst[m][k] = *(const LAS bf16x8*)(lds + PG8_SA(b, h) + aoff + m * 2048 + k * 1024); } while (0)
; #define PG8_MMA(ai, bj, At, Bt) do { __builtin_amdgcn_s_setprio(1); _Pragma("unroll") for (int m = 0; m < 4; ++m) _Pragma("unroll") for (int n = 0; n < 2; ++n) _Pragma("unroll") for (int k = 0; k < 2; ++k) \
;         acc[ai][bj][m][n] = __builtin_amdgcn_mfma_f32_16x16x32_bf16(Bt[n][k], At[m][k], acc[ai][bj][m][n], 0, 0, 0); __builtin_amdgcn_s_setprio(0); } while (0)
; #define PG8_WAIT_V(n) asm volatile("s_waitcnt vmcnt(" #n ")" ::: "memory")
; #define PG8_WAIT_L(n) asm volatile("s_waitcnt lgkmcnt(" #n ")" ::: "memory")
; #define PG8_BAR __builtin_amdgcn_s_barrier()
; #define PG8_SCHED __builtin_amdgcn_sched_barrier(0)
; template <class Epi, bool ALIGN_EPI = true, bool SP2 = true>
; DI void gemm_phase(LAS unsigned char* lds, const Gemm g, const StaticOrder& S, const Epi& E) {
;     ...
;             PG8_WAIT_V(8); PG8_WAIT_L(0); PG8_BAR; PG8_MMA(0, 0, At, B0); PG8_MMA(0, 1, At, B1); PG8_BAR; PG8_SCHED;
;             PG8_LDA(At, 1, 1); PG8_STAGE(PG8_SB(1, 0), b3, voffB); PG8_STAGE(PG8_SB(1, 1), b3 + hstep, voffB); PG8_STAGE(PG8_SA(1, 0), a3, voffA);
;             PG8_WAIT_V(8); PG8_WAIT_L(0); PG8_BAR; PG8_MMA(1, 0, At, B0); PG8_MMA(1, 1, At, B1); PG8_BAR; PG8_SCHED;
;     ...
;         if constexpr (ALIGN_EPI) { if (wr == 0) PG8_BAR; }
	s_waitcnt lgkmcnt(0)
	v_mfma_f32_16x16x32_bf16 v[36:39], v[8:11], v[24:27], v[64:67]
	v_mfma_f32_16x16x32_bf16 v[124:127], v[12:15], v[28:31], v[36:39]
	v_mfma_f32_16x16x32_bf16 v[36:39], v[16:19], v[24:27], v[68:71]
	v_mfma_f32_16x16x32_bf16 v[116:119], v[20:23], v[28:31], v[36:39]
	v_mfma_f32_16x16x32_bf16 v[36:39], v[8:11], v[60:63], v[72:75]
	v_mfma_f32_16x16x32_bf16 v[108:111], v[12:15], v[244:247], v[36:39]
	v_mfma_f32_16x16x32_bf16 v[36:39], v[16:19], v[60:63], v[76:79]
	v_mfma_f32_16x16x32_bf16 v[100:103], v[20:23], v[244:247], v[36:39]
	v_mfma_f32_16x16x32_bf16 v[36:39], v[8:11], v[248:251], v[80:83]
	v_mfma_f32_16x16x32_bf16 v[76:79], v[12:15], v[144:147], v[36:39]
	v_mfma_f32_16x16x32_bf16 v[36:39], v[16:19], v[248:251], v[84:87]
	v_mfma_f32_16x16x32_bf16 v[68:71], v[20:23], v[144:147], v[36:39]
	v_mfma_f32_16x16x32_bf16 v[36:39], v[8:11], v[138:141], v[88:91]
	v_mfma_f32_16x16x32_bf16 v[44:47], v[12:15], v[172:175], v[36:39]
	v_mfma_f32_16x16x32_bf16 v[36:39], v[16:19], v[138:141], v[92:95]
	v_mfma_f32_16x16x32_bf16 v[36:39], v[20:23], v[172:175], v[36:39]
	v_mfma_f32_16x16x32_bf16 v[64:67], v[192:195], v[24:27], v[96:99]
	v_mfma_f32_16x16x32_bf16 v[24:27], v[224:227], v[24:27], v[32:35]
	v_mfma_f32_16x16x32_bf16 v[112:115], v[240:243], v[28:31], v[24:27]
	v_mfma_f32_16x16x32_bf16 v[24:27], v[192:195], v[60:63], v[196:199]
	v_mfma_f32_16x16x32_bf16 v[104:107], v[220:223], v[244:247], v[24:27]
	v_mfma_f32_16x16x32_bf16 v[24:27], v[224:227], v[60:63], v[40:43]
	v_mfma_f32_16x16x32_bf16 v[96:99], v[240:243], v[244:247], v[24:27]
	v_mfma_f32_16x16x32_bf16 v[24:27], v[192:195], v[248:251], v[200:203]
	v_mfma_f32_16x16x32_bf16 v[72:75], v[220:223], v[144:147], v[24:27]
	v_mfma_f32_16x16x32_bf16 v[24:27], v[224:227], v[248:251], v[48:51]
	v_mfma_f32_16x16x32_bf16 v[120:123], v[220:223], v[28:31], v[64:67]
	v_mfma_f32_16x16x32_bf16 v[64:67], v[240:243], v[144:147], v[24:27]
	v_mfma_f32_16x16x32_bf16 v[24:27], v[192:195], v[138:141], v[52:55]
	v_mfma_f32_16x16x32_bf16 v[40:43], v[220:223], v[172:175], v[24:27]
	v_mfma_f32_16x16x32_bf16 v[24:27], v[224:227], v[138:141], v[56:59]
	v_mfma_f32_16x16x32_bf16 v[32:35], v[240:243], v[172:175], v[24:27]
	s_barrier
	s_add_u32 s16, s44, 0x80
	s_addc_u32 s17, s45, 0
	s_nop 2
	v_mov_b32_e32 v24, v129
	s_mov_b32 m0, s96
	ds_read_b128 v[48:51], v133 offset:49152
	ds_read_b128 v[52:55], v133 offset:50176
	ds_read_b128 v[138:141], v133 offset:51200
	ds_read_b128 v[144:147], v133 offset:52224
	ds_read_b128 v[172:175], v133 offset:53248
	ds_read_b128 v[196:199], v133 offset:54272
	ds_read_b128 v[200:203], v133 offset:55296
	ds_read_b128 v[244:247], v133 offset:56320
	s_nop 0
	global_load_lds_dwordx4 v24, s[16:17]
	v_mov_b32_e32 v24, v131
	s_mov_b32 m0, s8
	s_nop 0
	global_load_lds_dwordx4 v24, s[16:17]
	s_add_u32 s16, s44, 0x10080
	s_addc_u32 s17, s45, 0
	v_mov_b32_e32 v24, v129
	s_mov_b32 m0, s9
	s_nop 0
	global_load_lds_dwordx4 v24, s[16:17]
	v_mov_b32_e32 v24, v131
	s_mov_b32 m0, s46
	s_nop 0
	global_load_lds_dwordx4 v24, s[16:17]
	v_mov_b32_e32 v24, v128
	s_mov_b32 m0, s73
	s_nop 0
	global_load_lds_dwordx4 v24, s[6:7]
	v_mov_b32_e32 v24, v130
	s_mov_b32 m0, s81
	s_nop 0
	global_load_lds_dwordx4 v24, s[6:7]
	s_waitcnt vmcnt(8)
	s_waitcnt lgkmcnt(0)
	s_barrier
	s_waitcnt lgkmcnt(0)
	v_mfma_f32_16x16x32_bf16 v[24:27], v[8:11], v[48:51], v[148:151]
	v_mfma_f32_16x16x32_bf16 v[92:95], v[12:15], v[52:55], v[24:27]
	v_mfma_f32_16x16x32_bf16 v[24:27], v[16:19], v[48:51], v[152:155]
	v_mfma_f32_16x16x32_bf16 v[88:91], v[20:23], v[52:55], v[24:27]
	v_mfma_f32_16x16x32_bf16 v[24:27], v[8:11], v[138:141], v[156:159]
	v_mfma_f32_16x16x32_bf16 v[60:63], v[12:15], v[144:147], v[24:27]
	v_mfma_f32_16x16x32_bf16 v[24:27], v[16:19], v[138:141], v[176:179]
	v_mfma_f32_16x16x32_bf16 v[56:59], v[20:23], v[144:147], v[24:27]
	v_mfma_f32_16x16x32_bf16 v[24:27], v[8:11], v[172:175], v[180:183]
	v_mfma_f32_16x16x32_bf16 v[0:3], v[8:11], v[200:203], v[0:3]
	v_mfma_f32_16x16x32_bf16 v[28:31], v[12:15], v[196:199], v[24:27]
	v_mfma_f32_16x16x32_bf16 v[24:27], v[16:19], v[172:175], v[184:187]
	v_mfma_f32_16x16x32_bf16 v[12:15], v[12:15], v[244:247], v[0:3]
	v_mfma_f32_16x16x32_bf16 v[0:3], v[16:19], v[200:203], v[4:7]
	v_mfma_f32_16x16x32_bf16 v[24:27], v[20:23], v[196:199], v[24:27]
	v_mfma_f32_16x16x32_bf16 v[8:11], v[20:23], v[244:247], v[0:3]
	v_mfma_f32_16x16x32_bf16 v[0:3], v[192:195], v[48:51], v[228:231]
	v_mfma_f32_16x16x32_bf16 v[84:87], v[220:223], v[52:55], v[0:3]
	v_mfma_f32_16x16x32_bf16 v[0:3], v[224:227], v[48:51], v[232:235]
	v_mfma_f32_16x16x32_bf16 v[80:83], v[240:243], v[52:55], v[0:3]
	v_mfma_f32_16x16x32_bf16 v[0:3], v[192:195], v[138:141], v[236:239]
	v_mfma_f32_16x16x32_bf16 v[52:55], v[220:223], v[144:147], v[0:3]
	v_mfma_f32_16x16x32_bf16 v[0:3], v[224:227], v[138:141], v[204:207]
	v_mfma_f32_16x16x32_bf16 v[48:51], v[240:243], v[144:147], v[0:3]
	v_mfma_f32_16x16x32_bf16 v[0:3], v[192:195], v[172:175], v[208:211]
	v_mfma_f32_16x16x32_bf16 v[20:23], v[220:223], v[196:199], v[0:3]
	v_mfma_f32_16x16x32_bf16 v[0:3], v[224:227], v[172:175], v[212:215]
	v_mfma_f32_16x16x32_bf16 v[16:19], v[240:243], v[196:199], v[0:3]
	v_mfma_f32_16x16x32_bf16 v[0:3], v[192:195], v[200:203], v[216:219]
	v_mfma_f32_16x16x32_bf16 v[4:7], v[220:223], v[244:247], v[0:3]
	v_mfma_f32_16x16x32_bf16 v[0:3], v[224:227], v[200:203], v[188:191]
	v_mfma_f32_16x16x32_bf16 v[0:3], v[240:243], v[244:247], v[0:3]
	s_barrier
	s_andn2_b64 vcc, exec, s[76:77]
	s_cbranch_vccnz .LBB0_558
	s_barrier

; #define PG8_BAR __builtin_amdgcn_s_barrier()
; template <class Epi, bool ALIGN_EPI = true, bool SP2 = true>
; DI void gemm_phase(LAS unsigned char* lds, const Gemm g, const StaticOrder& S, const Epi& E) {
;     ...
;     for (int i = 0; i < 2; ++i) { int R, C; stage_rc(tid * 16 + i * 8192, R, C); const int Rb = Epi::PERM ? ((R & ~31) + perm32(R & 31)) : R;
;         voffA[i] = (unsigned)(R * g.lda + C) * 2u; voffB[i] = (unsigned)(Rb * K + C) * 2u; }
;     const size_t kstep = (size_t)(BK * 2);
;     const size_t hstep = (size_t)HALF * K * 2;
;     const size_t tstep = 2 * hstep;
;     const size_t hstepA = (size_t)HALF * g.lda * 2, tstepA = 2 * hstepA;
;     const unsigned ldsw = (unsigned)wid * 1024u;
;     const int aoff = lds_byte(wr * 64 + fr, fq * 8), boff = lds_byte(wc * 32 + fr, fq * 8);
;     ...
;     Unit cur, nxt; int ui = 0;
;     if (!S.next(0, cur)) return;
;     f32x4 acc[2][2][4][2];
; #pragma unroll
;     for (int a = 0; a < 2; ++a)
; #pragma unroll
;         for (int b = 0; b < 2; ++b)
; #pragma unroll
;             for (int m = 0; m < 4; ++m)
; #pragma unroll
;                 for (int n = 0; n < 2; ++n) acc[a][b][m][n] = (f32x4){0.f, 0.f, 0.f, 0.f};
;     bf16x8 At[4][2], B0[2][2], B1[2][2];
;     const char* cA = (const char*)g.A + (size_t)cur.pm * tstepA; const char* cB = (const char*)g.Bt + (size_t)cur.pn * tstep;
;     if constexpr (SP2) {
;         PG8_STAGE(PG8_SB(0, 0), cB, voffB); PG8_STAGE(PG8_SB(0, 1), cB + hstep, voffB); PG8_STAGE(PG8_SA(0, 0), cA, voffA); PG8_STAGE(PG8_SA(0, 1), cA + hstepA, voffA);
;         if (wr == 1) PG8_BAR;
; __global__ void __launch_bounds__(NTHREADS, 2) mega(Params P) {
;     ...
;         } else {
;             const bf16_t* Bt = (const bf16_t*)(ws + W_PLE + (size_t)l * SZ_PLE);
;             pg8::Gemm g{xcur, Bt, T_, D_, D_, D_}; pg8::StaticOrder S; S.init(T_, D_, G, bid);
;             EpiPle E{xcur, BIGb, P.in[11] + (size_t)l * D_, l == 1 ? XF : (float*)nullptr, l == 0 ? XBN : (bf16_t*)nullptr};
;             pg8::gemm_phase<EpiPle>(lds, g, S, E);
.LBB0_577:
	s_andn2_b64 vcc, exec, s[0:1]
	v_readlane_b32 s0, v255, 57
	v_readlane_b32 s1, v255, 58
	s_cbranch_vccnz .LBB0_663
	v_readlane_b32 s0, v253, 14
	v_mov_b32_e32 v0, v163
	v_readlane_b32 s1, v253, 15
	s_andn2_b64 vcc, exec, s[0:1]
	v_readfirstlane_b32 s2, v0
	s_cbranch_vccnz .LBB0_662
	v_bfe_i32 v3, v0, 27, 1
	v_lshlrev_b32_e32 v1, 4, v0
	v_lshrrev_b32_e32 v3, 22, v3
	v_add_u32_e32 v3, v1, v3
	v_and_b32_e32 v3, 0xfffffc00, v3
	v_sub_u32_e32 v3, v1, v3
	v_ashrrev_i32_e32 v2, 31, v0
	v_lshrrev_b32_e32 v4, 4, v3
	v_lshrrev_b32_e32 v2, 26, v2
	v_bitop3_b32 v4, v4, v3, 32 bitop3:0x6c
	v_ashrrev_i32_e32 v3, 31, v3
	v_add_u32_e32 v2, v0, v2
	v_lshrrev_b32_e32 v3, 26, v3
	v_readlane_b32 s0, v255, 54
	v_ashrrev_i32_e32 v2, 6, v2
	v_add_u32_e32 v3, v4, v3
	v_readlane_b32 s1, v255, 55
	v_lshlrev_b32_e32 v5, 3, v2
	v_ashrrev_i32_e32 v3, 6, v3
	s_and_b64 s[0:1], s[0:1], exec
	v_and_b32_e32 v5, -16, v5
	v_mul_i32_i24_e32 v6, 64, v3
	s_cselect_b32 s0, 0x280000, 0
	v_readlane_b32 s4, v253, 26
	v_add_u32_e32 v5, v3, v5
	v_sub_u32_e32 v4, v4, v6
	s_add_u32 s42, s4, s0
	v_lshlrev_b32_e32 v2, 5, v2
	v_ashrrev_i16_sdwa v4, v166, sext(v4) dst_sel:DWORD dst_unused:UNUSED_PAD src0_sel:DWORD src1_sel:BYTE_0
	v_lshlrev_b32_e32 v6, 1, v5
	v_lshrrev_b32_e32 v7, 2, v5
	v_and_b32_e32 v3, 3, v3
	s_mov_b32 s0, 0x1fffe0
	v_and_b32_e32 v2, 32, v2
	v_bfe_i32 v4, v4, 0, 16
	v_and_b32_e32 v6, 24, v6
	v_and_b32_e32 v7, 4, v7
	v_and_or_b32 v3, v5, s0, v3
	v_or3_b32 v3, v3, v7, v6
	v_add_lshl_u32 v2, v2, v4, 1
	v_add_u32_e32 v1, 0x2000, v1
	v_lshl_add_u32 v136, v5, 11, v2
	v_lshl_add_u32 v143, v3, 11, v2
	v_ashrrev_i32_e32 v2, 31, v1
	v_lshrrev_b32_e32 v2, 22, v2
	v_add_u32_e32 v2, v1, v2
	v_ashrrev_i32_e32 v2, 10, v2
	v_mul_i32_i24_e32 v3, 0x400, v2
	v_sub_u32_e32 v1, v1, v3
	v_lshrrev_b32_e32 v3, 4, v1
	v_bitop3_b32 v1, v3, v1, 32 bitop3:0x6c
	v_ashrrev_i32_e32 v4, 31, v1
	v_lshrrev_b32_e32 v4, 26, v4
	v_lshlrev_b32_e32 v3, 3, v2
	v_add_u32_e32 v4, v1, v4
	v_readlane_b32 s5, v253, 27
	v_and_b32_e32 v3, -16, v3
	v_ashrrev_i32_e32 v5, 6, v4
	v_and_b32_e32 v4, 0xc0, v4
	s_addc_u32 s43, s5, 0
	v_add_u32_e32 v3, v5, v3
	v_sub_u32_e32 v1, v1, v4
	v_and_b32_e32 v5, 3, v5
	s_ashr_i32 s4, s2, 6
	s_ashr_i32 s3, s2, 8
	v_lshlrev_b32_e32 v2, 5, v2
	v_ashrrev_i16_sdwa v1, v166, sext(v1) dst_sel:DWORD dst_unused:UNUSED_PAD src0_sel:DWORD src1_sel:BYTE_0
	v_lshlrev_b32_e32 v4, 1, v3
	v_lshrrev_b32_e32 v6, 2, v3
	v_and_or_b32 v5, v3, s0, v5
	s_lshl_b32 s69, s4, 10
	v_readlane_b32 s0, v254, 37
	v_and_b32_e32 v2, 32, v2
	v_bfe_i32 v1, v1, 0, 16
	v_and_b32_e32 v4, 24, v4
	v_and_b32_e32 v6, 4, v6
	v_readlane_b32 s1, v254, 38
	s_add_u32 s6, s42, s0
	v_or3_b32 v4, v5, v6, v4
	v_add_lshl_u32 v1, v2, v1, 1
	s_addc_u32 s7, s43, s1
	v_lshl_add_u32 v150, v3, 11, v1
	v_lshl_add_u32 v151, v4, 11, v1
	s_mov_b64 s[0:1], s[6:7]
	s_add_i32 s92, s69, 0
	v_mov_b32_e32 v1, v143
	s_add_i32 m0, s92, 0x10000
	v_readlane_b32 s8, v254, 39
	global_load_lds_dwordx4 v1, s[0:1]
	v_mov_b32_e32 v1, v151
	s_add_i32 m0, s92, 0x12000
	v_readlane_b32 s9, v254, 40
	global_load_lds_dwordx4 v1, s[0:1]
	s_add_u32 s0, s6, 0x40000
	s_addc_u32 s1, s7, 0
	v_mov_b32_e32 v1, v143
	s_add_i32 m0, s92, 0x14000
	s_add_i32 s73, s92, 0x2000
	global_load_lds_dwordx4 v1, s[0:1]
	v_mov_b32_e32 v1, v151
	s_add_i32 m0, s92, 0x16000
	s_mov_b32 s36, s23
	global_load_lds_dwordx4 v1, s[0:1]
	v_readlane_b32 s0, v254, 41
	v_readlane_b32 s1, v254, 42
	v_mov_b32_e32 v1, v136
	s_mov_b32 m0, s92
	s_nop 2
	global_load_lds_dwordx4 v1, s[0:1]
	v_mov_b32_e32 v1, v150
	s_mov_b32 m0, s73
	s_nop 0
	global_load_lds_dwordx4 v1, s[0:1]
	s_add_i32 s0, s92, 0x4000
	v_mov_b32_e32 v1, v136
	s_mov_b32 m0, s0
	s_add_i32 s1, s92, 0x6000
	global_load_lds_dwordx4 v1, s[8:9]
	v_mov_b32_e32 v1, v150
	s_mov_b32 m0, s1
	s_cmp_eq_u32 s3, 1
	global_load_lds_dwordx4 v1, s[8:9]
	s_cselect_b64 s[74:75], -1, 0
	s_cmp_lg_u32 s3, 1
	s_cbranch_scc1 .LBB0_581
	s_barrier
	s_setprio 1

; #define PG8_LDA(dst, b, h) do { _Pragma("unroll") for (int m = 0; m < 4; ++m) _Pragma("unroll") for (int k = 0; k < 2; ++k) dst[m][k] = *(const LAS bf16x8*)(lds + PG8_SA(b, h) + aoff + m * 2048 + k * 1024); } while (0)
; #define PG8_LDB(dst, b, h) do { _Pragma("unroll") for (int n = 0; n < 2; ++n) _Pragma("unroll") for (int k = 0; k < 2; ++k) dst[n][k] = *(const LAS bf16x8*)(lds + PG8_SB(b, h) + boff + n * 2048 + k * 1024); } while (0)
; #define PG8_MMA(ai, bj, At, Bt) do { __builtin_amdgcn_s_setprio(1); _Pragma("unroll") for (int m = 0; m < 4; ++m) _Pragma("unroll") for (int n = 0; n < 2; ++n) _Pragma("unroll") for (int k = 0; k < 2; ++k) \
;         acc[ai][bj][m][n] = __builtin_amdgcn_mfma_f32_16x16x32_bf16(Bt[n][k], At[m][k], acc[ai][bj][m][n], 0, 0, 0); __builtin_amdgcn_s_setprio(0); } while (0)
; #define PG8_WAIT_V(n) asm volatile("s_waitcnt vmcnt(" #n ")" ::: "memory")
; #define PG8_WAIT_L(n) asm volatile("s_waitcnt lgkmcnt(" #n ")" ::: "memory")
; #define PG8_BAR __builtin_amdgcn_s_barrier()
; #define PG8_SCHED __builtin_amdgcn_sched_barrier(0)
; template <class Epi, bool ALIGN_EPI = true, bool SP2 = true>
; DI void gemm_phase(LAS unsigned char* lds, const Gemm g, const StaticOrder& S, const Epi& E) {
;     ...
;             PG8_LDB(B0, 0, 0); PG8_LDB(B1, 0, 1); PG8_SCHED; PG8_LDA(At, 0, 0); PG8_STAGE(PG8_SA(1, 1), a1 + hstepA, voffA);
;             PG8_WAIT_V(8); PG8_WAIT_L(0); PG8_BAR; PG8_MMA(0, 0, At, B0); PG8_MMA(0, 1, At, B1); PG8_BAR; PG8_SCHED;
;             PG8_LDA(At, 0, 1); PG8_STAGE(PG8_SB(0, 0), b2, voffB); PG8_STAGE(PG8_SB(0, 1), b2 + hstep, voffB); PG8_STAGE(PG8_SA(0, 0), a2, voffA);
;             PG8_WAIT_V(8); PG8_WAIT_L(0); PG8_BAR; PG8_MMA(1, 0, At, B0); PG8_MMA(1, 1, At, B1); PG8_BAR; PG8_SCHED;
.LBB0_591:
	s_add_u32 s6, s4, 0xfffc0080
	s_addc_u32 s7, s5, -1
	s_cmp_eq_u32 s81, 12
	s_cselect_b32 s48, s36, s6
	s_cselect_b32 s49, s19, s7
	s_cselect_b32 s40, s38, s70
	s_cselect_b32 s41, s17, s72
	s_add_u32 s6, s48, 0x80
	s_addc_u32 s7, s49, 0
	s_add_i32 s96, 0, 0x10000
	s_add_i32 s97, 0, 0x14000
	v_add_u32_e32 v144, s96, v152
	v_add_u32_e32 v148, s97, v152
	ds_read_b128 v[128:131], v144
	ds_read_b128 v[132:135], v144 offset:1024
	ds_read_b128 v[138:141], v144 offset:2048
	ds_read_b128 v[144:147], v144 offset:3072
	ds_read_b128 v[154:157], v148
	ds_read_b128 v[158:161], v148 offset:1024
	ds_read_b128 v[172:175], v148 offset:2048
	ds_read_b128 v[176:179], v148 offset:3072
	s_mov_b64 s[94:95], s[4:5]
	v_mov_b32_e32 v148, v136
	ds_read_b128 v[180:183], v153
	ds_read_b128 v[184:187], v153 offset:1024
	ds_read_b128 v[188:191], v153 offset:2048
	ds_read_b128 v[192:195], v153 offset:3072
	ds_read_b128 v[196:199], v153 offset:4096
	ds_read_b128 v[200:203], v153 offset:5120
	ds_read_b128 v[204:207], v153 offset:6144
	ds_read_b128 v[208:211], v153 offset:7168
	s_add_i32 m0, s92, 0xc000
	s_nop 0
	global_load_lds_dwordx4 v148, s[94:95]
	v_mov_b32_e32 v148, v150
	s_add_i32 m0, s92, 0xe000
	s_nop 0
	global_load_lds_dwordx4 v148, s[94:95]
	s_waitcnt vmcnt(8)
	s_waitcnt lgkmcnt(0)
	s_barrier
	s_waitcnt lgkmcnt(0)
	v_mfma_f32_16x16x32_bf16 v[124:127], v[128:131], v[180:183], v[124:127]
	v_mfma_f32_16x16x32_bf16 v[120:123], v[138:141], v[180:183], v[120:123]
	v_mfma_f32_16x16x32_bf16 v[108:111], v[128:131], v[188:191], v[108:111]
	v_mfma_f32_16x16x32_bf16 v[104:107], v[138:141], v[188:191], v[104:107]
	v_mfma_f32_16x16x32_bf16 v[92:95], v[128:131], v[196:199], v[92:95]
	v_mfma_f32_16x16x32_bf16 v[88:91], v[138:141], v[196:199], v[88:91]
	v_mfma_f32_16x16x32_bf16 v[76:79], v[128:131], v[204:207], v[76:79]
	v_mfma_f32_16x16x32_bf16 v[72:75], v[138:141], v[204:207], v[72:75]
	v_mfma_f32_16x16x32_bf16 v[124:127], v[132:135], v[184:187], v[124:127]
	v_mfma_f32_16x16x32_bf16 v[120:123], v[144:147], v[184:187], v[120:123]
	v_mfma_f32_16x16x32_bf16 v[108:111], v[132:135], v[192:195], v[108:111]
	v_mfma_f32_16x16x32_bf16 v[104:107], v[144:147], v[192:195], v[104:107]
	v_mfma_f32_16x16x32_bf16 v[92:95], v[132:135], v[200:203], v[92:95]
	v_mfma_f32_16x16x32_bf16 v[88:91], v[144:147], v[200:203], v[88:91]
	v_mfma_f32_16x16x32_bf16 v[76:79], v[132:135], v[208:211], v[76:79]
	v_mfma_f32_16x16x32_bf16 v[72:75], v[144:147], v[208:211], v[72:75]
	v_mfma_f32_16x16x32_bf16 v[116:119], v[154:157], v[180:183], v[116:119]
	v_mfma_f32_16x16x32_bf16 v[112:115], v[172:175], v[180:183], v[112:115]
	v_mfma_f32_16x16x32_bf16 v[100:103], v[154:157], v[188:191], v[100:103]
	v_mfma_f32_16x16x32_bf16 v[96:99], v[172:175], v[188:191], v[96:99]
	v_mfma_f32_16x16x32_bf16 v[84:87], v[154:157], v[196:199], v[84:87]
	v_mfma_f32_16x16x32_bf16 v[80:83], v[172:175], v[196:199], v[80:83]
	v_mfma_f32_16x16x32_bf16 v[68:71], v[154:157], v[204:207], v[68:71]
	v_mfma_f32_16x16x32_bf16 v[64:67], v[172:175], v[204:207], v[64:67]
	v_mfma_f32_16x16x32_bf16 v[116:119], v[158:161], v[184:187], v[116:119]
	v_mfma_f32_16x16x32_bf16 v[112:115], v[176:179], v[184:187], v[112:115]
	v_mfma_f32_16x16x32_bf16 v[100:103], v[158:161], v[192:195], v[100:103]
	v_mfma_f32_16x16x32_bf16 v[96:99], v[176:179], v[192:195], v[96:99]
	v_mfma_f32_16x16x32_bf16 v[84:87], v[158:161], v[200:203], v[84:87]
	v_mfma_f32_16x16x32_bf16 v[80:83], v[176:179], v[200:203], v[80:83]
	v_mfma_f32_16x16x32_bf16 v[68:71], v[158:161], v[208:211], v[68:71]
	v_mfma_f32_16x16x32_bf16 v[64:67], v[176:179], v[208:211], v[64:67]
	s_barrier
	s_mov_b64 s[94:95], s[40:41]
	v_mov_b32_e32 v148, v143
	s_add_i32 s96, s96, s69
	ds_read_b128 v[180:183], v153 offset:16384
	ds_read_b128 v[184:187], v153 offset:17408
	ds_read_b128 v[188:191], v153 offset:18432
	ds_read_b128 v[192:195], v153 offset:19456
	ds_read_b128 v[196:199], v153 offset:20480
	ds_read_b128 v[200:203], v153 offset:21504
	ds_read_b128 v[204:207], v153 offset:22528
	ds_read_b128 v[208:211], v153 offset:23552
	s_mov_b32 m0, s96
	s_nop 0
	global_load_lds_dwordx4 v148, s[94:95]
	v_mov_b32_e32 v148, v151
	s_add_i32 m0, s96, 0x2000
	s_nop 0
	global_load_lds_dwordx4 v148, s[94:95]
	s_add_u32 s94, s40, 0x40000
	s_addc_u32 s95, s41, 0
	v_mov_b32_e32 v148, v143
	s_add_i32 s96, s97, s69
	s_mov_b32 m0, s96
	s_nop 0
	global_load_lds_dwordx4 v148, s[94:95]
	v_mov_b32_e32 v148, v151
	s_add_i32 m0, s96, 0x2000
	s_nop 0
	global_load_lds_dwordx4 v148, s[94:95]
	s_mov_b64 s[94:95], s[48:49]
	v_mov_b32_e32 v148, v136
	s_mov_b32 m0, s92
	s_nop 0
	global_load_lds_dwordx4 v148, s[94:95]
	v_mov_b32_e32 v148, v150
	s_mov_b32 m0, s73
	s_nop 0
	global_load_lds_dwordx4 v148, s[94:95]
	s_waitcnt vmcnt(8)
	s_waitcnt lgkmcnt(0)
	s_barrier
; #define PG8_LDA(dst, b, h) do { _Pragma("unroll") for (int m = 0; m < 4; ++m) _Pragma("unroll") for (int k = 0; k < 2; ++k) dst[m][k] = *(const LAS bf16x8*)(lds + PG8_SA(b, h) + aoff + m * 2048 + k * 1024); } while (0)
; #define PG8_LDB(dst, b, h) do { _Pragma("unroll") for (int n = 0; n < 2; ++n) _Pragma("unroll") for (int k = 0; k < 2; ++k) dst[n][k] = *(const LAS bf16x8*)(lds + PG8_SB(b, h) + boff + n * 2048 + k * 1024); } while (0)
; #define PG8_MMA(ai, bj, At, Bt) do { __builtin_amdgcn_s_setprio(1); _Pragma("unroll") for (int m = 0; m < 4; ++m) _Pragma("unroll") for (int n = 0; n < 2; ++n) _Pragma("unroll") for (int k = 0; k < 2; ++k) \
;         acc[ai][bj][m][n] = __builtin_amdgcn_mfma_f32_16x16x32_bf16(Bt[n][k], At[m][k], acc[ai][bj][m][n], 0, 0, 0); __builtin_amdgcn_s_setprio(0); } while (0)
; #define PG8_WAIT_V(n) asm volatile("s_waitcnt vmcnt(" #n ")" ::: "memory")
; #define PG8_WAIT_L(n) asm volatile("s_waitcnt lgkmcnt(" #n ")" ::: "memory")
; #define PG8_BAR __builtin_amdgcn_s_barrier()
; #define PG8_SCHED __builtin_amdgcn_sched_barrier(0)
; template <class Epi, bool ALIGN_EPI = true, bool SP2 = true>
; DI void gemm_phase(LAS unsigned char* lds, const Gemm g, const StaticOrder& S, const Epi& E) {
;     ...
;             PG8_WAIT_V(8); PG8_WAIT_L(0); PG8_BAR; PG8_MMA(0, 0, At, B0); PG8_MMA(0, 1, At, B1); PG8_BAR; PG8_SCHED;
;             PG8_LDA(At, 0, 1); PG8_STAGE(PG8_SB(0, 0), b2, voffB); PG8_STAGE(PG8_SB(0, 1), b2 + hstep, voffB); PG8_STAGE(PG8_SA(0, 0), a2, voffA);
;             PG8_WAIT_V(8); PG8_WAIT_L(0); PG8_BAR; PG8_MMA(1, 0, At, B0); PG8_MMA(1, 1, At, B1); PG8_BAR; PG8_SCHED;
;             PG8_LDB(B0, 1, 0); PG8_LDB(B1, 1, 1); PG8_SCHED; PG8_LDA(At, 1, 0); PG8_STAGE(PG8_SA(0, 1), a2 + hstepA, voffA);
;             PG8_WAIT_V(8); PG8_WAIT_L(0); PG8_BAR; PG8_MMA(0, 0, At, B0); PG8_MMA(0, 1, At, B1); PG8_BAR; PG8_SCHED;
	s_waitcnt lgkmcnt(0)
	v_mfma_f32_16x16x32_bf16 v[60:63], v[128:131], v[180:183], v[60:63]
	v_mfma_f32_16x16x32_bf16 v[56:59], v[138:141], v[180:183], v[56:59]
	v_mfma_f32_16x16x32_bf16 v[44:47], v[128:131], v[188:191], v[44:47]
	v_mfma_f32_16x16x32_bf16 v[40:43], v[138:141], v[188:191], v[40:43]
	v_mfma_f32_16x16x32_bf16 v[28:31], v[128:131], v[196:199], v[28:31]
	v_mfma_f32_16x16x32_bf16 v[24:27], v[138:141], v[196:199], v[24:27]
	v_mfma_f32_16x16x32_bf16 v[12:15], v[128:131], v[204:207], v[12:15]
	v_mfma_f32_16x16x32_bf16 v[8:11], v[138:141], v[204:207], v[8:11]
	v_mfma_f32_16x16x32_bf16 v[60:63], v[132:135], v[184:187], v[60:63]
	v_mfma_f32_16x16x32_bf16 v[56:59], v[144:147], v[184:187], v[56:59]
	v_mfma_f32_16x16x32_bf16 v[44:47], v[132:135], v[192:195], v[44:47]
	v_mfma_f32_16x16x32_bf16 v[40:43], v[144:147], v[192:195], v[40:43]
	v_mfma_f32_16x16x32_bf16 v[28:31], v[132:135], v[200:203], v[28:31]
	v_mfma_f32_16x16x32_bf16 v[24:27], v[144:147], v[200:203], v[24:27]
	v_mfma_f32_16x16x32_bf16 v[12:15], v[132:135], v[208:211], v[12:15]
	v_mfma_f32_16x16x32_bf16 v[8:11], v[144:147], v[208:211], v[8:11]
	v_mfma_f32_16x16x32_bf16 v[52:55], v[154:157], v[180:183], v[52:55]
	v_mfma_f32_16x16x32_bf16 v[48:51], v[172:175], v[180:183], v[48:51]
	v_mfma_f32_16x16x32_bf16 v[36:39], v[154:157], v[188:191], v[36:39]
	v_mfma_f32_16x16x32_bf16 v[32:35], v[172:175], v[188:191], v[32:35]
	v_mfma_f32_16x16x32_bf16 v[20:23], v[154:157], v[196:199], v[20:23]
	v_mfma_f32_16x16x32_bf16 v[16:19], v[172:175], v[196:199], v[16:19]
	v_mfma_f32_16x16x32_bf16 v[4:7], v[154:157], v[204:207], v[4:7]
	v_mfma_f32_16x16x32_bf16 v[0:3], v[172:175], v[204:207], v[0:3]
	v_mfma_f32_16x16x32_bf16 v[52:55], v[158:161], v[184:187], v[52:55]
	v_mfma_f32_16x16x32_bf16 v[48:51], v[176:179], v[184:187], v[48:51]
	v_mfma_f32_16x16x32_bf16 v[36:39], v[158:161], v[192:195], v[36:39]
	v_mfma_f32_16x16x32_bf16 v[32:35], v[176:179], v[192:195], v[32:35]
	v_mfma_f32_16x16x32_bf16 v[20:23], v[158:161], v[200:203], v[20:23]
	v_mfma_f32_16x16x32_bf16 v[16:19], v[176:179], v[200:203], v[16:19]
	v_mfma_f32_16x16x32_bf16 v[4:7], v[158:161], v[208:211], v[4:7]
	v_mfma_f32_16x16x32_bf16 v[0:3], v[176:179], v[208:211], v[0:3]
	s_barrier
	s_add_i32 s94, 0, 0x18000
	s_add_i32 s95, 0, 0x1c000
	v_add_u32_e32 v144, s94, v152
	v_add_u32_e32 v148, s95, v152
	ds_read_b128 v[128:131], v144
	ds_read_b128 v[132:135], v144 offset:1024
	ds_read_b128 v[138:141], v144 offset:2048
	ds_read_b128 v[144:147], v144 offset:3072
	ds_read_b128 v[154:157], v148
	ds_read_b128 v[158:161], v148 offset:1024
	ds_read_b128 v[172:175], v148 offset:2048
	ds_read_b128 v[176:179], v148 offset:3072
	s_add_u32 s48, s48, 0x40000
	s_addc_u32 s49, s49, 0
	v_mov_b32_e32 v148, v136
	s_mov_b32 m0, s0
	ds_read_b128 v[180:183], v153 offset:32768
	ds_read_b128 v[184:187], v153 offset:33792
	ds_read_b128 v[188:191], v153 offset:34816
	ds_read_b128 v[192:195], v153 offset:35840
	ds_read_b128 v[196:199], v153 offset:36864
	ds_read_b128 v[200:203], v153 offset:37888
	ds_read_b128 v[204:207], v153 offset:38912
	ds_read_b128 v[208:211], v153 offset:39936
	s_nop 0
	global_load_lds_dwordx4 v148, s[48:49]
	v_mov_b32_e32 v148, v150
	s_mov_b32 m0, s1
	s_nop 0
	global_load_lds_dwordx4 v148, s[48:49]
	s_waitcnt vmcnt(8)
	s_waitcnt lgkmcnt(0)
	s_barrier
	s_waitcnt lgkmcnt(0)
	v_mfma_f32_16x16x32_bf16 v[124:127], v[128:131], v[180:183], v[124:127]
	v_mfma_f32_16x16x32_bf16 v[120:123], v[138:141], v[180:183], v[120:123]
	v_mfma_f32_16x16x32_bf16 v[108:111], v[128:131], v[188:191], v[108:111]
	v_mfma_f32_16x16x32_bf16 v[104:107], v[138:141], v[188:191], v[104:107]
	v_mfma_f32_16x16x32_bf16 v[92:95], v[128:131], v[196:199], v[92:95]
	v_mfma_f32_16x16x32_bf16 v[88:91], v[138:141], v[196:199], v[88:91]
	v_mfma_f32_16x16x32_bf16 v[76:79], v[128:131], v[204:207], v[76:79]
	v_mfma_f32_16x16x32_bf16 v[72:75], v[138:141], v[204:207], v[72:75]
	v_mfma_f32_16x16x32_bf16 v[124:127], v[132:135], v[184:187], v[124:127]
	v_mfma_f32_16x16x32_bf16 v[120:123], v[144:147], v[184:187], v[120:123]
	v_mfma_f32_16x16x32_bf16 v[108:111], v[132:135], v[192:195], v[108:111]
	v_mfma_f32_16x16x32_bf16 v[104:107], v[144:147], v[192:195], v[104:107]
	v_mfma_f32_16x16x32_bf16 v[92:95], v[132:135], v[200:203], v[92:95]
	v_mfma_f32_16x16x32_bf16 v[88:91], v[144:147], v[200:203], v[88:91]
	v_mfma_f32_16x16x32_bf16 v[76:79], v[132:135], v[208:211], v[76:79]
	v_mfma_f32_16x16x32_bf16 v[72:75], v[144:147], v[208:211], v[72:75]
	v_mfma_f32_16x16x32_bf16 v[116:119], v[154:157], v[180:183], v[116:119]
	v_mfma_f32_16x16x32_bf16 v[112:115], v[172:175], v[180:183], v[112:115]
	v_mfma_f32_16x16x32_bf16 v[100:103], v[154:157], v[188:191], v[100:103]
	v_mfma_f32_16x16x32_bf16 v[96:99], v[172:175], v[188:191], v[96:99]
	v_mfma_f32_16x16x32_bf16 v[84:87], v[154:157], v[196:199], v[84:87]
	v_mfma_f32_16x16x32_bf16 v[80:83], v[172:175], v[196:199], v[80:83]
	v_mfma_f32_16x16x32_bf16 v[68:71], v[154:157], v[204:207], v[68:71]
	v_mfma_f32_16x16x32_bf16 v[64:67], v[172:175], v[204:207], v[64:67]
	v_mfma_f32_16x16x32_bf16 v[116:119], v[158:161], v[184:187], v[116:119]
	v_mfma_f32_16x16x32_bf16 v[112:115], v[176:179], v[184:187], v[112:115]
	v_mfma_f32_16x16x32_bf16 v[100:103], v[158:161], v[192:195], v[100:103]
	v_mfma_f32_16x16x32_bf16 v[96:99], v[176:179], v[192:195], v[96:99]
	v_mfma_f32_16x16x32_bf16 v[84:87], v[158:161], v[200:203], v[84:87]
	v_mfma_f32_16x16x32_bf16 v[80:83], v[176:179], v[200:203], v[80:83]
	v_mfma_f32_16x16x32_bf16 v[68:71], v[158:161], v[208:211], v[68:71]
	v_mfma_f32_16x16x32_bf16 v[64:67], v[176:179], v[208:211], v[64:67]
	s_barrier
; #define PG8_LDA(dst, b, h) do { _Pragma("unroll") for (int m = 0; m < 4; ++m) _Pragma("unroll") for (int k = 0; k < 2; ++k) dst[m][k] = *(const LAS bf16x8*)(lds + PG8_SA(b, h) + aoff + m * 2048 + k * 1024); } while (0)
; #define PG8_LDB(dst, b, h) do { _Pragma("unroll") for (int n = 0; n < 2; ++n) _Pragma("unroll") for (int k = 0; k < 2; ++k) dst[n][k] = *(const LAS bf16x8*)(lds + PG8_SB(b, h) + boff + n * 2048 + k * 1024); } while (0)
; #define PG8_MMA(ai, bj, At, Bt) do { __builtin_amdgcn_s_setprio(1); _Pragma("unroll") for (int m = 0; m < 4; ++m) _Pragma("unroll") for (int n = 0; n < 2; ++n) _Pragma("unroll") for (int k = 0; k < 2; ++k) \
;         acc[ai][bj][m][n] = __builtin_amdgcn_mfma_f32_16x16x32_bf16(Bt[n][k], At[m][k], acc[ai][bj][m][n], 0, 0, 0); __builtin_amdgcn_s_setprio(0); } while (0)
; #define PG8_WAIT_V(n) asm volatile("s_waitcnt vmcnt(" #n ")" ::: "memory")
; #define PG8_WAIT_L(n) asm volatile("s_waitcnt lgkmcnt(" #n ")" ::: "memory")
; #define PG8_BAR __builtin_amdgcn_s_barrier()
; #define PG8_SCHED __builtin_amdgcn_sched_barrier(0)
; template <class Epi, bool ALIGN_EPI = true, bool SP2 = true>
; DI void gemm_phase(LAS unsigned char* lds, const Gemm g, const StaticOrder& S, const Epi& E) {
;     ...
;             PG8_LDB(B0, 1, 0); PG8_LDB(B1, 1, 1); PG8_SCHED; PG8_LDA(At, 1, 0); PG8_STAGE(PG8_SA(0, 1), a2 + hstepA, voffA);
;             PG8_WAIT_V(8); PG8_WAIT_L(0); PG8_BAR; PG8_MMA(0, 0, At, B0); PG8_MMA(0, 1, At, B1); PG8_BAR; PG8_SCHED;
;             PG8_LDA(At, 1, 1); PG8_STAGE(PG8_SB(1, 0), b3, voffB); PG8_STAGE(PG8_SB(1, 1), b3 + hstep, voffB); PG8_STAGE(PG8_SA(1, 0), a3, voffA);
;             PG8_WAIT_V(8); PG8_WAIT_L(0); PG8_BAR; PG8_MMA(1, 0, At, B0); PG8_MMA(1, 1, At, B1); PG8_BAR; PG8_SCHED;
	s_add_u32 s48, s40, 0x80
	s_addc_u32 s49, s41, 0
	v_mov_b32_e32 v148, v143
	s_add_i32 s94, s94, s69
	ds_read_b128 v[180:183], v153 offset:49152
	ds_read_b128 v[184:187], v153 offset:50176
	ds_read_b128 v[188:191], v153 offset:51200
	ds_read_b128 v[192:195], v153 offset:52224
	ds_read_b128 v[196:199], v153 offset:53248
	ds_read_b128 v[200:203], v153 offset:54272
	ds_read_b128 v[204:207], v153 offset:55296
	ds_read_b128 v[208:211], v153 offset:56320
	s_mov_b32 m0, s94
	s_nop 0
	global_load_lds_dwordx4 v148, s[48:49]
	v_mov_b32_e32 v148, v151
	s_add_i32 m0, s94, 0x2000
	s_add_u32 s40, s40, 0x40080
	global_load_lds_dwordx4 v148, s[48:49]
	s_addc_u32 s41, s41, 0
	v_mov_b32_e32 v148, v143
	s_add_i32 s48, s95, s69
	s_mov_b32 m0, s48
	s_nop 0
	global_load_lds_dwordx4 v148, s[40:41]
	v_mov_b32_e32 v148, v151
	s_add_i32 m0, s48, 0x2000
	s_nop 0
	global_load_lds_dwordx4 v148, s[40:41]
	v_mov_b32_e32 v148, v136
	s_mov_b32 m0, s55
	s_nop 0
	global_load_lds_dwordx4 v148, s[6:7]
	v_mov_b32_e32 v148, v150
	s_mov_b32 m0, s83
	s_nop 0
	global_load_lds_dwordx4 v148, s[6:7]
	s_waitcnt vmcnt(8)
	s_waitcnt lgkmcnt(0)
	s_barrier
	s_waitcnt lgkmcnt(0)
	v_mfma_f32_16x16x32_bf16 v[60:63], v[128:131], v[180:183], v[60:63]
	v_mfma_f32_16x16x32_bf16 v[56:59], v[138:141], v[180:183], v[56:59]
	v_mfma_f32_16x16x32_bf16 v[44:47], v[128:131], v[188:191], v[44:47]
	v_mfma_f32_16x16x32_bf16 v[40:43], v[138:141], v[188:191], v[40:43]
	v_mfma_f32_16x16x32_bf16 v[28:31], v[128:131], v[196:199], v[28:31]
	v_mfma_f32_16x16x32_bf16 v[24:27], v[138:141], v[196:199], v[24:27]
	v_mfma_f32_16x16x32_bf16 v[12:15], v[128:131], v[204:207], v[12:15]
	v_mfma_f32_16x16x32_bf16 v[8:11], v[138:141], v[204:207], v[8:11]
	v_mfma_f32_16x16x32_bf16 v[60:63], v[132:135], v[184:187], v[60:63]
	v_mfma_f32_16x16x32_bf16 v[56:59], v[144:147], v[184:187], v[56:59]
	v_mfma_f32_16x16x32_bf16 v[44:47], v[132:135], v[192:195], v[44:47]
	v_mfma_f32_16x16x32_bf16 v[40:43], v[144:147], v[192:195], v[40:43]
	v_mfma_f32_16x16x32_bf16 v[28:31], v[132:135], v[200:203], v[28:31]
	v_mfma_f32_16x16x32_bf16 v[24:27], v[144:147], v[200:203], v[24:27]
	v_mfma_f32_16x16x32_bf16 v[12:15], v[132:135], v[208:211], v[12:15]
	v_mfma_f32_16x16x32_bf16 v[8:11], v[144:147], v[208:211], v[8:11]
	v_mfma_f32_16x16x32_bf16 v[52:55], v[154:157], v[180:183], v[52:55]
	v_mfma_f32_16x16x32_bf16 v[48:51], v[172:175], v[180:183], v[48:51]
	v_mfma_f32_16x16x32_bf16 v[36:39], v[154:157], v[188:191], v[36:39]
	v_mfma_f32_16x16x32_bf16 v[32:35], v[172:175], v[188:191], v[32:35]
	v_mfma_f32_16x16x32_bf16 v[20:23], v[154:157], v[196:199], v[20:23]
	v_mfma_f32_16x16x32_bf16 v[16:19], v[172:175], v[196:199], v[16:19]
	v_mfma_f32_16x16x32_bf16 v[4:7], v[154:157], v[204:207], v[4:7]
	v_mfma_f32_16x16x32_bf16 v[0:3], v[172:175], v[204:207], v[0:3]
	v_mfma_f32_16x16x32_bf16 v[52:55], v[158:161], v[184:187], v[52:55]
	v_mfma_f32_16x16x32_bf16 v[48:51], v[176:179], v[184:187], v[48:51]
	v_mfma_f32_16x16x32_bf16 v[36:39], v[158:161], v[192:195], v[36:39]
	v_mfma_f32_16x16x32_bf16 v[32:35], v[176:179], v[192:195], v[32:35]
	v_mfma_f32_16x16x32_bf16 v[20:23], v[158:161], v[200:203], v[20:23]
	v_mfma_f32_16x16x32_bf16 v[16:19], v[176:179], v[200:203], v[16:19]
	v_mfma_f32_16x16x32_bf16 v[4:7], v[158:161], v[208:211], v[4:7]
	v_mfma_f32_16x16x32_bf16 v[0:3], v[176:179], v[208:211], v[0:3]
	s_barrier
	s_add_i32 s81, s81, 2
	s_add_u32 s4, s4, 0x100
	s_addc_u32 s5, s5, 0
	s_add_u32 s70, s70, 0x100
	s_addc_u32 s72, s72, 0
	s_cmp_gt_u32 s81, 13
	s_cbranch_scc0 .LBB0_591
	s_and_b64 vcc, exec, s[12:13]
	s_cbranch_vccz .LBB0_594
	s_barrier

; #define PG8_BAR __builtin_amdgcn_s_barrier()
; template <class Epi, bool ALIGN_EPI = true, bool SP2 = true>
; DI void gemm_phase(LAS unsigned char* lds, const Gemm g, const StaticOrder& S, const Epi& E) {
;     ...
;     for (int i = 0; i < 2; ++i) { int R, C; stage_rc(tid * 16 + i * 8192, R, C); const int Rb = Epi::PERM ? ((R & ~31) + perm32(R & 31)) : R;
;         voffA[i] = (unsigned)(R * g.lda + C) * 2u; voffB[i] = (unsigned)(Rb * K + C) * 2u; }
;     const size_t kstep = (size_t)(BK * 2);
;     const size_t hstep = (size_t)HALF * K * 2;
;     const size_t tstep = 2 * hstep;
;     const size_t hstepA = (size_t)HALF * g.lda * 2, tstepA = 2 * hstepA;
;     const unsigned ldsw = (unsigned)wid * 1024u;
;     const int aoff = lds_byte(wr * 64 + fr, fq * 8), boff = lds_byte(wc * 32 + fr, fq * 8);
;     ...
;     Unit cur, nxt; int ui = 0;
;     if (!S.next(0, cur)) return;
;     f32x4 acc[2][2][4][2];
; #pragma unroll
;     for (int a = 0; a < 2; ++a)
; #pragma unroll
;         for (int b = 0; b < 2; ++b)
; #pragma unroll
;             for (int m = 0; m < 4; ++m)
; #pragma unroll
;                 for (int n = 0; n < 2; ++n) acc[a][b][m][n] = (f32x4){0.f, 0.f, 0.f, 0.f};
;     bf16x8 At[4][2], B0[2][2], B1[2][2];
;     const char* cA = (const char*)g.A + (size_t)cur.pm * tstepA; const char* cB = (const char*)g.Bt + (size_t)cur.pn * tstep;
;     if constexpr (SP2) {
;         PG8_STAGE(PG8_SB(0, 0), cB, voffB); PG8_STAGE(PG8_SB(0, 1), cB + hstep, voffB); PG8_STAGE(PG8_SA(0, 0), cA, voffA); PG8_STAGE(PG8_SA(0, 1), cA + hstepA, voffA);
;         if (wr == 1) PG8_BAR;
; __global__ void __launch_bounds__(NTHREADS, 2) mega(Params P) {
;     ...
;         } else if (s == 1 || s == 8 || s == 5) {
;             const bf16_t* A; const bf16_t* Bt; int K, lda; float scale;
;             if (s == 5) { A = (l == 0) ? YC0 : (BIGb + 3072); lda = (l == 0) ? D_ : PJ1; Bt = (const bf16_t*)(ws + (l == 0 ? W_AB_OUT : W_C_OUT)); K = D_; scale = 1.0f; }
;             else { A = BIGb; lda = FF_; Bt = (const bf16_t*)(ws + W_FFN + (size_t)(l * 2 + (s == 8)) * (SZ_UP + SZ_DN) + SZ_UP); K = FF_; scale = 0.5f; }
;             const float* res = (l == 0 && s == 1) ? P.in[0] : XF;
;             const bf16_t* resb = (s == 8 || s == 5) ? xcur : ((s == 1 && l == 1) ? XBN : (const bf16_t*)nullptr);
;             bf16_t* vout = (s == 5 || (s == 1 && l == 1)) ? (bf16_t*)XF : VB;
.LBB0_671:
	v_readlane_b32 s8, v253, 14
	v_mov_b32_e32 v0, v163
	v_readlane_b32 s9, v253, 15
	s_andn2_b64 vcc, exec, s[8:9]
	v_readfirstlane_b32 s34, v0
	s_cbranch_vccnz .LBB0_760
	v_bfe_i32 v3, v0, 27, 1
	v_lshlrev_b32_e32 v1, 4, v0
	v_lshrrev_b32_e32 v3, 22, v3
	v_add_u32_e32 v3, v1, v3
	v_and_b32_e32 v3, 0xfffffc00, v3
	v_sub_u32_e32 v3, v1, v3
	v_lshrrev_b32_e32 v4, 4, v3
	v_ashrrev_i32_e32 v2, 31, v0
	v_bitop3_b32 v4, v4, v3, 32 bitop3:0x6c
	v_ashrrev_i32_e32 v3, 31, v3
	v_lshrrev_b32_e32 v2, 26, v2
	v_lshrrev_b32_e32 v3, 26, v3
	v_add_u32_e32 v2, v0, v2
	v_add_u32_e32 v3, v4, v3
	v_ashrrev_i32_e32 v2, 6, v2
	v_ashrrev_i32_e32 v3, 6, v3
	v_lshlrev_b32_e32 v5, 3, v2
	v_mul_i32_i24_e32 v6, 64, v3
	v_and_b32_e32 v5, -16, v5
	v_lshlrev_b32_e32 v2, 5, v2
	v_sub_u32_e32 v4, v4, v6
	v_add_u32_e32 v5, v3, v5
	v_and_b32_e32 v2, 32, v2
	v_ashrrev_i16_sdwa v4, v166, sext(v4) dst_sel:DWORD dst_unused:UNUSED_PAD src0_sel:DWORD src1_sel:BYTE_0
	v_add_u32_sdwa v2, v2, sext(v4) dst_sel:DWORD dst_unused:UNUSED_PAD src0_sel:DWORD src1_sel:WORD_0
	v_lshlrev_b32_e32 v4, 1, v5
	v_lshrrev_b32_e32 v6, 2, v5
	v_and_b32_e32 v3, 3, v3
	s_mov_b32 s5, 0x7fffffe0
	v_and_b32_e32 v4, 24, v4
	v_and_b32_e32 v6, 4, v6
	v_and_or_b32 v3, v5, s5, v3
	v_or3_b32 v3, v3, v6, v4
	v_mul_lo_u32 v4, v5, s4
	v_mul_lo_u32 v3, v3, s12
	v_add_u32_e32 v1, 0x2000, v1
	v_add_lshl_u32 v136, v2, v4, 1
	v_add_lshl_u32 v143, v3, v2, 1
	v_ashrrev_i32_e32 v2, 31, v1
	v_lshrrev_b32_e32 v2, 22, v2
	v_add_u32_e32 v2, v1, v2
	v_ashrrev_i32_e32 v2, 10, v2
	v_mul_i32_i24_e32 v3, 0x400, v2
	v_sub_u32_e32 v1, v1, v3
	v_lshrrev_b32_e32 v3, 4, v1
	v_bitop3_b32 v1, v3, v1, 32 bitop3:0x6c
	v_ashrrev_i32_e32 v4, 31, v1
	v_lshrrev_b32_e32 v4, 26, v4
	v_add_u32_e32 v4, v1, v4
	v_lshlrev_b32_e32 v3, 3, v2
	v_ashrrev_i32_e32 v5, 6, v4
	v_and_b32_e32 v4, 0xc0, v4
	v_and_b32_e32 v3, -16, v3
	v_lshlrev_b32_e32 v2, 5, v2
	v_sub_u32_e32 v1, v1, v4
	v_add_u32_e32 v3, v5, v3
	v_and_b32_e32 v2, 32, v2
	v_ashrrev_i16_sdwa v1, v166, sext(v1) dst_sel:DWORD dst_unused:UNUSED_PAD src0_sel:DWORD src1_sel:BYTE_0
	v_and_b32_e32 v5, 3, v5
	v_add_u32_sdwa v1, v2, sext(v1) dst_sel:DWORD dst_unused:UNUSED_PAD src0_sel:DWORD src1_sel:WORD_0
	v_lshlrev_b32_e32 v2, 1, v3
	v_lshrrev_b32_e32 v4, 2, v3
	v_and_or_b32 v5, v3, s5, v5
	v_mul_lo_u32 v3, v3, s4
	s_lshl_b32 s69, s4, 8
	s_lshl_b32 s76, s4, 9
	v_readlane_b32 s4, v254, 33
	v_readlane_b32 s5, v254, 34
	s_mul_hi_i32 s17, s76, s4
	s_mul_i32 s26, s76, s4
	v_readlane_b32 s4, v254, 35
	s_ashr_i32 s13, s34, 6
	s_lshl_b32 s22, s12, 9
	v_readlane_b32 s5, v254, 36
	v_and_b32_e32 v2, 24, v2
	v_and_b32_e32 v4, 4, v4
	s_ashr_i32 s16, s34, 8
	s_lshl_b32 s54, s12, 8
	s_lshl_b32 s83, s13, 10
	s_mul_hi_i32 s5, s22, s4
	s_mul_i32 s4, s22, s4
	v_or3_b32 v2, v5, v4, v2
	s_add_u32 s4, s6, s4
	v_mul_lo_u32 v2, v2, s12
	s_addc_u32 s5, s7, s5
	s_add_i32 s86, s83, 0
	v_add_lshl_u32 v176, v1, v3, 1
	v_add_lshl_u32 v177, v2, v1, 1
	s_mov_b64 s[14:15], s[4:5]
	s_add_i32 m0, s86, 0x10000
	v_mov_b32_e32 v1, v143
	s_nop 0
	global_load_lds_dwordx4 v1, s[14:15]
	s_add_i32 m0, s86, 0x12000
	v_mov_b32_e32 v1, v177
	s_add_u32 s18, s4, s54
	s_addc_u32 s19, s5, 0
	global_load_lds_dwordx4 v1, s[14:15]
	s_mov_b64 s[14:15], s[18:19]
	s_add_i32 m0, s86, 0x14000
	v_mov_b32_e32 v1, v143
	s_nop 0
	global_load_lds_dwordx4 v1, s[14:15]
	s_add_i32 m0, s86, 0x16000
	v_mov_b32_e32 v1, v177
	s_add_u32 s40, s74, s26
	s_addc_u32 s41, s75, s17
	global_load_lds_dwordx4 v1, s[14:15]
	s_mov_b64 s[14:15], s[40:41]
	v_mov_b32_e32 v1, v136
	s_mov_b32 m0, s86
	s_add_i32 s92, s86, 0x2000
	global_load_lds_dwordx4 v1, s[14:15]
	v_mov_b32_e32 v1, v176
	s_mov_b32 m0, s92
	s_nop 0
	global_load_lds_dwordx4 v1, s[14:15]
	s_add_u32 s14, s40, s69
	s_addc_u32 s15, s41, 0
	s_add_i32 s26, s86, 0x4000
	v_mov_b32_e32 v1, v136
	s_mov_b32 m0, s26
	s_add_i32 s36, s86, 0x6000
	global_load_lds_dwordx4 v1, s[14:15]
	v_mov_b32_e32 v1, v176
	s_mov_b32 m0, s36
	s_cmp_eq_u32 s16, 1
	global_load_lds_dwordx4 v1, s[14:15]
	s_cselect_b64 s[78:79], -1, 0
	s_cmp_lg_u32 s16, 1
	s_cbranch_scc1 .LBB0_674
	s_barrier
	s_setprio 1

; #define PG8_LDA(dst, b, h) do { _Pragma("unroll") for (int m = 0; m < 4; ++m) _Pragma("unroll") for (int k = 0; k < 2; ++k) dst[m][k] = *(const LAS bf16x8*)(lds + PG8_SA(b, h) + aoff + m * 2048 + k * 1024); } while (0)
; #define PG8_LDB(dst, b, h) do { _Pragma("unroll") for (int n = 0; n < 2; ++n) _Pragma("unroll") for (int k = 0; k < 2; ++k) dst[n][k] = *(const LAS bf16x8*)(lds + PG8_SB(b, h) + boff + n * 2048 + k * 1024); } while (0)
; #define PG8_MMA(ai, bj, At, Bt) do { __builtin_amdgcn_s_setprio(1); _Pragma("unroll") for (int m = 0; m < 4; ++m) _Pragma("unroll") for (int n = 0; n < 2; ++n) _Pragma("unroll") for (int k = 0; k < 2; ++k) \
;         acc[ai][bj][m][n] = __builtin_amdgcn_mfma_f32_16x16x32_bf16(Bt[n][k], At[m][k], acc[ai][bj][m][n], 0, 0, 0); __builtin_amdgcn_s_setprio(0); } while (0)
; #define PG8_WAIT_V(n) asm volatile("s_waitcnt vmcnt(" #n ")" ::: "memory")
; #define PG8_WAIT_L(n) asm volatile("s_waitcnt lgkmcnt(" #n ")" ::: "memory")
; #define PG8_BAR __builtin_amdgcn_s_barrier()
; #define PG8_SCHED __builtin_amdgcn_sched_barrier(0)
; template <class Epi, bool ALIGN_EPI = true, bool SP2 = true>
; DI void gemm_phase(LAS unsigned char* lds, const Gemm g, const StaticOrder& S, const Epi& E) {
;     ...
;         const bool has_next = S.next(ui + 1, nxt);
;         const char* nA = has_next ? (const char*)g.A + (size_t)nxt.pm * tstepA : cA; const char* nB = has_next ? (const char*)g.Bt + (size_t)nxt.pn * tstep : cB;
;         for (int t = 0; t < nt; t += 2) {
;             const bool last = (t == nt - 2);
;             const char* a1 = cA + (size_t)(t + 1) * kstep;
;             const char* a2 = last ? nA : cA + (size_t)(t + 2) * kstep; const char* b2 = last ? nB : cB + (size_t)(t + 2) * kstep;
;             const char* a3 = a2 + kstep; const char* b3 = b2 + kstep;
;             if constexpr (SP2) {
;             PG8_LDB(B0, 0, 0); PG8_LDB(B1, 0, 1); PG8_SCHED; PG8_LDA(At, 0, 0); PG8_STAGE(PG8_SA(1, 1), a1 + hstepA, voffA);
;             PG8_WAIT_V(8); PG8_WAIT_L(0); PG8_BAR; PG8_MMA(0, 0, At, B0); PG8_MMA(0, 1, At, B1); PG8_BAR; PG8_SCHED;
;             PG8_LDA(At, 0, 1); PG8_STAGE(PG8_SB(0, 0), b2, voffB); PG8_STAGE(PG8_SB(0, 1), b2 + hstep, voffB); PG8_STAGE(PG8_SA(0, 0), a2, voffA);
;             PG8_WAIT_V(8); PG8_WAIT_L(0); PG8_BAR; PG8_MMA(1, 0, At, B0); PG8_MMA(1, 1, At, B1); PG8_BAR; PG8_SCHED;
.LBB0_688:
	s_add_i32 s18, s4, 2
	s_cmp_eq_u32 s96, s4
	s_cselect_b32 s46, s0, vcc_lo
	s_cselect_b32 s47, s1, vcc_hi
	s_cselect_b32 s40, s44, s55
	s_cselect_b32 s41, s45, s73
	s_add_u32 s4, s46, 0x80
	s_addc_u32 s5, s47, 0
	s_add_i32 s19, 0, 0x10000
	v_add_u32_e32 v138, s19, v178
	s_add_i32 s8, 0, 0x14000
	ds_read_b128 v[128:131], v138
	ds_read_b128 v[132:135], v138 offset:1024
	ds_read_b128 v[152:155], v138 offset:2048
	ds_read_b128 v[156:159], v138 offset:3072
	v_add_u32_e32 v138, s8, v178
	ds_read_b128 v[180:183], v138
	ds_read_b128 v[184:187], v138 offset:1024
	ds_read_b128 v[188:191], v138 offset:2048
	ds_read_b128 v[192:195], v138 offset:3072
	s_add_u32 s9, vcc_lo, s69
	s_addc_u32 s49, vcc_hi, 0
	s_add_u32 s48, s9, 0xffffff80
	s_addc_u32 s49, s49, -1
	v_mov_b32_e32 v138, v136
	ds_read_b128 v[196:199], v179
	ds_read_b128 v[200:203], v179 offset:1024
	ds_read_b128 v[204:207], v179 offset:2048
	ds_read_b128 v[208:211], v179 offset:3072
	ds_read_b128 v[212:215], v179 offset:4096
	ds_read_b128 v[216:219], v179 offset:5120
	ds_read_b128 v[220:223], v179 offset:6144
	ds_read_b128 v[224:227], v179 offset:7168
	s_add_i32 m0, s86, 0xc000
	s_nop 0
	global_load_lds_dwordx4 v138, s[48:49]
	v_mov_b32_e32 v138, v176
	s_add_i32 m0, s86, 0xe000
	s_nop 0
	global_load_lds_dwordx4 v138, s[48:49]
	s_waitcnt vmcnt(8)
	s_waitcnt lgkmcnt(0)
	s_barrier
	s_waitcnt lgkmcnt(0)
	v_mfma_f32_16x16x32_bf16 v[124:127], v[128:131], v[196:199], v[124:127]
	v_mfma_f32_16x16x32_bf16 v[120:123], v[152:155], v[196:199], v[120:123]
	v_mfma_f32_16x16x32_bf16 v[108:111], v[128:131], v[204:207], v[108:111]
	v_mfma_f32_16x16x32_bf16 v[104:107], v[152:155], v[204:207], v[104:107]
	v_mfma_f32_16x16x32_bf16 v[92:95], v[128:131], v[212:215], v[92:95]
	v_mfma_f32_16x16x32_bf16 v[88:91], v[152:155], v[212:215], v[88:91]
	v_mfma_f32_16x16x32_bf16 v[76:79], v[128:131], v[220:223], v[76:79]
	v_mfma_f32_16x16x32_bf16 v[72:75], v[152:155], v[220:223], v[72:75]
	v_mfma_f32_16x16x32_bf16 v[124:127], v[132:135], v[200:203], v[124:127]
	v_mfma_f32_16x16x32_bf16 v[120:123], v[156:159], v[200:203], v[120:123]
	v_mfma_f32_16x16x32_bf16 v[108:111], v[132:135], v[208:211], v[108:111]
	v_mfma_f32_16x16x32_bf16 v[104:107], v[156:159], v[208:211], v[104:107]
	v_mfma_f32_16x16x32_bf16 v[92:95], v[132:135], v[216:219], v[92:95]
	v_mfma_f32_16x16x32_bf16 v[88:91], v[156:159], v[216:219], v[88:91]
	v_mfma_f32_16x16x32_bf16 v[76:79], v[132:135], v[224:227], v[76:79]
	v_mfma_f32_16x16x32_bf16 v[72:75], v[156:159], v[224:227], v[72:75]
	v_mfma_f32_16x16x32_bf16 v[116:119], v[180:183], v[196:199], v[116:119]
	v_mfma_f32_16x16x32_bf16 v[112:115], v[188:191], v[196:199], v[112:115]
	v_mfma_f32_16x16x32_bf16 v[100:103], v[180:183], v[204:207], v[100:103]
	v_mfma_f32_16x16x32_bf16 v[96:99], v[188:191], v[204:207], v[96:99]
	v_mfma_f32_16x16x32_bf16 v[84:87], v[180:183], v[212:215], v[84:87]
	v_mfma_f32_16x16x32_bf16 v[80:83], v[188:191], v[212:215], v[80:83]
	v_mfma_f32_16x16x32_bf16 v[68:71], v[180:183], v[220:223], v[68:71]
	v_mfma_f32_16x16x32_bf16 v[64:67], v[188:191], v[220:223], v[64:67]
	v_mfma_f32_16x16x32_bf16 v[116:119], v[184:187], v[200:203], v[116:119]
	v_mfma_f32_16x16x32_bf16 v[112:115], v[192:195], v[200:203], v[112:115]
	v_mfma_f32_16x16x32_bf16 v[100:103], v[184:187], v[208:211], v[100:103]
	v_mfma_f32_16x16x32_bf16 v[96:99], v[192:195], v[208:211], v[96:99]
	v_mfma_f32_16x16x32_bf16 v[84:87], v[184:187], v[216:219], v[84:87]
	v_mfma_f32_16x16x32_bf16 v[80:83], v[192:195], v[216:219], v[80:83]
	v_mfma_f32_16x16x32_bf16 v[68:71], v[184:187], v[224:227], v[68:71]
	v_mfma_f32_16x16x32_bf16 v[64:67], v[192:195], v[224:227], v[64:67]
	s_barrier
	s_add_i32 s9, s19, s83
	s_mov_b64 s[48:49], s[40:41]
	v_mov_b32_e32 v138, v143
	s_mov_b32 m0, s9
	ds_read_b128 v[196:199], v179 offset:16384
	ds_read_b128 v[200:203], v179 offset:17408
	ds_read_b128 v[204:207], v179 offset:18432
	ds_read_b128 v[208:211], v179 offset:19456
	ds_read_b128 v[212:215], v179 offset:20480
	ds_read_b128 v[216:219], v179 offset:21504
	ds_read_b128 v[220:223], v179 offset:22528
	ds_read_b128 v[224:227], v179 offset:23552
	s_nop 0
	global_load_lds_dwordx4 v138, s[48:49]
	s_add_i32 m0, s9, 0x2000
	v_mov_b32_e32 v138, v177
	s_add_u32 s94, s40, s54
	s_addc_u32 s95, s41, 0
	global_load_lds_dwordx4 v138, s[48:49]
	s_mov_b64 s[48:49], s[94:95]
	v_mov_b32_e32 v138, v143
	s_add_i32 s8, s8, s83
	s_mov_b32 m0, s8
	s_nop 0
	global_load_lds_dwordx4 v138, s[48:49]
	v_mov_b32_e32 v138, v177
	s_add_i32 m0, s8, 0x2000
	s_nop 0
	global_load_lds_dwordx4 v138, s[48:49]
	s_mov_b64 s[48:49], s[46:47]
	v_mov_b32_e32 v138, v136
	s_mov_b32 m0, s86
	s_nop 0
	global_load_lds_dwordx4 v138, s[48:49]
	v_mov_b32_e32 v138, v176
	s_mov_b32 m0, s92
	s_nop 0
	global_load_lds_dwordx4 v138, s[48:49]
	s_waitcnt vmcnt(8)
	s_waitcnt lgkmcnt(0)
	s_barrier
; #define PG8_LDA(dst, b, h) do { _Pragma("unroll") for (int m = 0; m < 4; ++m) _Pragma("unroll") for (int k = 0; k < 2; ++k) dst[m][k] = *(const LAS bf16x8*)(lds + PG8_SA(b, h) + aoff + m * 2048 + k * 1024); } while (0)
; #define PG8_LDB(dst, b, h) do { _Pragma("unroll") for (int n = 0; n < 2; ++n) _Pragma("unroll") for (int k = 0; k < 2; ++k) dst[n][k] = *(const LAS bf16x8*)(lds + PG8_SB(b, h) + boff + n * 2048 + k * 1024); } while (0)
; #define PG8_MMA(ai, bj, At, Bt) do { __builtin_amdgcn_s_setprio(1); _Pragma("unroll") for (int m = 0; m < 4; ++m) _Pragma("unroll") for (int n = 0; n < 2; ++n) _Pragma("unroll") for (int k = 0; k < 2; ++k) \
;         acc[ai][bj][m][n] = __builtin_amdgcn_mfma_f32_16x16x32_bf16(Bt[n][k], At[m][k], acc[ai][bj][m][n], 0, 0, 0); __builtin_amdgcn_s_setprio(0); } while (0)
; #define PG8_WAIT_V(n) asm volatile("s_waitcnt vmcnt(" #n ")" ::: "memory")
; #define PG8_WAIT_L(n) asm volatile("s_waitcnt lgkmcnt(" #n ")" ::: "memory")
; #define PG8_BAR __builtin_amdgcn_s_barrier()
; #define PG8_SCHED __builtin_amdgcn_sched_barrier(0)
; template <class Epi, bool ALIGN_EPI = true, bool SP2 = true>
; DI void gemm_phase(LAS unsigned char* lds, const Gemm g, const StaticOrder& S, const Epi& E) {
;     ...
;             PG8_WAIT_V(8); PG8_WAIT_L(0); PG8_BAR; PG8_MMA(1, 0, At, B0); PG8_MMA(1, 1, At, B1); PG8_BAR; PG8_SCHED;
;             PG8_LDB(B0, 1, 0); PG8_LDB(B1, 1, 1); PG8_SCHED; PG8_LDA(At, 1, 0); PG8_STAGE(PG8_SA(0, 1), a2 + hstepA, voffA);
;             PG8_WAIT_V(8); PG8_WAIT_L(0); PG8_BAR; PG8_MMA(0, 0, At, B0); PG8_MMA(0, 1, At, B1); PG8_BAR; PG8_SCHED;
	s_waitcnt lgkmcnt(0)
	v_mfma_f32_16x16x32_bf16 v[60:63], v[128:131], v[196:199], v[60:63]
	v_mfma_f32_16x16x32_bf16 v[56:59], v[152:155], v[196:199], v[56:59]
	v_mfma_f32_16x16x32_bf16 v[44:47], v[128:131], v[204:207], v[44:47]
	v_mfma_f32_16x16x32_bf16 v[40:43], v[152:155], v[204:207], v[40:43]
	v_mfma_f32_16x16x32_bf16 v[28:31], v[128:131], v[212:215], v[28:31]
	v_mfma_f32_16x16x32_bf16 v[24:27], v[152:155], v[212:215], v[24:27]
	v_mfma_f32_16x16x32_bf16 v[12:15], v[128:131], v[220:223], v[12:15]
	v_mfma_f32_16x16x32_bf16 v[8:11], v[152:155], v[220:223], v[8:11]
	v_mfma_f32_16x16x32_bf16 v[60:63], v[132:135], v[200:203], v[60:63]
	v_mfma_f32_16x16x32_bf16 v[56:59], v[156:159], v[200:203], v[56:59]
	v_mfma_f32_16x16x32_bf16 v[44:47], v[132:135], v[208:211], v[44:47]
	v_mfma_f32_16x16x32_bf16 v[40:43], v[156:159], v[208:211], v[40:43]
	v_mfma_f32_16x16x32_bf16 v[28:31], v[132:135], v[216:219], v[28:31]
	v_mfma_f32_16x16x32_bf16 v[24:27], v[156:159], v[216:219], v[24:27]
	v_mfma_f32_16x16x32_bf16 v[12:15], v[132:135], v[224:227], v[12:15]
	v_mfma_f32_16x16x32_bf16 v[8:11], v[156:159], v[224:227], v[8:11]
	v_mfma_f32_16x16x32_bf16 v[52:55], v[180:183], v[196:199], v[52:55]
	v_mfma_f32_16x16x32_bf16 v[48:51], v[188:191], v[196:199], v[48:51]
	v_mfma_f32_16x16x32_bf16 v[36:39], v[180:183], v[204:207], v[36:39]
	v_mfma_f32_16x16x32_bf16 v[32:35], v[188:191], v[204:207], v[32:35]
	v_mfma_f32_16x16x32_bf16 v[20:23], v[180:183], v[212:215], v[20:23]
	v_mfma_f32_16x16x32_bf16 v[16:19], v[188:191], v[212:215], v[16:19]
	v_mfma_f32_16x16x32_bf16 v[4:7], v[180:183], v[220:223], v[4:7]
	v_mfma_f32_16x16x32_bf16 v[0:3], v[188:191], v[220:223], v[0:3]
	v_mfma_f32_16x16x32_bf16 v[52:55], v[184:187], v[200:203], v[52:55]
	v_mfma_f32_16x16x32_bf16 v[48:51], v[192:195], v[200:203], v[48:51]
	v_mfma_f32_16x16x32_bf16 v[36:39], v[184:187], v[208:211], v[36:39]
	v_mfma_f32_16x16x32_bf16 v[32:35], v[192:195], v[208:211], v[32:35]
	v_mfma_f32_16x16x32_bf16 v[20:23], v[184:187], v[216:219], v[20:23]
	v_mfma_f32_16x16x32_bf16 v[16:19], v[192:195], v[216:219], v[16:19]
	v_mfma_f32_16x16x32_bf16 v[4:7], v[184:187], v[224:227], v[4:7]
	v_mfma_f32_16x16x32_bf16 v[0:3], v[192:195], v[224:227], v[0:3]
	s_barrier
	s_add_i32 s8, 0, 0x18000
	v_add_u32_e32 v138, s8, v178
	s_add_i32 s9, 0, 0x1c000
	ds_read_b128 v[128:131], v138
	ds_read_b128 v[132:135], v138 offset:1024
	ds_read_b128 v[152:155], v138 offset:2048
	ds_read_b128 v[156:159], v138 offset:3072
	v_add_u32_e32 v138, s9, v178
	ds_read_b128 v[180:183], v138
	ds_read_b128 v[184:187], v138 offset:1024
	ds_read_b128 v[188:191], v138 offset:2048
	ds_read_b128 v[192:195], v138 offset:3072
	s_add_u32 s46, s46, s69
	s_addc_u32 s47, s47, 0
	v_mov_b32_e32 v138, v136
	s_mov_b32 m0, s26
	ds_read_b128 v[196:199], v179 offset:32768
	ds_read_b128 v[200:203], v179 offset:33792
	ds_read_b128 v[204:207], v179 offset:34816
	ds_read_b128 v[208:211], v179 offset:35840
	ds_read_b128 v[212:215], v179 offset:36864
	ds_read_b128 v[216:219], v179 offset:37888
	ds_read_b128 v[220:223], v179 offset:38912
	ds_read_b128 v[224:227], v179 offset:39936
	s_nop 0
	global_load_lds_dwordx4 v138, s[46:47]
	v_mov_b32_e32 v138, v176
	s_mov_b32 m0, s36
	s_nop 0
	global_load_lds_dwordx4 v138, s[46:47]
	s_waitcnt vmcnt(8)
	s_waitcnt lgkmcnt(0)
	s_barrier
	s_waitcnt lgkmcnt(0)
	v_mfma_f32_16x16x32_bf16 v[124:127], v[128:131], v[196:199], v[124:127]
	v_mfma_f32_16x16x32_bf16 v[120:123], v[152:155], v[196:199], v[120:123]
	v_mfma_f32_16x16x32_bf16 v[108:111], v[128:131], v[204:207], v[108:111]
	v_mfma_f32_16x16x32_bf16 v[104:107], v[152:155], v[204:207], v[104:107]
	v_mfma_f32_16x16x32_bf16 v[92:95], v[128:131], v[212:215], v[92:95]
	v_mfma_f32_16x16x32_bf16 v[88:91], v[152:155], v[212:215], v[88:91]
	v_mfma_f32_16x16x32_bf16 v[76:79], v[128:131], v[220:223], v[76:79]
	v_mfma_f32_16x16x32_bf16 v[72:75], v[152:155], v[220:223], v[72:75]
	v_mfma_f32_16x16x32_bf16 v[124:127], v[132:135], v[200:203], v[124:127]
	v_mfma_f32_16x16x32_bf16 v[120:123], v[156:159], v[200:203], v[120:123]
	v_mfma_f32_16x16x32_bf16 v[108:111], v[132:135], v[208:211], v[108:111]
	v_mfma_f32_16x16x32_bf16 v[104:107], v[156:159], v[208:211], v[104:107]
	v_mfma_f32_16x16x32_bf16 v[92:95], v[132:135], v[216:219], v[92:95]
	v_mfma_f32_16x16x32_bf16 v[88:91], v[156:159], v[216:219], v[88:91]
	v_mfma_f32_16x16x32_bf16 v[76:79], v[132:135], v[224:227], v[76:79]
	v_mfma_f32_16x16x32_bf16 v[72:75], v[156:159], v[224:227], v[72:75]
	v_mfma_f32_16x16x32_bf16 v[116:119], v[180:183], v[196:199], v[116:119]
	v_mfma_f32_16x16x32_bf16 v[112:115], v[188:191], v[196:199], v[112:115]
	v_mfma_f32_16x16x32_bf16 v[100:103], v[180:183], v[204:207], v[100:103]
	v_mfma_f32_16x16x32_bf16 v[96:99], v[188:191], v[204:207], v[96:99]
	v_mfma_f32_16x16x32_bf16 v[84:87], v[180:183], v[212:215], v[84:87]
	v_mfma_f32_16x16x32_bf16 v[80:83], v[188:191], v[212:215], v[80:83]
	v_mfma_f32_16x16x32_bf16 v[68:71], v[180:183], v[220:223], v[68:71]
	v_mfma_f32_16x16x32_bf16 v[64:67], v[188:191], v[220:223], v[64:67]
	v_mfma_f32_16x16x32_bf16 v[116:119], v[184:187], v[200:203], v[116:119]
	v_mfma_f32_16x16x32_bf16 v[112:115], v[192:195], v[200:203], v[112:115]
	v_mfma_f32_16x16x32_bf16 v[100:103], v[184:187], v[208:211], v[100:103]
	v_mfma_f32_16x16x32_bf16 v[96:99], v[192:195], v[208:211], v[96:99]
	v_mfma_f32_16x16x32_bf16 v[84:87], v[184:187], v[216:219], v[84:87]
	v_mfma_f32_16x16x32_bf16 v[80:83], v[192:195], v[216:219], v[80:83]
	v_mfma_f32_16x16x32_bf16 v[68:71], v[184:187], v[224:227], v[68:71]
	v_mfma_f32_16x16x32_bf16 v[64:67], v[192:195], v[224:227], v[64:67]
	s_barrier
; #define PG8_LDA(dst, b, h) do { _Pragma("unroll") for (int m = 0; m < 4; ++m) _Pragma("unroll") for (int k = 0; k < 2; ++k) dst[m][k] = *(const LAS bf16x8*)(lds + PG8_SA(b, h) + aoff + m * 2048 + k * 1024); } while (0)
; #define PG8_MMA(ai, bj, At, Bt) do { __builtin_amdgcn_s_setprio(1); _Pragma("unroll") for (int m = 0; m < 4; ++m) _Pragma("unroll") for (int n = 0; n < 2; ++n) _Pragma("unroll") for (int k = 0; k < 2; ++k) \
;         acc[ai][bj][m][n] = __builtin_amdgcn_mfma_f32_16x16x32_bf16(Bt[n][k], At[m][k], acc[ai][bj][m][n], 0, 0, 0); __builtin_amdgcn_s_setprio(0); } while (0)
; #define PG8_WAIT_V(n) asm volatile("s_waitcnt vmcnt(" #n ")" ::: "memory")
; #define PG8_WAIT_L(n) asm volatile("s_waitcnt lgkmcnt(" #n ")" ::: "memory")
; #define PG8_BAR __builtin_amdgcn_s_barrier()
; #define PG8_SCHED __builtin_amdgcn_sched_barrier(0)
; template <class Epi, bool ALIGN_EPI = true, bool SP2 = true>
; DI void gemm_phase(LAS unsigned char* lds, const Gemm g, const StaticOrder& S, const Epi& E) {
;     ...
;             PG8_LDA(At, 1, 1); PG8_STAGE(PG8_SB(1, 0), b3, voffB); PG8_STAGE(PG8_SB(1, 1), b3 + hstep, voffB); PG8_STAGE(PG8_SA(1, 0), a3, voffA);
;             PG8_WAIT_V(8); PG8_WAIT_L(0); PG8_BAR; PG8_MMA(1, 0, At, B0); PG8_MMA(1, 1, At, B1); PG8_BAR; PG8_SCHED;
;     ...
;         }
;         if constexpr (ALIGN_EPI) { if (wr == 0) PG8_BAR; }
	s_add_u32 s40, s40, 0x80
	s_addc_u32 s41, s41, 0
	v_mov_b32_e32 v138, v143
	s_add_i32 s8, s8, s83
	ds_read_b128 v[196:199], v179 offset:49152
	ds_read_b128 v[200:203], v179 offset:50176
	ds_read_b128 v[204:207], v179 offset:51200
	ds_read_b128 v[208:211], v179 offset:52224
	ds_read_b128 v[212:215], v179 offset:53248
	ds_read_b128 v[216:219], v179 offset:54272
	ds_read_b128 v[220:223], v179 offset:55296
	ds_read_b128 v[224:227], v179 offset:56320
	s_mov_b32 m0, s8
	s_nop 0
	global_load_lds_dwordx4 v138, s[40:41]
	v_mov_b32_e32 v138, v177
	s_add_i32 m0, s8, 0x2000
	s_nop 0
	global_load_lds_dwordx4 v138, s[40:41]
	s_add_u32 s40, s94, 0x80
	s_addc_u32 s41, s95, 0
	v_mov_b32_e32 v138, v143
	s_add_i32 s8, s9, s83
	s_mov_b32 m0, s8
	s_nop 0
	global_load_lds_dwordx4 v138, s[40:41]
	v_mov_b32_e32 v138, v177
	s_add_i32 m0, s8, 0x2000
	s_nop 0
	global_load_lds_dwordx4 v138, s[40:41]
	v_mov_b32_e32 v138, v136
	s_mov_b32 m0, s12
	s_nop 0
	global_load_lds_dwordx4 v138, s[4:5]
	v_mov_b32_e32 v138, v176
	s_mov_b32 m0, s13
	s_nop 0
	global_load_lds_dwordx4 v138, s[4:5]
	s_waitcnt vmcnt(8)
	s_waitcnt lgkmcnt(0)
	s_barrier
	s_waitcnt lgkmcnt(0)
	v_mfma_f32_16x16x32_bf16 v[60:63], v[128:131], v[196:199], v[60:63]
	v_mfma_f32_16x16x32_bf16 v[56:59], v[152:155], v[196:199], v[56:59]
	v_mfma_f32_16x16x32_bf16 v[44:47], v[128:131], v[204:207], v[44:47]
	v_mfma_f32_16x16x32_bf16 v[40:43], v[152:155], v[204:207], v[40:43]
	v_mfma_f32_16x16x32_bf16 v[28:31], v[128:131], v[212:215], v[28:31]
	v_mfma_f32_16x16x32_bf16 v[24:27], v[152:155], v[212:215], v[24:27]
	v_mfma_f32_16x16x32_bf16 v[12:15], v[128:131], v[220:223], v[12:15]
	v_mfma_f32_16x16x32_bf16 v[8:11], v[152:155], v[220:223], v[8:11]
	v_mfma_f32_16x16x32_bf16 v[60:63], v[132:135], v[200:203], v[60:63]
	v_mfma_f32_16x16x32_bf16 v[56:59], v[156:159], v[200:203], v[56:59]
	v_mfma_f32_16x16x32_bf16 v[44:47], v[132:135], v[208:211], v[44:47]
	v_mfma_f32_16x16x32_bf16 v[40:43], v[156:159], v[208:211], v[40:43]
	v_mfma_f32_16x16x32_bf16 v[28:31], v[132:135], v[216:219], v[28:31]
	v_mfma_f32_16x16x32_bf16 v[24:27], v[156:159], v[216:219], v[24:27]
	v_mfma_f32_16x16x32_bf16 v[12:15], v[132:135], v[224:227], v[12:15]
	v_mfma_f32_16x16x32_bf16 v[8:11], v[156:159], v[224:227], v[8:11]
	v_mfma_f32_16x16x32_bf16 v[52:55], v[180:183], v[196:199], v[52:55]
	v_mfma_f32_16x16x32_bf16 v[48:51], v[188:191], v[196:199], v[48:51]
	v_mfma_f32_16x16x32_bf16 v[36:39], v[180:183], v[204:207], v[36:39]
	v_mfma_f32_16x16x32_bf16 v[32:35], v[188:191], v[204:207], v[32:35]
	v_mfma_f32_16x16x32_bf16 v[20:23], v[180:183], v[212:215], v[20:23]
	v_mfma_f32_16x16x32_bf16 v[16:19], v[188:191], v[212:215], v[16:19]
	v_mfma_f32_16x16x32_bf16 v[4:7], v[180:183], v[220:223], v[4:7]
	v_mfma_f32_16x16x32_bf16 v[0:3], v[188:191], v[220:223], v[0:3]
	v_mfma_f32_16x16x32_bf16 v[52:55], v[184:187], v[200:203], v[52:55]
	v_mfma_f32_16x16x32_bf16 v[48:51], v[192:195], v[200:203], v[48:51]
	v_mfma_f32_16x16x32_bf16 v[36:39], v[184:187], v[208:211], v[36:39]
	v_mfma_f32_16x16x32_bf16 v[32:35], v[192:195], v[208:211], v[32:35]
	v_mfma_f32_16x16x32_bf16 v[20:23], v[184:187], v[216:219], v[20:23]
	v_mfma_f32_16x16x32_bf16 v[16:19], v[192:195], v[216:219], v[16:19]
	v_mfma_f32_16x16x32_bf16 v[4:7], v[184:187], v[224:227], v[4:7]
	v_mfma_f32_16x16x32_bf16 v[0:3], v[192:195], v[224:227], v[0:3]
	s_barrier
	s_add_u32 vcc_lo, vcc_lo, 0x100
	s_addc_u32 vcc_hi, vcc_hi, 0
	s_add_u32 s55, s55, 0x100
	s_addc_u32 s73, s73, 0
	s_cmp_ge_u32 s18, s81
	s_mov_b32 s4, s18
	s_cbranch_scc0 .LBB0_688
	s_and_b64 vcc, exec, s[84:85]
	s_cbranch_vccz .LBB0_691
	s_barrier

; DI int otid() { int t = threadIdx.x; asm volatile("" : "+v"(t)); return t; }
; #define PG8_BAR __builtin_amdgcn_s_barrier()
; template <class Epi, bool ALIGN_EPI = true, bool SP2 = true>
; DI void gemm_phase(LAS unsigned char* lds, const Gemm g, const StaticOrder& S, const Epi& E) {
;     const int tid = otid(), wid = __builtin_amdgcn_readfirstlane(tid >> 6), lane = tid & 63, wr = wid >> 2, wc = wid & 3, fr = lane & 15, fq = lane >> 4;
;     const int K = g.K, nt = K / BK;
;     unsigned voffA[2], voffB[2];
; #pragma unroll
;     for (int i = 0; i < 2; ++i) { int R, C; stage_rc(tid * 16 + i * 8192, R, C); const int Rb = Epi::PERM ? ((R & ~31) + perm32(R & 31)) : R;
;         voffA[i] = (unsigned)(R * g.lda + C) * 2u; voffB[i] = (unsigned)(Rb * K + C) * 2u; }
;     ...
;     const char* cA = (const char*)g.A + (size_t)cur.pm * tstepA; const char* cB = (const char*)g.Bt + (size_t)cur.pn * tstep;
;     if constexpr (SP2) {
;         PG8_STAGE(PG8_SB(0, 0), cB, voffB); PG8_STAGE(PG8_SB(0, 1), cB + hstep, voffB); PG8_STAGE(PG8_SA(0, 0), cA, voffA); PG8_STAGE(PG8_SA(0, 1), cA + hstepA, voffA);
;         if (wr == 1) PG8_BAR;
.LBB0_761:
	v_readlane_b32 s0, v253, 12
	v_mov_b32_e32 v0, v163
	v_readlane_b32 s1, v253, 13
	s_andn2_b64 vcc, exec, s[0:1]
	v_readfirstlane_b32 s2, v0
	s_cbranch_vccnz .LBB0_3
	v_readlane_b32 s3, v255, 56
	s_cmp_eq_u32 s3, 7
	v_readlane_b32 s6, v255, 54
	s_cselect_b64 s[0:1], -1, 0
	s_cmp_eq_u32 s3, 0
	v_readlane_b32 s7, v255, 55
	v_cndmask_b32_e64 v1, 0, 1, s[0:1]
	s_cselect_b64 s[0:1], -1, 0
	s_and_b64 s[4:5], s[6:7], exec
	v_bfe_i32 v3, v0, 27, 1
	v_readfirstlane_b32 s4, v1
	v_lshlrev_b32_e32 v1, 4, v0
	v_lshrrev_b32_e32 v3, 22, v3
	v_add_u32_e32 v3, v1, v3
	v_and_b32_e32 v3, 0xfffffc00, v3
	v_sub_u32_e32 v3, v1, v3
	v_ashrrev_i32_e32 v2, 31, v0
	v_lshrrev_b32_e32 v4, 4, v3
	s_cselect_b32 s3, 2, 0
	v_lshrrev_b32_e32 v2, 26, v2
	v_bitop3_b32 v4, v4, v3, 32 bitop3:0x6c
	v_ashrrev_i32_e32 v3, 31, v3
	s_or_b32 s3, s3, s4
	v_add_u32_e32 v2, v0, v2
	v_lshrrev_b32_e32 v3, 26, v3
	s_mul_i32 s3, s3, 0x1080000
	v_ashrrev_i32_e32 v2, 6, v2
	v_add_u32_e32 v3, v4, v3
	s_add_u32 s42, s88, s3
	v_lshlrev_b32_e32 v5, 3, v2
	v_ashrrev_i32_e32 v3, 6, v3
	s_addc_u32 s43, s89, 0
	s_and_b64 s[0:1], s[6:7], s[0:1]
	v_and_b32_e32 v5, -16, v5
	v_mul_i32_i24_e32 v6, 64, v3
	s_and_b64 s[0:1], s[0:1], exec
	v_add_u32_e32 v5, v3, v5
	v_sub_u32_e32 v4, v4, v6
	v_lshlrev_b32_e32 v2, 5, v2
	v_ashrrev_i16_sdwa v4, v166, sext(v4) dst_sel:DWORD dst_unused:UNUSED_PAD src0_sel:DWORD src1_sel:BYTE_0
	v_lshlrev_b32_e32 v6, 1, v5
	v_lshrrev_b32_e32 v7, 2, v5
	v_and_b32_e32 v3, 3, v3
	s_mov_b32 s0, 0x1fffe0
	v_and_b32_e32 v2, 32, v2
	v_bfe_i32 v4, v4, 0, 16
	v_and_b32_e32 v6, 24, v6
	v_and_b32_e32 v7, 4, v7
	v_and_or_b32 v3, v5, s0, v3
	v_or3_b32 v3, v3, v7, v6
	v_add_lshl_u32 v2, v2, v4, 1
	v_add_u32_e32 v1, 0x2000, v1
	v_lshl_add_u32 v130, v5, 11, v2
	v_lshl_add_u32 v131, v3, 11, v2
	v_ashrrev_i32_e32 v2, 31, v1
	v_lshrrev_b32_e32 v2, 22, v2
	v_add_u32_e32 v2, v1, v2
	v_ashrrev_i32_e32 v2, 10, v2
	v_mul_i32_i24_e32 v3, 0x400, v2
	v_sub_u32_e32 v1, v1, v3
	v_lshrrev_b32_e32 v3, 4, v1
	v_bitop3_b32 v1, v3, v1, 32 bitop3:0x6c
	v_ashrrev_i32_e32 v4, 31, v1
	v_lshrrev_b32_e32 v4, 26, v4
	v_lshlrev_b32_e32 v3, 3, v2
	v_add_u32_e32 v4, v1, v4
	v_and_b32_e32 v3, -16, v3
	v_ashrrev_i32_e32 v5, 6, v4
	v_and_b32_e32 v4, 0xc0, v4
	s_cselect_b32 s44, s97, s95
	s_cselect_b32 s45, s96, s94
	v_add_u32_e32 v3, v5, v3
	v_sub_u32_e32 v1, v1, v4
	v_and_b32_e32 v5, 3, v5
	s_ashr_i32 s4, s2, 6
	s_ashr_i32 s3, s2, 8
	v_lshlrev_b32_e32 v2, 5, v2
	v_ashrrev_i16_sdwa v1, v166, sext(v1) dst_sel:DWORD dst_unused:UNUSED_PAD src0_sel:DWORD src1_sel:BYTE_0
	v_lshlrev_b32_e32 v4, 1, v3
	v_lshrrev_b32_e32 v6, 2, v3
	v_and_or_b32 v5, v3, s0, v5
	s_lshl_b32 s46, s4, 10
	v_readlane_b32 s0, v254, 16
	v_and_b32_e32 v2, 32, v2
	v_bfe_i32 v1, v1, 0, 16
	v_and_b32_e32 v4, 24, v4
	v_and_b32_e32 v6, 4, v6
	v_readlane_b32 s1, v254, 17
	s_add_u32 s16, s42, s0
	v_or3_b32 v4, v5, v6, v4
	v_add_lshl_u32 v1, v2, v1, 1
	s_addc_u32 s17, s43, s1
	v_lshl_add_u32 v132, v3, 11, v1
	v_lshl_add_u32 v133, v4, 11, v1
	s_mov_b64 s[0:1], s[16:17]
	s_add_i32 s47, s46, 0
	v_mov_b32_e32 v1, v131
	s_add_i32 m0, s47, 0x10000
	s_nop 0
	global_load_lds_dwordx4 v1, s[0:1]
	v_mov_b32_e32 v1, v133
	s_add_i32 m0, s47, 0x12000
	s_nop 0
	global_load_lds_dwordx4 v1, s[0:1]
	s_add_u32 s0, s16, 0x40000
	s_addc_u32 s1, s17, 0
	v_mov_b32_e32 v1, v131
	s_add_i32 m0, s47, 0x14000
	s_nop 0
	global_load_lds_dwordx4 v1, s[0:1]
	v_mov_b32_e32 v1, v133
	s_add_i32 m0, s47, 0x16000
	s_nop 0
	global_load_lds_dwordx4 v1, s[0:1]
	v_readlane_b32 s0, v254, 21
	v_readlane_b32 s1, v254, 22
	s_add_u32 s14, s45, s0
	s_addc_u32 s15, s44, s1
	s_mov_b64 s[0:1], s[14:15]
	v_mov_b32_e32 v1, v130
	s_mov_b32 m0, s47
	s_add_i32 s48, s47, 0x2000
	global_load_lds_dwordx4 v1, s[0:1]
	v_mov_b32_e32 v1, v132
	s_mov_b32 m0, s48
	s_nop 0
	global_load_lds_dwordx4 v1, s[0:1]
	s_add_u32 s0, s14, 0x40000
	s_addc_u32 s1, s15, 0
	s_add_i32 s49, s47, 0x4000
	v_mov_b32_e32 v1, v130
	s_mov_b32 m0, s49
	s_add_i32 s54, s47, 0x6000
	global_load_lds_dwordx4 v1, s[0:1]
	v_mov_b32_e32 v1, v132
	s_mov_b32 m0, s54
	s_cmp_eq_u32 s3, 1
	global_load_lds_dwordx4 v1, s[0:1]
	s_cselect_b64 s[0:1], -1, 0
	s_cmp_lg_u32 s3, 1
	s_cbranch_scc1 .LBB0_764
	s_barrier
	s_setprio 1

; #define PG8_LDA(dst, b, h) do { _Pragma("unroll") for (int m = 0; m < 4; ++m) _Pragma("unroll") for (int k = 0; k < 2; ++k) dst[m][k] = *(const LAS bf16x8*)(lds + PG8_SA(b, h) + aoff + m * 2048 + k * 1024); } while (0)
; #define PG8_LDB(dst, b, h) do { _Pragma("unroll") for (int n = 0; n < 2; ++n) _Pragma("unroll") for (int k = 0; k < 2; ++k) dst[n][k] = *(const LAS bf16x8*)(lds + PG8_SB(b, h) + boff + n * 2048 + k * 1024); } while (0)
; #define PG8_MMA(ai, bj, At, Bt) do { __builtin_amdgcn_s_setprio(1); _Pragma("unroll") for (int m = 0; m < 4; ++m) _Pragma("unroll") for (int n = 0; n < 2; ++n) _Pragma("unroll") for (int k = 0; k < 2; ++k) \
;         acc[ai][bj][m][n] = __builtin_amdgcn_mfma_f32_16x16x32_bf16(Bt[n][k], At[m][k], acc[ai][bj][m][n], 0, 0, 0); __builtin_amdgcn_s_setprio(0); } while (0)
; #define PG8_WAIT_V(n) asm volatile("s_waitcnt vmcnt(" #n ")" ::: "memory")
; #define PG8_WAIT_L(n) asm volatile("s_waitcnt lgkmcnt(" #n ")" ::: "memory")
; #define PG8_BAR __builtin_amdgcn_s_barrier()
; #define PG8_SCHED __builtin_amdgcn_sched_barrier(0)
; template <class Epi, bool ALIGN_EPI = true, bool SP2 = true>
; DI void gemm_phase(LAS unsigned char* lds, const Gemm g, const StaticOrder& S, const Epi& E) {
;     ...
;         const bool has_next = S.next(ui + 1, nxt);
;         const char* nA = has_next ? (const char*)g.A + (size_t)nxt.pm * tstepA : cA; const char* nB = has_next ? (const char*)g.Bt + (size_t)nxt.pn * tstep : cB;
;         for (int t = 0; t < nt; t += 2) {
;             const bool last = (t == nt - 2);
;             const char* a1 = cA + (size_t)(t + 1) * kstep;
;             const char* a2 = last ? nA : cA + (size_t)(t + 2) * kstep; const char* b2 = last ? nB : cB + (size_t)(t + 2) * kstep;
;             const char* a3 = a2 + kstep; const char* b3 = b2 + kstep;
;             if constexpr (SP2) {
;             PG8_LDB(B0, 0, 0); PG8_LDB(B1, 0, 1); PG8_SCHED; PG8_LDA(At, 0, 0); PG8_STAGE(PG8_SA(1, 1), a1 + hstepA, voffA);
;             PG8_WAIT_V(8); PG8_WAIT_L(0); PG8_BAR; PG8_MMA(0, 0, At, B0); PG8_MMA(0, 1, At, B1); PG8_BAR; PG8_SCHED;
;             PG8_LDA(At, 0, 1); PG8_STAGE(PG8_SB(0, 0), b2, voffB); PG8_STAGE(PG8_SB(0, 1), b2 + hstep, voffB); PG8_STAGE(PG8_SA(0, 0), a2, voffA);
;             PG8_WAIT_V(8); PG8_WAIT_L(0); PG8_BAR; PG8_MMA(1, 0, At, B0); PG8_MMA(1, 1, At, B1); PG8_BAR; PG8_SCHED;
.LBB0_770:
	s_add_u32 s16, s14, 0xfffc0080
	s_addc_u32 s17, s15, -1
	s_cmp_eq_u32 s81, 12
	s_cselect_b32 s40, s36, s16
	s_cselect_b32 s41, s9, s17
	s_cselect_b32 s18, s38, s70
	s_cselect_b32 s19, s7, s72
	s_add_u32 s16, s40, 0x80
	s_addc_u32 s17, s41, 0
	s_add_i32 s86, 0, 0x10000
	v_add_u32_e32 v128, s86, v134
	s_add_i32 s92, 0, 0x14000
	ds_read_b128 v[148:151], v128
	ds_read_b128 v[152:155], v128 offset:1024
	ds_read_b128 v[156:159], v128 offset:2048
	ds_read_b128 v[176:179], v128 offset:3072
	v_add_u32_e32 v128, s92, v134
	ds_read_b128 v[180:183], v128
	ds_read_b128 v[184:187], v128 offset:1024
	ds_read_b128 v[188:191], v128 offset:2048
	ds_read_b128 v[192:195], v128 offset:3072
	s_mov_b64 s[96:97], s[14:15]
	v_mov_b32_e32 v128, v130
	ds_read_b128 v[196:199], v135
	ds_read_b128 v[200:203], v135 offset:1024
	ds_read_b128 v[204:207], v135 offset:2048
	ds_read_b128 v[208:211], v135 offset:3072
	ds_read_b128 v[212:215], v135 offset:4096
	ds_read_b128 v[216:219], v135 offset:5120
	ds_read_b128 v[220:223], v135 offset:6144
	ds_read_b128 v[224:227], v135 offset:7168
	s_add_i32 m0, s47, 0xc000
	s_nop 0
	global_load_lds_dwordx4 v128, s[96:97]
	v_mov_b32_e32 v128, v132
	s_add_i32 m0, s47, 0xe000
	s_nop 0
	global_load_lds_dwordx4 v128, s[96:97]
	s_waitcnt vmcnt(8)
	s_waitcnt lgkmcnt(0)
	s_barrier
	s_waitcnt lgkmcnt(0)
	v_mfma_f32_16x16x32_bf16 v[124:127], v[148:151], v[196:199], v[124:127]
	v_mfma_f32_16x16x32_bf16 v[116:119], v[156:159], v[196:199], v[116:119]
	v_mfma_f32_16x16x32_bf16 v[108:111], v[148:151], v[204:207], v[108:111]
	v_mfma_f32_16x16x32_bf16 v[100:103], v[156:159], v[204:207], v[100:103]
	v_mfma_f32_16x16x32_bf16 v[92:95], v[148:151], v[212:215], v[92:95]
	v_mfma_f32_16x16x32_bf16 v[84:87], v[156:159], v[212:215], v[84:87]
	v_mfma_f32_16x16x32_bf16 v[76:79], v[148:151], v[220:223], v[76:79]
	v_mfma_f32_16x16x32_bf16 v[68:71], v[156:159], v[220:223], v[68:71]
	v_mfma_f32_16x16x32_bf16 v[124:127], v[152:155], v[200:203], v[124:127]
	v_mfma_f32_16x16x32_bf16 v[116:119], v[176:179], v[200:203], v[116:119]
	v_mfma_f32_16x16x32_bf16 v[108:111], v[152:155], v[208:211], v[108:111]
	v_mfma_f32_16x16x32_bf16 v[100:103], v[176:179], v[208:211], v[100:103]
	v_mfma_f32_16x16x32_bf16 v[92:95], v[152:155], v[216:219], v[92:95]
	v_mfma_f32_16x16x32_bf16 v[84:87], v[176:179], v[216:219], v[84:87]
	v_mfma_f32_16x16x32_bf16 v[76:79], v[152:155], v[224:227], v[76:79]
	v_mfma_f32_16x16x32_bf16 v[68:71], v[176:179], v[224:227], v[68:71]
	v_mfma_f32_16x16x32_bf16 v[120:123], v[180:183], v[196:199], v[120:123]
	v_mfma_f32_16x16x32_bf16 v[112:115], v[188:191], v[196:199], v[112:115]
	v_mfma_f32_16x16x32_bf16 v[104:107], v[180:183], v[204:207], v[104:107]
	v_mfma_f32_16x16x32_bf16 v[96:99], v[188:191], v[204:207], v[96:99]
	v_mfma_f32_16x16x32_bf16 v[88:91], v[180:183], v[212:215], v[88:91]
	v_mfma_f32_16x16x32_bf16 v[80:83], v[188:191], v[212:215], v[80:83]
	v_mfma_f32_16x16x32_bf16 v[72:75], v[180:183], v[220:223], v[72:75]
	v_mfma_f32_16x16x32_bf16 v[64:67], v[188:191], v[220:223], v[64:67]
	v_mfma_f32_16x16x32_bf16 v[120:123], v[184:187], v[200:203], v[120:123]
	v_mfma_f32_16x16x32_bf16 v[112:115], v[192:195], v[200:203], v[112:115]
	v_mfma_f32_16x16x32_bf16 v[104:107], v[184:187], v[208:211], v[104:107]
	v_mfma_f32_16x16x32_bf16 v[96:99], v[192:195], v[208:211], v[96:99]
	v_mfma_f32_16x16x32_bf16 v[88:91], v[184:187], v[216:219], v[88:91]
	v_mfma_f32_16x16x32_bf16 v[80:83], v[192:195], v[216:219], v[80:83]
	v_mfma_f32_16x16x32_bf16 v[72:75], v[184:187], v[224:227], v[72:75]
	v_mfma_f32_16x16x32_bf16 v[64:67], v[192:195], v[224:227], v[64:67]
	s_barrier
	s_mov_b64 s[96:97], s[18:19]
	v_mov_b32_e32 v128, v131
	s_add_i32 s86, s86, s46
	ds_read_b128 v[196:199], v135 offset:16384
	ds_read_b128 v[200:203], v135 offset:17408
	ds_read_b128 v[204:207], v135 offset:18432
	ds_read_b128 v[208:211], v135 offset:19456
	ds_read_b128 v[212:215], v135 offset:20480
	ds_read_b128 v[216:219], v135 offset:21504
	ds_read_b128 v[220:223], v135 offset:22528
	ds_read_b128 v[224:227], v135 offset:23552
	s_mov_b32 m0, s86
	s_nop 0
	global_load_lds_dwordx4 v128, s[96:97]
	v_mov_b32_e32 v128, v133
	s_add_i32 m0, s86, 0x2000
	s_nop 0
	global_load_lds_dwordx4 v128, s[96:97]
	s_add_u32 s96, s18, 0x40000
	s_addc_u32 s97, s19, 0
	v_mov_b32_e32 v128, v131
	s_add_i32 s86, s92, s46
	s_mov_b32 m0, s86
	s_nop 0
	global_load_lds_dwordx4 v128, s[96:97]
	v_mov_b32_e32 v128, v133
	s_add_i32 m0, s86, 0x2000
	s_nop 0
	global_load_lds_dwordx4 v128, s[96:97]
	s_mov_b64 s[96:97], s[40:41]
	v_mov_b32_e32 v128, v130
	s_mov_b32 m0, s47
	s_nop 0
	global_load_lds_dwordx4 v128, s[96:97]
	v_mov_b32_e32 v128, v132
	s_mov_b32 m0, s48
	s_nop 0
	global_load_lds_dwordx4 v128, s[96:97]
	s_waitcnt vmcnt(8)
	s_waitcnt lgkmcnt(0)
	s_barrier
; #define PG8_LDA(dst, b, h) do { _Pragma("unroll") for (int m = 0; m < 4; ++m) _Pragma("unroll") for (int k = 0; k < 2; ++k) dst[m][k] = *(const LAS bf16x8*)(lds + PG8_SA(b, h) + aoff + m * 2048 + k * 1024); } while (0)
; #define PG8_LDB(dst, b, h) do { _Pragma("unroll") for (int n = 0; n < 2; ++n) _Pragma("unroll") for (int k = 0; k < 2; ++k) dst[n][k] = *(const LAS bf16x8*)(lds + PG8_SB(b, h) + boff + n * 2048 + k * 1024); } while (0)
; #define PG8_MMA(ai, bj, At, Bt) do { __builtin_amdgcn_s_setprio(1); _Pragma("unroll") for (int m = 0; m < 4; ++m) _Pragma("unroll") for (int n = 0; n < 2; ++n) _Pragma("unroll") for (int k = 0; k < 2; ++k) \
;         acc[ai][bj][m][n] = __builtin_amdgcn_mfma_f32_16x16x32_bf16(Bt[n][k], At[m][k], acc[ai][bj][m][n], 0, 0, 0); __builtin_amdgcn_s_setprio(0); } while (0)
; #define PG8_WAIT_V(n) asm volatile("s_waitcnt vmcnt(" #n ")" ::: "memory")
; #define PG8_WAIT_L(n) asm volatile("s_waitcnt lgkmcnt(" #n ")" ::: "memory")
; #define PG8_BAR __builtin_amdgcn_s_barrier()
; #define PG8_SCHED __builtin_amdgcn_sched_barrier(0)
; template <class Epi, bool ALIGN_EPI = true, bool SP2 = true>
; DI void gemm_phase(LAS unsigned char* lds, const Gemm g, const StaticOrder& S, const Epi& E) {
;     ...
;             PG8_WAIT_V(8); PG8_WAIT_L(0); PG8_BAR; PG8_MMA(1, 0, At, B0); PG8_MMA(1, 1, At, B1); PG8_BAR; PG8_SCHED;
;             PG8_LDB(B0, 1, 0); PG8_LDB(B1, 1, 1); PG8_SCHED; PG8_LDA(At, 1, 0); PG8_STAGE(PG8_SA(0, 1), a2 + hstepA, voffA);
;             PG8_WAIT_V(8); PG8_WAIT_L(0); PG8_BAR; PG8_MMA(0, 0, At, B0); PG8_MMA(0, 1, At, B1); PG8_BAR; PG8_SCHED;
	s_waitcnt lgkmcnt(0)
	v_mfma_f32_16x16x32_bf16 v[60:63], v[148:151], v[196:199], v[60:63]
	v_mfma_f32_16x16x32_bf16 v[52:55], v[156:159], v[196:199], v[52:55]
	v_mfma_f32_16x16x32_bf16 v[44:47], v[148:151], v[204:207], v[44:47]
	v_mfma_f32_16x16x32_bf16 v[36:39], v[156:159], v[204:207], v[36:39]
	v_mfma_f32_16x16x32_bf16 v[28:31], v[148:151], v[212:215], v[28:31]
	v_mfma_f32_16x16x32_bf16 v[20:23], v[156:159], v[212:215], v[20:23]
	v_mfma_f32_16x16x32_bf16 v[12:15], v[148:151], v[220:223], v[12:15]
	v_mfma_f32_16x16x32_bf16 v[4:7], v[156:159], v[220:223], v[4:7]
	v_mfma_f32_16x16x32_bf16 v[60:63], v[152:155], v[200:203], v[60:63]
	v_mfma_f32_16x16x32_bf16 v[52:55], v[176:179], v[200:203], v[52:55]
	v_mfma_f32_16x16x32_bf16 v[44:47], v[152:155], v[208:211], v[44:47]
	v_mfma_f32_16x16x32_bf16 v[36:39], v[176:179], v[208:211], v[36:39]
	v_mfma_f32_16x16x32_bf16 v[28:31], v[152:155], v[216:219], v[28:31]
	v_mfma_f32_16x16x32_bf16 v[20:23], v[176:179], v[216:219], v[20:23]
	v_mfma_f32_16x16x32_bf16 v[12:15], v[152:155], v[224:227], v[12:15]
	v_mfma_f32_16x16x32_bf16 v[4:7], v[176:179], v[224:227], v[4:7]
	v_mfma_f32_16x16x32_bf16 v[56:59], v[180:183], v[196:199], v[56:59]
	v_mfma_f32_16x16x32_bf16 v[48:51], v[188:191], v[196:199], v[48:51]
	v_mfma_f32_16x16x32_bf16 v[40:43], v[180:183], v[204:207], v[40:43]
	v_mfma_f32_16x16x32_bf16 v[32:35], v[188:191], v[204:207], v[32:35]
	v_mfma_f32_16x16x32_bf16 v[24:27], v[180:183], v[212:215], v[24:27]
	v_mfma_f32_16x16x32_bf16 v[16:19], v[188:191], v[212:215], v[16:19]
	v_mfma_f32_16x16x32_bf16 v[8:11], v[180:183], v[220:223], v[8:11]
	v_mfma_f32_16x16x32_bf16 v[0:3], v[188:191], v[220:223], v[0:3]
	v_mfma_f32_16x16x32_bf16 v[56:59], v[184:187], v[200:203], v[56:59]
	v_mfma_f32_16x16x32_bf16 v[48:51], v[192:195], v[200:203], v[48:51]
	v_mfma_f32_16x16x32_bf16 v[40:43], v[184:187], v[208:211], v[40:43]
	v_mfma_f32_16x16x32_bf16 v[32:35], v[192:195], v[208:211], v[32:35]
	v_mfma_f32_16x16x32_bf16 v[24:27], v[184:187], v[216:219], v[24:27]
	v_mfma_f32_16x16x32_bf16 v[16:19], v[192:195], v[216:219], v[16:19]
	v_mfma_f32_16x16x32_bf16 v[8:11], v[184:187], v[224:227], v[8:11]
	v_mfma_f32_16x16x32_bf16 v[0:3], v[192:195], v[224:227], v[0:3]
	s_barrier
	s_add_i32 s86, 0, 0x18000
	v_add_u32_e32 v128, s86, v134
	s_add_i32 s92, 0, 0x1c000
	ds_read_b128 v[148:151], v128
	ds_read_b128 v[152:155], v128 offset:1024
	ds_read_b128 v[156:159], v128 offset:2048
	ds_read_b128 v[176:179], v128 offset:3072
	v_add_u32_e32 v128, s92, v134
	ds_read_b128 v[180:183], v128
	ds_read_b128 v[184:187], v128 offset:1024
	ds_read_b128 v[188:191], v128 offset:2048
	ds_read_b128 v[192:195], v128 offset:3072
	s_add_u32 s40, s40, 0x40000
	s_addc_u32 s41, s41, 0
	v_mov_b32_e32 v128, v130
	s_mov_b32 m0, s49
	ds_read_b128 v[196:199], v135 offset:32768
	ds_read_b128 v[200:203], v135 offset:33792
	ds_read_b128 v[204:207], v135 offset:34816
	ds_read_b128 v[208:211], v135 offset:35840
	ds_read_b128 v[212:215], v135 offset:36864
	ds_read_b128 v[216:219], v135 offset:37888
	ds_read_b128 v[220:223], v135 offset:38912
	ds_read_b128 v[224:227], v135 offset:39936
	s_nop 0
	global_load_lds_dwordx4 v128, s[40:41]
	v_mov_b32_e32 v128, v132
	s_mov_b32 m0, s54
	s_nop 0
	global_load_lds_dwordx4 v128, s[40:41]
	s_waitcnt vmcnt(8)
	s_waitcnt lgkmcnt(0)
	s_barrier
	s_waitcnt lgkmcnt(0)
	v_mfma_f32_16x16x32_bf16 v[124:127], v[148:151], v[196:199], v[124:127]
	v_mfma_f32_16x16x32_bf16 v[116:119], v[156:159], v[196:199], v[116:119]
	v_mfma_f32_16x16x32_bf16 v[108:111], v[148:151], v[204:207], v[108:111]
	v_mfma_f32_16x16x32_bf16 v[100:103], v[156:159], v[204:207], v[100:103]
	v_mfma_f32_16x16x32_bf16 v[92:95], v[148:151], v[212:215], v[92:95]
	v_mfma_f32_16x16x32_bf16 v[84:87], v[156:159], v[212:215], v[84:87]
	v_mfma_f32_16x16x32_bf16 v[76:79], v[148:151], v[220:223], v[76:79]
	v_mfma_f32_16x16x32_bf16 v[68:71], v[156:159], v[220:223], v[68:71]
	v_mfma_f32_16x16x32_bf16 v[124:127], v[152:155], v[200:203], v[124:127]
	v_mfma_f32_16x16x32_bf16 v[116:119], v[176:179], v[200:203], v[116:119]
	v_mfma_f32_16x16x32_bf16 v[108:111], v[152:155], v[208:211], v[108:111]
	v_mfma_f32_16x16x32_bf16 v[100:103], v[176:179], v[208:211], v[100:103]
	v_mfma_f32_16x16x32_bf16 v[92:95], v[152:155], v[216:219], v[92:95]
	v_mfma_f32_16x16x32_bf16 v[84:87], v[176:179], v[216:219], v[84:87]
	v_mfma_f32_16x16x32_bf16 v[76:79], v[152:155], v[224:227], v[76:79]
	v_mfma_f32_16x16x32_bf16 v[68:71], v[176:179], v[224:227], v[68:71]
	v_mfma_f32_16x16x32_bf16 v[120:123], v[180:183], v[196:199], v[120:123]
	v_mfma_f32_16x16x32_bf16 v[112:115], v[188:191], v[196:199], v[112:115]
	v_mfma_f32_16x16x32_bf16 v[104:107], v[180:183], v[204:207], v[104:107]
	v_mfma_f32_16x16x32_bf16 v[96:99], v[188:191], v[204:207], v[96:99]
	v_mfma_f32_16x16x32_bf16 v[88:91], v[180:183], v[212:215], v[88:91]
	v_mfma_f32_16x16x32_bf16 v[80:83], v[188:191], v[212:215], v[80:83]
	v_mfma_f32_16x16x32_bf16 v[72:75], v[180:183], v[220:223], v[72:75]
	v_mfma_f32_16x16x32_bf16 v[64:67], v[188:191], v[220:223], v[64:67]
	v_mfma_f32_16x16x32_bf16 v[120:123], v[184:187], v[200:203], v[120:123]
	v_mfma_f32_16x16x32_bf16 v[112:115], v[192:195], v[200:203], v[112:115]
	v_mfma_f32_16x16x32_bf16 v[104:107], v[184:187], v[208:211], v[104:107]
	v_mfma_f32_16x16x32_bf16 v[96:99], v[192:195], v[208:211], v[96:99]
	v_mfma_f32_16x16x32_bf16 v[88:91], v[184:187], v[216:219], v[88:91]
	v_mfma_f32_16x16x32_bf16 v[80:83], v[192:195], v[216:219], v[80:83]
	v_mfma_f32_16x16x32_bf16 v[72:75], v[184:187], v[224:227], v[72:75]
	v_mfma_f32_16x16x32_bf16 v[64:67], v[192:195], v[224:227], v[64:67]
	s_barrier
; #define PG8_LDA(dst, b, h) do { _Pragma("unroll") for (int m = 0; m < 4; ++m) _Pragma("unroll") for (int k = 0; k < 2; ++k) dst[m][k] = *(const LAS bf16x8*)(lds + PG8_SA(b, h) + aoff + m * 2048 + k * 1024); } while (0)
; #define PG8_MMA(ai, bj, At, Bt) do { __builtin_amdgcn_s_setprio(1); _Pragma("unroll") for (int m = 0; m < 4; ++m) _Pragma("unroll") for (int n = 0; n < 2; ++n) _Pragma("unroll") for (int k = 0; k < 2; ++k) \
;         acc[ai][bj][m][n] = __builtin_amdgcn_mfma_f32_16x16x32_bf16(Bt[n][k], At[m][k], acc[ai][bj][m][n], 0, 0, 0); __builtin_amdgcn_s_setprio(0); } while (0)
; #define PG8_WAIT_V(n) asm volatile("s_waitcnt vmcnt(" #n ")" ::: "memory")
; #define PG8_WAIT_L(n) asm volatile("s_waitcnt lgkmcnt(" #n ")" ::: "memory")
; #define PG8_BAR __builtin_amdgcn_s_barrier()
; #define PG8_SCHED __builtin_amdgcn_sched_barrier(0)
; template <class Epi, bool ALIGN_EPI = true, bool SP2 = true>
; DI void gemm_phase(LAS unsigned char* lds, const Gemm g, const StaticOrder& S, const Epi& E) {
;     ...
;             PG8_LDA(At, 1, 1); PG8_STAGE(PG8_SB(1, 0), b3, voffB); PG8_STAGE(PG8_SB(1, 1), b3 + hstep, voffB); PG8_STAGE(PG8_SA(1, 0), a3, voffA);
;             PG8_WAIT_V(8); PG8_WAIT_L(0); PG8_BAR; PG8_MMA(1, 0, At, B0); PG8_MMA(1, 1, At, B1); PG8_BAR; PG8_SCHED;
;     ...
;         }
;         if constexpr (ALIGN_EPI) { if (wr == 0) PG8_BAR; }
	s_add_u32 s40, s18, 0x80
	s_addc_u32 s41, s19, 0
	v_mov_b32_e32 v128, v131
	s_add_i32 s86, s86, s46
	ds_read_b128 v[196:199], v135 offset:49152
	ds_read_b128 v[200:203], v135 offset:50176
	ds_read_b128 v[204:207], v135 offset:51200
	ds_read_b128 v[208:211], v135 offset:52224
	ds_read_b128 v[212:215], v135 offset:53248
	ds_read_b128 v[216:219], v135 offset:54272
	ds_read_b128 v[220:223], v135 offset:55296
	ds_read_b128 v[224:227], v135 offset:56320
	s_mov_b32 m0, s86
	s_nop 0
	global_load_lds_dwordx4 v128, s[40:41]
	v_mov_b32_e32 v128, v133
	s_add_i32 m0, s86, 0x2000
	s_add_u32 s18, s18, 0x40080
	global_load_lds_dwordx4 v128, s[40:41]
	s_addc_u32 s19, s19, 0
	v_mov_b32_e32 v128, v131
	s_add_i32 s40, s92, s46
	s_mov_b32 m0, s40
	s_nop 0
	global_load_lds_dwordx4 v128, s[18:19]
	v_mov_b32_e32 v128, v133
	s_add_i32 m0, s40, 0x2000
	s_nop 0
	global_load_lds_dwordx4 v128, s[18:19]
	v_mov_b32_e32 v128, v130
	s_mov_b32 m0, s69
	s_nop 0
	global_load_lds_dwordx4 v128, s[16:17]
	v_mov_b32_e32 v128, v132
	s_mov_b32 m0, s73
	s_nop 0
	global_load_lds_dwordx4 v128, s[16:17]
	s_waitcnt vmcnt(8)
	s_waitcnt lgkmcnt(0)
	s_barrier
	s_waitcnt lgkmcnt(0)
	v_mfma_f32_16x16x32_bf16 v[60:63], v[148:151], v[196:199], v[60:63]
	v_mfma_f32_16x16x32_bf16 v[52:55], v[156:159], v[196:199], v[52:55]
	v_mfma_f32_16x16x32_bf16 v[44:47], v[148:151], v[204:207], v[44:47]
	v_mfma_f32_16x16x32_bf16 v[36:39], v[156:159], v[204:207], v[36:39]
	v_mfma_f32_16x16x32_bf16 v[28:31], v[148:151], v[212:215], v[28:31]
	v_mfma_f32_16x16x32_bf16 v[20:23], v[156:159], v[212:215], v[20:23]
	v_mfma_f32_16x16x32_bf16 v[12:15], v[148:151], v[220:223], v[12:15]
	v_mfma_f32_16x16x32_bf16 v[4:7], v[156:159], v[220:223], v[4:7]
	v_mfma_f32_16x16x32_bf16 v[60:63], v[152:155], v[200:203], v[60:63]
	v_mfma_f32_16x16x32_bf16 v[52:55], v[176:179], v[200:203], v[52:55]
	v_mfma_f32_16x16x32_bf16 v[44:47], v[152:155], v[208:211], v[44:47]
	v_mfma_f32_16x16x32_bf16 v[36:39], v[176:179], v[208:211], v[36:39]
	v_mfma_f32_16x16x32_bf16 v[28:31], v[152:155], v[216:219], v[28:31]
	v_mfma_f32_16x16x32_bf16 v[20:23], v[176:179], v[216:219], v[20:23]
	v_mfma_f32_16x16x32_bf16 v[12:15], v[152:155], v[224:227], v[12:15]
	v_mfma_f32_16x16x32_bf16 v[4:7], v[176:179], v[224:227], v[4:7]
	v_mfma_f32_16x16x32_bf16 v[56:59], v[180:183], v[196:199], v[56:59]
	v_mfma_f32_16x16x32_bf16 v[48:51], v[188:191], v[196:199], v[48:51]
	v_mfma_f32_16x16x32_bf16 v[40:43], v[180:183], v[204:207], v[40:43]
	v_mfma_f32_16x16x32_bf16 v[32:35], v[188:191], v[204:207], v[32:35]
	v_mfma_f32_16x16x32_bf16 v[24:27], v[180:183], v[212:215], v[24:27]
	v_mfma_f32_16x16x32_bf16 v[16:19], v[188:191], v[212:215], v[16:19]
	v_mfma_f32_16x16x32_bf16 v[8:11], v[180:183], v[220:223], v[8:11]
	v_mfma_f32_16x16x32_bf16 v[0:3], v[188:191], v[220:223], v[0:3]
	v_mfma_f32_16x16x32_bf16 v[56:59], v[184:187], v[200:203], v[56:59]
	v_mfma_f32_16x16x32_bf16 v[48:51], v[192:195], v[200:203], v[48:51]
	v_mfma_f32_16x16x32_bf16 v[40:43], v[184:187], v[208:211], v[40:43]
	v_mfma_f32_16x16x32_bf16 v[32:35], v[192:195], v[208:211], v[32:35]
	v_mfma_f32_16x16x32_bf16 v[24:27], v[184:187], v[216:219], v[24:27]
	v_mfma_f32_16x16x32_bf16 v[16:19], v[192:195], v[216:219], v[16:19]
	v_mfma_f32_16x16x32_bf16 v[8:11], v[184:187], v[224:227], v[8:11]
	v_mfma_f32_16x16x32_bf16 v[0:3], v[192:195], v[224:227], v[0:3]
	s_barrier
	s_add_i32 s81, s81, 2
	s_add_u32 s14, s14, 0x100
	s_addc_u32 s15, s15, 0
	s_add_u32 s70, s70, 0x100
	s_addc_u32 s72, s72, 0
	s_cmp_gt_u32 s81, 13
	s_cbranch_scc0 .LBB0_770
	s_and_b64 vcc, exec, s[4:5]
	s_cbranch_vccz .LBB0_773
	s_barrier
